# GEMM K-loop barrier handoff trimmed: setprio 1 before the barrier, redundant lgkmcnt(0) removed, closing barrier right after the last MFMA with setprio 0 after it
# speedup vs baseline: 1.0198x; 1.0198x over previous
; #define PG8_STAGE(bufoff, gbase, voff) do { _Pragma("unroll") for (int _i = 0; _i < 2; ++_i) \
;         __builtin_amdgcn_global_load_lds((const unsigned*)((const char*)(gbase) + (voff)[_i]), (PG8_LAS unsigned*)(lds + (bufoff) + ldsw + _i * 8192), 16, 0, 0); } while (0)
; #define PG8_LDA(dst, b, h) do { _Pragma("unroll") for (int m = 0; m < 4; ++m) _Pragma("unroll") for (int k = 0; k < 2; ++k) dst[m][k] = *(const PG8_LAS bf16x8*)(lds + PG8_SA(b, h) + aoff + m * 2048 + k * 1024); } while (0)
; #define PG8_LDB(dst, b, h) do { _Pragma("unroll") for (int n = 0; n < 2; ++n) _Pragma("unroll") for (int k = 0; k < 2; ++k) dst[n][k] = *(const PG8_LAS bf16x8*)(lds + PG8_SB(b, h) + boff + n * 2048 + k * 1024); } while (0)
; #define PG8_WAIT_V(n) asm volatile("s_waitcnt vmcnt(" #n ")" ::: "memory")
; #define PG8_WAIT_L(n) asm volatile("s_waitcnt lgkmcnt(" #n ")" ::: "memory")
; #define PG8_BAR __builtin_amdgcn_s_barrier()
; #define PG8_SCHED __builtin_amdgcn_sched_barrier(0)
; template <class Epi, class Sched, bool ALIGN_EPI = false, bool SP2 = false>
; __device__ __forceinline__ void gemm_phase(PG8_LAS unsigned char* lds, const Gemm g, const Sched& S, const Epi& E) {
;     ...
;         const bool has_next = S.next(ui + 1, nxt);
;         const char* nA = has_next ? (const char*)g.A + (size_t)nxt.pm * tstep + (size_t)nxt.pn * g.a_gs : cA; const char* nB = has_next ? (const char*)g.Bt + (size_t)nxt.pn * tstep : cB;
;         for (int t = 0; t < nt; t += 2) {
;             const bool last = (t == nt - 2);
;             const char* a1 = cA + (size_t)(t + 1) * kstep;
;             const char* a2 = last ? nA : cA + (size_t)(t + 2) * kstep; const char* b2 = last ? nB : cB + (size_t)(t + 2) * kstep;
;             const char* a3 = a2 + kstep; const char* b3 = b2 + kstep;
;             if (last && has_next) S.a_ready(nxt);
;             if constexpr (SP2) {
;             PG8_LDB(B0, 0, 0); PG8_LDB(B1, 0, 1); PG8_SCHED; PG8_LDA(At, 0, 0); PG8_STAGE(PG8_SA(1, 1), a1 + hstep, voffA);
;             PG8_WAIT_V(8); PG8_WAIT_L(0); PG8_BAR; PG8_MMA(0, 0, At, B0); PG8_MMA(0, 1, At, B1); PG8_BAR; PG8_SCHED;
;             PG8_LDA(At, 0, 1); PG8_STAGE(PG8_SB(0, 0), b2, voffB); PG8_STAGE(PG8_SB(0, 1), b2 + hstep, voffB); PG8_STAGE(PG8_SA(0, 0), a2, voffA);
;             PG8_WAIT_V(8); PG8_WAIT_L(0); PG8_BAR; PG8_MMA(1, 0, At, B0); PG8_MMA(1, 1, At, B1); PG8_BAR; PG8_SCHED;
.LBB0_218:
	s_ashr_i32 s73, s72, 31
	s_lshl_b64 s[38:39], s[72:73], 19
	s_add_u32 s74, s10, s38
	s_addc_u32 s75, s11, s39
	s_and_b64 s[38:39], s[44:45], exec
	s_cselect_b32 s50, s75, s49
	s_cselect_b32 s51, s74, s48
	s_ashr_i32 s71, s70, 31
	s_lshl_b64 s[38:39], s[70:71], 19
	s_add_u32 s76, s62, s38
	s_addc_u32 s77, s63, s39
	s_and_b64 s[38:39], s[44:45], exec
	s_cselect_b32 s52, s77, s47
	s_cselect_b32 s53, s76, s46
	s_add_u32 s38, s48, 0x40080
	s_addc_u32 s39, s49, 0
	s_add_u32 s71, s46, 0x100
	s_addc_u32 s73, s47, 0
	s_mov_b32 vcc_lo, -2
	s_add_u32 s46, s38, 0xfffc0080
	s_addc_u32 s47, s39, -1
	s_add_i32 s56, 0, 0x10000
	s_cmp_eq_u32 vcc_lo, 12
	s_cselect_b32 s49, s50, s47
	s_cselect_b32 s48, s51, s46
	s_cselect_b32 s47, s52, s73
	s_cselect_b32 s46, s53, s71
	s_add_i32 vcc_hi, 0, 0x14000
	v_add_u32_e32 v152, s56, v165
	v_add_u32_e32 v169, vcc_hi, v165
	ds_read_b128 v[128:131], v152
	ds_read_b128 v[144:147], v152 offset:1024
	ds_read_b128 v[148:151], v152 offset:2048
	ds_read_b128 v[152:155], v152 offset:3072
	ds_read_b128 v[156:159], v169
	ds_read_b128 v[160:163], v169 offset:1024
	ds_read_b128 v[170:173], v169 offset:2048
	ds_read_b128 v[180:183], v169 offset:3072
	v_lshl_add_u64 v[176:177], s[38:39], 0, v[140:141]
	s_add_i32 m0, s9, 0xc000
	ds_read_b128 v[184:187], v168
	ds_read_b128 v[188:191], v168 offset:1024
	ds_read_b128 v[192:195], v168 offset:2048
	ds_read_b128 v[196:199], v168 offset:3072
	ds_read_b128 v[200:203], v168 offset:4096
	ds_read_b128 v[204:207], v168 offset:5120
	ds_read_b128 v[218:221], v168 offset:6144
	ds_read_b128 v[222:225], v168 offset:7168
	global_load_lds_dwordx4 v[176:177], off
	v_lshl_add_u64 v[176:177], s[38:39], 0, v[142:143]
	s_add_i32 m0, s9, 0xe000
	s_nop 0
	global_load_lds_dwordx4 v[176:177], off
	s_waitcnt vmcnt(8)
	s_waitcnt lgkmcnt(0)
	s_setprio 1
	s_barrier
	v_mfma_f32_16x16x32_bf16 v[124:127], v[128:131], v[184:187], 0
	v_mfma_f32_16x16x32_bf16 v[120:123], v[148:151], v[184:187], 0
	v_mfma_f32_16x16x32_bf16 v[108:111], v[128:131], v[192:195], 0
	v_mfma_f32_16x16x32_bf16 v[104:107], v[148:151], v[192:195], 0
	v_mfma_f32_16x16x32_bf16 v[92:95], v[128:131], v[200:203], 0
	v_mfma_f32_16x16x32_bf16 v[88:91], v[148:151], v[200:203], 0
	v_mfma_f32_16x16x32_bf16 v[76:79], v[128:131], v[218:221], 0
	v_mfma_f32_16x16x32_bf16 v[72:75], v[148:151], v[218:221], 0
	v_mfma_f32_16x16x32_bf16 v[124:127], v[144:147], v[188:191], v[124:127]
	v_mfma_f32_16x16x32_bf16 v[120:123], v[152:155], v[188:191], v[120:123]
	v_mfma_f32_16x16x32_bf16 v[108:111], v[144:147], v[196:199], v[108:111]
	v_mfma_f32_16x16x32_bf16 v[104:107], v[152:155], v[196:199], v[104:107]
	v_mfma_f32_16x16x32_bf16 v[92:95], v[144:147], v[204:207], v[92:95]
	v_mfma_f32_16x16x32_bf16 v[88:91], v[152:155], v[204:207], v[88:91]
	v_mfma_f32_16x16x32_bf16 v[76:79], v[144:147], v[222:225], v[76:79]
	v_mfma_f32_16x16x32_bf16 v[72:75], v[152:155], v[222:225], v[72:75]
	v_mfma_f32_16x16x32_bf16 v[116:119], v[156:159], v[184:187], 0
	v_mfma_f32_16x16x32_bf16 v[112:115], v[170:173], v[184:187], 0
	v_mfma_f32_16x16x32_bf16 v[100:103], v[156:159], v[192:195], 0
	v_mfma_f32_16x16x32_bf16 v[96:99], v[170:173], v[192:195], 0
	v_mfma_f32_16x16x32_bf16 v[84:87], v[156:159], v[200:203], 0
	v_mfma_f32_16x16x32_bf16 v[80:83], v[170:173], v[200:203], 0
	v_mfma_f32_16x16x32_bf16 v[68:71], v[156:159], v[218:221], 0
	v_mfma_f32_16x16x32_bf16 v[64:67], v[170:173], v[218:221], 0
	v_mfma_f32_16x16x32_bf16 v[116:119], v[160:163], v[188:191], v[116:119]
	v_mfma_f32_16x16x32_bf16 v[112:115], v[180:183], v[188:191], v[112:115]
	v_mfma_f32_16x16x32_bf16 v[100:103], v[160:163], v[196:199], v[100:103]
	v_mfma_f32_16x16x32_bf16 v[96:99], v[180:183], v[196:199], v[96:99]
	v_mfma_f32_16x16x32_bf16 v[84:87], v[160:163], v[204:207], v[84:87]
	v_mfma_f32_16x16x32_bf16 v[80:83], v[180:183], v[204:207], v[80:83]
	v_mfma_f32_16x16x32_bf16 v[68:71], v[160:163], v[222:225], v[68:71]
	v_mfma_f32_16x16x32_bf16 v[64:67], v[180:183], v[222:225], v[64:67]
	s_barrier
	s_setprio 0
	s_add_i32 s56, s56, s8
	v_lshl_add_u64 v[176:177], s[46:47], 0, v[174:175]
	s_mov_b32 m0, s56
	ds_read_b128 v[184:187], v168 offset:16384
	ds_read_b128 v[188:191], v168 offset:17408
	ds_read_b128 v[192:195], v168 offset:18432
	ds_read_b128 v[196:199], v168 offset:19456
	ds_read_b128 v[200:203], v168 offset:20480
	ds_read_b128 v[204:207], v168 offset:21504
	ds_read_b128 v[218:221], v168 offset:22528
	ds_read_b128 v[222:225], v168 offset:23552
	global_load_lds_dwordx4 v[176:177], off
	s_add_i32 m0, s56, 0x2000
	s_add_u32 s56, s46, 0x40000
	v_lshl_add_u64 v[178:179], s[46:47], 0, v[136:137]
	s_addc_u32 s57, s47, 0
	s_add_i32 vcc_hi, vcc_hi, s8
	global_load_lds_dwordx4 v[178:179], off
	v_lshl_add_u64 v[208:209], s[56:57], 0, v[174:175]
	s_mov_b32 m0, vcc_hi
	v_lshl_add_u64 v[226:227], s[48:49], 0, v[134:135]
	global_load_lds_dwordx4 v[208:209], off
	v_lshl_add_u64 v[208:209], s[56:57], 0, v[136:137]
	s_add_i32 m0, vcc_hi, 0x2000
	s_nop 0
	global_load_lds_dwordx4 v[208:209], off
	v_lshl_add_u64 v[208:209], s[48:49], 0, v[132:133]
	s_mov_b32 m0, s9
	s_nop 0
	global_load_lds_dwordx4 v[208:209], off
	s_mov_b32 m0, s79
	s_nop 0
	global_load_lds_dwordx4 v[226:227], off
	s_waitcnt vmcnt(8)
	s_waitcnt lgkmcnt(0)
	s_setprio 1
	s_barrier
; #define PG8_STAGE(bufoff, gbase, voff) do { _Pragma("unroll") for (int _i = 0; _i < 2; ++_i) \
;         __builtin_amdgcn_global_load_lds((const unsigned*)((const char*)(gbase) + (voff)[_i]), (PG8_LAS unsigned*)(lds + (bufoff) + ldsw + _i * 8192), 16, 0, 0); } while (0)
; #define PG8_LDA(dst, b, h) do { _Pragma("unroll") for (int m = 0; m < 4; ++m) _Pragma("unroll") for (int k = 0; k < 2; ++k) dst[m][k] = *(const PG8_LAS bf16x8*)(lds + PG8_SA(b, h) + aoff + m * 2048 + k * 1024); } while (0)
; #define PG8_LDB(dst, b, h) do { _Pragma("unroll") for (int n = 0; n < 2; ++n) _Pragma("unroll") for (int k = 0; k < 2; ++k) dst[n][k] = *(const PG8_LAS bf16x8*)(lds + PG8_SB(b, h) + boff + n * 2048 + k * 1024); } while (0)
; #define PG8_MMA(ai, bj, At, Bt) do { __builtin_amdgcn_s_setprio(1); _Pragma("unroll") for (int m = 0; m < 4; ++m) _Pragma("unroll") for (int n = 0; n < 2; ++n) _Pragma("unroll") for (int k = 0; k < 2; ++k) \
;         acc[ai][bj][m][n] = __builtin_amdgcn_mfma_f32_16x16x32_bf16(Bt[n][k], At[m][k], acc[ai][bj][m][n], 0, 0, 0); __builtin_amdgcn_s_setprio(0); } while (0)
; #define PG8_WAIT_V(n) asm volatile("s_waitcnt vmcnt(" #n ")" ::: "memory")
; #define PG8_WAIT_L(n) asm volatile("s_waitcnt lgkmcnt(" #n ")" ::: "memory")
; #define PG8_BAR __builtin_amdgcn_s_barrier()
; #define PG8_SCHED __builtin_amdgcn_sched_barrier(0)
; template <class Epi, class Sched, bool ALIGN_EPI = false, bool SP2 = false>
; __device__ __forceinline__ void gemm_phase(PG8_LAS unsigned char* lds, const Gemm g, const Sched& S, const Epi& E) {
;     ...
;             PG8_WAIT_V(8); PG8_WAIT_L(0); PG8_BAR; PG8_MMA(0, 0, At, B0); PG8_MMA(0, 1, At, B1); PG8_BAR; PG8_SCHED;
;             PG8_LDA(At, 0, 1); PG8_STAGE(PG8_SB(0, 0), b2, voffB); PG8_STAGE(PG8_SB(0, 1), b2 + hstep, voffB); PG8_STAGE(PG8_SA(0, 0), a2, voffA);
;             PG8_WAIT_V(8); PG8_WAIT_L(0); PG8_BAR; PG8_MMA(1, 0, At, B0); PG8_MMA(1, 1, At, B1); PG8_BAR; PG8_SCHED;
;             PG8_LDB(B0, 1, 0); PG8_LDB(B1, 1, 1); PG8_SCHED; PG8_LDA(At, 1, 0); PG8_STAGE(PG8_SA(0, 1), a2 + hstep, voffA);
;             PG8_WAIT_V(8); PG8_WAIT_L(0); PG8_BAR; PG8_MMA(0, 0, At, B0); PG8_MMA(0, 1, At, B1); PG8_BAR; PG8_SCHED;
	v_mfma_f32_16x16x32_bf16 v[60:63], v[128:131], v[184:187], 0
	v_mfma_f32_16x16x32_bf16 v[56:59], v[148:151], v[184:187], 0
	v_mfma_f32_16x16x32_bf16 v[44:47], v[128:131], v[192:195], 0
	v_mfma_f32_16x16x32_bf16 v[40:43], v[148:151], v[192:195], 0
	v_mfma_f32_16x16x32_bf16 v[28:31], v[128:131], v[200:203], 0
	v_mfma_f32_16x16x32_bf16 v[24:27], v[148:151], v[200:203], 0
	v_mfma_f32_16x16x32_bf16 v[12:15], v[128:131], v[218:221], 0
	v_mfma_f32_16x16x32_bf16 v[8:11], v[148:151], v[218:221], 0
	v_mfma_f32_16x16x32_bf16 v[60:63], v[144:147], v[188:191], v[60:63]
	v_mfma_f32_16x16x32_bf16 v[56:59], v[152:155], v[188:191], v[56:59]
	v_mfma_f32_16x16x32_bf16 v[44:47], v[144:147], v[196:199], v[44:47]
	v_mfma_f32_16x16x32_bf16 v[40:43], v[152:155], v[196:199], v[40:43]
	v_mfma_f32_16x16x32_bf16 v[28:31], v[144:147], v[204:207], v[28:31]
	v_mfma_f32_16x16x32_bf16 v[24:27], v[152:155], v[204:207], v[24:27]
	v_mfma_f32_16x16x32_bf16 v[12:15], v[144:147], v[222:225], v[12:15]
	v_mfma_f32_16x16x32_bf16 v[8:11], v[152:155], v[222:225], v[8:11]
	v_mfma_f32_16x16x32_bf16 v[52:55], v[156:159], v[184:187], 0
	v_mfma_f32_16x16x32_bf16 v[48:51], v[170:173], v[184:187], 0
	v_mfma_f32_16x16x32_bf16 v[36:39], v[156:159], v[192:195], 0
	v_mfma_f32_16x16x32_bf16 v[32:35], v[170:173], v[192:195], 0
	v_mfma_f32_16x16x32_bf16 v[20:23], v[156:159], v[200:203], 0
	v_mfma_f32_16x16x32_bf16 v[16:19], v[170:173], v[200:203], 0
	v_mfma_f32_16x16x32_bf16 v[4:7], v[156:159], v[218:221], 0
	v_mfma_f32_16x16x32_bf16 v[0:3], v[170:173], v[218:221], 0
	v_mfma_f32_16x16x32_bf16 v[52:55], v[160:163], v[188:191], v[52:55]
	v_mfma_f32_16x16x32_bf16 v[48:51], v[180:183], v[188:191], v[48:51]
	v_mfma_f32_16x16x32_bf16 v[36:39], v[160:163], v[196:199], v[36:39]
	v_mfma_f32_16x16x32_bf16 v[32:35], v[180:183], v[196:199], v[32:35]
	v_mfma_f32_16x16x32_bf16 v[20:23], v[160:163], v[204:207], v[20:23]
	v_mfma_f32_16x16x32_bf16 v[16:19], v[180:183], v[204:207], v[16:19]
	v_mfma_f32_16x16x32_bf16 v[4:7], v[160:163], v[222:225], v[4:7]
	v_mfma_f32_16x16x32_bf16 v[0:3], v[180:183], v[222:225], v[0:3]
	s_barrier
	s_setprio 0
	s_add_i32 s56, 0, 0x18000
	s_add_i32 s57, 0, 0x1c000
	v_add_u32_e32 v152, s56, v165
	v_add_u32_e32 v169, s57, v165
	ds_read_b128 v[128:131], v152
	ds_read_b128 v[144:147], v152 offset:1024
	ds_read_b128 v[148:151], v152 offset:2048
	ds_read_b128 v[152:155], v152 offset:3072
	ds_read_b128 v[156:159], v169
	ds_read_b128 v[160:163], v169 offset:1024
	ds_read_b128 v[170:173], v169 offset:2048
	ds_read_b128 v[180:183], v169 offset:3072
	s_add_u32 s48, s48, 0x40000
	s_addc_u32 s49, s49, 0
	s_mov_b32 m0, s54
	v_lshl_add_u64 v[228:229], s[48:49], 0, v[132:133]
	ds_read_b128 v[184:187], v168 offset:32768
	ds_read_b128 v[188:191], v168 offset:33792
	ds_read_b128 v[192:195], v168 offset:34816
	ds_read_b128 v[196:199], v168 offset:35840
	ds_read_b128 v[200:203], v168 offset:36864
	ds_read_b128 v[204:207], v168 offset:37888
	ds_read_b128 v[218:221], v168 offset:38912
	ds_read_b128 v[222:225], v168 offset:39936
	global_load_lds_dwordx4 v[228:229], off
	v_lshl_add_u64 v[228:229], s[48:49], 0, v[134:135]
	s_mov_b32 m0, s55
	s_nop 0
	global_load_lds_dwordx4 v[228:229], off
	s_waitcnt vmcnt(8)
	s_waitcnt lgkmcnt(0)
	s_setprio 1
	s_barrier
	v_mfma_f32_16x16x32_bf16 v[124:127], v[128:131], v[184:187], v[124:127]
	v_mfma_f32_16x16x32_bf16 v[120:123], v[148:151], v[184:187], v[120:123]
	v_mfma_f32_16x16x32_bf16 v[108:111], v[128:131], v[192:195], v[108:111]
	v_mfma_f32_16x16x32_bf16 v[104:107], v[148:151], v[192:195], v[104:107]
	v_mfma_f32_16x16x32_bf16 v[92:95], v[128:131], v[200:203], v[92:95]
	v_mfma_f32_16x16x32_bf16 v[88:91], v[148:151], v[200:203], v[88:91]
	v_mfma_f32_16x16x32_bf16 v[76:79], v[128:131], v[218:221], v[76:79]
	v_mfma_f32_16x16x32_bf16 v[72:75], v[148:151], v[218:221], v[72:75]
	v_mfma_f32_16x16x32_bf16 v[124:127], v[144:147], v[188:191], v[124:127]
	v_mfma_f32_16x16x32_bf16 v[120:123], v[152:155], v[188:191], v[120:123]
	v_mfma_f32_16x16x32_bf16 v[108:111], v[144:147], v[196:199], v[108:111]
	v_mfma_f32_16x16x32_bf16 v[104:107], v[152:155], v[196:199], v[104:107]
	v_mfma_f32_16x16x32_bf16 v[92:95], v[144:147], v[204:207], v[92:95]
	v_mfma_f32_16x16x32_bf16 v[88:91], v[152:155], v[204:207], v[88:91]
	v_mfma_f32_16x16x32_bf16 v[76:79], v[144:147], v[222:225], v[76:79]
	v_mfma_f32_16x16x32_bf16 v[72:75], v[152:155], v[222:225], v[72:75]
	v_mfma_f32_16x16x32_bf16 v[116:119], v[156:159], v[184:187], v[116:119]
	v_mfma_f32_16x16x32_bf16 v[112:115], v[170:173], v[184:187], v[112:115]
	v_mfma_f32_16x16x32_bf16 v[100:103], v[156:159], v[192:195], v[100:103]
	v_mfma_f32_16x16x32_bf16 v[96:99], v[170:173], v[192:195], v[96:99]
	v_mfma_f32_16x16x32_bf16 v[84:87], v[156:159], v[200:203], v[84:87]
	v_mfma_f32_16x16x32_bf16 v[80:83], v[170:173], v[200:203], v[80:83]
	v_mfma_f32_16x16x32_bf16 v[68:71], v[156:159], v[218:221], v[68:71]
	v_mfma_f32_16x16x32_bf16 v[64:67], v[170:173], v[218:221], v[64:67]
	v_mfma_f32_16x16x32_bf16 v[116:119], v[160:163], v[188:191], v[116:119]
	v_mfma_f32_16x16x32_bf16 v[112:115], v[180:183], v[188:191], v[112:115]
	v_mfma_f32_16x16x32_bf16 v[100:103], v[160:163], v[196:199], v[100:103]
	v_mfma_f32_16x16x32_bf16 v[96:99], v[180:183], v[196:199], v[96:99]
	v_mfma_f32_16x16x32_bf16 v[84:87], v[160:163], v[204:207], v[84:87]
	v_mfma_f32_16x16x32_bf16 v[80:83], v[180:183], v[204:207], v[80:83]
	v_mfma_f32_16x16x32_bf16 v[68:71], v[160:163], v[222:225], v[68:71]
	v_mfma_f32_16x16x32_bf16 v[64:67], v[180:183], v[222:225], v[64:67]
	s_barrier
; #define PG8_STAGE(bufoff, gbase, voff) do { _Pragma("unroll") for (int _i = 0; _i < 2; ++_i) \
;         __builtin_amdgcn_global_load_lds((const unsigned*)((const char*)(gbase) + (voff)[_i]), (PG8_LAS unsigned*)(lds + (bufoff) + ldsw + _i * 8192), 16, 0, 0); } while (0)
; #define PG8_LDA(dst, b, h) do { _Pragma("unroll") for (int m = 0; m < 4; ++m) _Pragma("unroll") for (int k = 0; k < 2; ++k) dst[m][k] = *(const PG8_LAS bf16x8*)(lds + PG8_SA(b, h) + aoff + m * 2048 + k * 1024); } while (0)
; #define PG8_LDB(dst, b, h) do { _Pragma("unroll") for (int n = 0; n < 2; ++n) _Pragma("unroll") for (int k = 0; k < 2; ++k) dst[n][k] = *(const PG8_LAS bf16x8*)(lds + PG8_SB(b, h) + boff + n * 2048 + k * 1024); } while (0)
; #define PG8_MMA(ai, bj, At, Bt) do { __builtin_amdgcn_s_setprio(1); _Pragma("unroll") for (int m = 0; m < 4; ++m) _Pragma("unroll") for (int n = 0; n < 2; ++n) _Pragma("unroll") for (int k = 0; k < 2; ++k) \
;         acc[ai][bj][m][n] = __builtin_amdgcn_mfma_f32_16x16x32_bf16(Bt[n][k], At[m][k], acc[ai][bj][m][n], 0, 0, 0); __builtin_amdgcn_s_setprio(0); } while (0)
; #define PG8_WAIT_V(n) asm volatile("s_waitcnt vmcnt(" #n ")" ::: "memory")
; #define PG8_WAIT_L(n) asm volatile("s_waitcnt lgkmcnt(" #n ")" ::: "memory")
; #define PG8_BAR __builtin_amdgcn_s_barrier()
; #define PG8_SCHED __builtin_amdgcn_sched_barrier(0)
; template <class Epi, class Sched, bool ALIGN_EPI = false, bool SP2 = false>
; __device__ __forceinline__ void gemm_phase(PG8_LAS unsigned char* lds, const Gemm g, const Sched& S, const Epi& E) {
;     ...
;             PG8_LDB(B0, 0, 0); PG8_LDB(B1, 0, 1); PG8_SCHED; PG8_LDA(At, 0, 0); PG8_STAGE(PG8_SA(1, 1), a1 + hstep, voffA);
;             PG8_WAIT_V(8); PG8_WAIT_L(0); PG8_BAR; PG8_MMA(0, 0, At, B0); PG8_MMA(0, 1, At, B1); PG8_BAR; PG8_SCHED;
;     ...
;             PG8_LDA(At, 1, 1); PG8_STAGE(PG8_SB(1, 0), b3, voffB); PG8_STAGE(PG8_SB(1, 1), b3 + hstep, voffB); PG8_STAGE(PG8_SA(1, 0), a3, voffA);
;             PG8_WAIT_V(8); PG8_WAIT_L(0); PG8_BAR; PG8_MMA(1, 0, At, B0); PG8_MMA(1, 1, At, B1); PG8_BAR; PG8_SCHED;
	s_setprio 0
	s_add_i32 s48, s56, s8
	v_lshl_add_u64 v[176:177], v[176:177], 0, s[4:5]
	s_mov_b32 m0, s48
	ds_read_b128 v[184:187], v168 offset:49152
	ds_read_b128 v[188:191], v168 offset:50176
	ds_read_b128 v[192:195], v168 offset:51200
	ds_read_b128 v[196:199], v168 offset:52224
	ds_read_b128 v[200:203], v168 offset:53248
	ds_read_b128 v[204:207], v168 offset:54272
	ds_read_b128 v[218:221], v168 offset:55296
	ds_read_b128 v[222:225], v168 offset:56320
	global_load_lds_dwordx4 v[176:177], off
	s_add_i32 m0, s48, 0x2000
	s_add_u32 s46, s46, 0x40080
	v_lshl_add_u64 v[176:177], v[178:179], 0, s[4:5]
	s_addc_u32 s47, s47, 0
	s_add_i32 s48, s57, s8
	global_load_lds_dwordx4 v[176:177], off
	v_lshl_add_u64 v[176:177], s[46:47], 0, v[174:175]
	s_mov_b32 m0, s48
	s_nop 0
	global_load_lds_dwordx4 v[176:177], off
	v_lshl_add_u64 v[176:177], s[46:47], 0, v[136:137]
	s_add_i32 m0, s48, 0x2000
	s_nop 0
	global_load_lds_dwordx4 v[176:177], off
	v_lshl_add_u64 v[176:177], v[208:209], 0, s[4:5]
	s_mov_b32 m0, s93
	s_nop 0
	global_load_lds_dwordx4 v[176:177], off
	v_lshl_add_u64 v[176:177], v[226:227], 0, s[4:5]
	s_mov_b32 m0, s66
	s_nop 0
	global_load_lds_dwordx4 v[176:177], off
	s_waitcnt vmcnt(8)
	s_waitcnt lgkmcnt(0)
	s_setprio 1
	s_barrier
	v_mfma_f32_16x16x32_bf16 v[60:63], v[128:131], v[184:187], v[60:63]
	v_mfma_f32_16x16x32_bf16 v[56:59], v[148:151], v[184:187], v[56:59]
	v_mfma_f32_16x16x32_bf16 v[44:47], v[128:131], v[192:195], v[44:47]
	v_mfma_f32_16x16x32_bf16 v[40:43], v[148:151], v[192:195], v[40:43]
	v_mfma_f32_16x16x32_bf16 v[28:31], v[128:131], v[200:203], v[28:31]
	v_mfma_f32_16x16x32_bf16 v[24:27], v[148:151], v[200:203], v[24:27]
	v_mfma_f32_16x16x32_bf16 v[12:15], v[128:131], v[218:221], v[12:15]
	v_mfma_f32_16x16x32_bf16 v[8:11], v[148:151], v[218:221], v[8:11]
	v_mfma_f32_16x16x32_bf16 v[60:63], v[144:147], v[188:191], v[60:63]
	v_mfma_f32_16x16x32_bf16 v[56:59], v[152:155], v[188:191], v[56:59]
	v_mfma_f32_16x16x32_bf16 v[44:47], v[144:147], v[196:199], v[44:47]
	v_mfma_f32_16x16x32_bf16 v[40:43], v[152:155], v[196:199], v[40:43]
	v_mfma_f32_16x16x32_bf16 v[28:31], v[144:147], v[204:207], v[28:31]
	v_mfma_f32_16x16x32_bf16 v[24:27], v[152:155], v[204:207], v[24:27]
	v_mfma_f32_16x16x32_bf16 v[12:15], v[144:147], v[222:225], v[12:15]
	v_mfma_f32_16x16x32_bf16 v[8:11], v[152:155], v[222:225], v[8:11]
	v_mfma_f32_16x16x32_bf16 v[52:55], v[156:159], v[184:187], v[52:55]
	v_mfma_f32_16x16x32_bf16 v[48:51], v[170:173], v[184:187], v[48:51]
	v_mfma_f32_16x16x32_bf16 v[36:39], v[156:159], v[192:195], v[36:39]
	v_mfma_f32_16x16x32_bf16 v[32:35], v[170:173], v[192:195], v[32:35]
	v_mfma_f32_16x16x32_bf16 v[20:23], v[156:159], v[200:203], v[20:23]
	v_mfma_f32_16x16x32_bf16 v[16:19], v[170:173], v[200:203], v[16:19]
	v_mfma_f32_16x16x32_bf16 v[4:7], v[156:159], v[218:221], v[4:7]
	v_mfma_f32_16x16x32_bf16 v[0:3], v[170:173], v[218:221], v[0:3]
	v_mfma_f32_16x16x32_bf16 v[52:55], v[160:163], v[188:191], v[52:55]
	v_mfma_f32_16x16x32_bf16 v[48:51], v[180:183], v[188:191], v[48:51]
	v_mfma_f32_16x16x32_bf16 v[36:39], v[160:163], v[196:199], v[36:39]
	v_mfma_f32_16x16x32_bf16 v[32:35], v[180:183], v[196:199], v[32:35]
	v_mfma_f32_16x16x32_bf16 v[20:23], v[160:163], v[204:207], v[20:23]
	v_mfma_f32_16x16x32_bf16 v[16:19], v[180:183], v[204:207], v[16:19]
	v_mfma_f32_16x16x32_bf16 v[4:7], v[160:163], v[222:225], v[4:7]
	v_mfma_f32_16x16x32_bf16 v[0:3], v[180:183], v[222:225], v[0:3]
	s_barrier
	s_setprio 0
	s_add_i32 vcc_lo, vcc_lo, 2
	s_add_u32 s38, s38, 0x100
	s_addc_u32 s39, s39, 0
	s_add_u32 s71, s71, 0x100
	s_addc_u32 s73, s73, 0
	s_cmp_gt_u32 vcc_lo, 13
	s_cbranch_scc0 .LBB0_219
.LBB0_219:
	s_add_u32 s46, s38, 0xfffc0080
	s_addc_u32 s47, s39, -1
	s_add_i32 s56, 0, 0x10000
	s_cmp_eq_u32 vcc_lo, 12
	s_cselect_b32 s49, s50, s47
	s_cselect_b32 s48, s51, s46
	s_cselect_b32 s47, s52, s73
	s_cselect_b32 s46, s53, s71
	s_add_i32 vcc_hi, 0, 0x14000
	v_add_u32_e32 v152, s56, v165
	v_add_u32_e32 v169, vcc_hi, v165
	ds_read_b128 v[128:131], v152
	ds_read_b128 v[144:147], v152 offset:1024
	ds_read_b128 v[148:151], v152 offset:2048
	ds_read_b128 v[152:155], v152 offset:3072
	ds_read_b128 v[156:159], v169
	ds_read_b128 v[160:163], v169 offset:1024
	ds_read_b128 v[170:173], v169 offset:2048
	ds_read_b128 v[180:183], v169 offset:3072
	v_lshl_add_u64 v[176:177], s[38:39], 0, v[140:141]
	s_add_i32 m0, s9, 0xc000
	ds_read_b128 v[184:187], v168
	ds_read_b128 v[188:191], v168 offset:1024
	ds_read_b128 v[192:195], v168 offset:2048
	ds_read_b128 v[196:199], v168 offset:3072
	ds_read_b128 v[200:203], v168 offset:4096
	ds_read_b128 v[204:207], v168 offset:5120
	ds_read_b128 v[218:221], v168 offset:6144
	ds_read_b128 v[222:225], v168 offset:7168
	global_load_lds_dwordx4 v[176:177], off
	v_lshl_add_u64 v[176:177], s[38:39], 0, v[142:143]
	s_add_i32 m0, s9, 0xe000
	s_nop 0
	global_load_lds_dwordx4 v[176:177], off
	s_waitcnt vmcnt(8)
	s_waitcnt lgkmcnt(0)
	s_setprio 1
	s_barrier
; #define PG8_STAGE(bufoff, gbase, voff) do { _Pragma("unroll") for (int _i = 0; _i < 2; ++_i) \
;         __builtin_amdgcn_global_load_lds((const unsigned*)((const char*)(gbase) + (voff)[_i]), (PG8_LAS unsigned*)(lds + (bufoff) + ldsw + _i * 8192), 16, 0, 0); } while (0)
; #define PG8_LDA(dst, b, h) do { _Pragma("unroll") for (int m = 0; m < 4; ++m) _Pragma("unroll") for (int k = 0; k < 2; ++k) dst[m][k] = *(const PG8_LAS bf16x8*)(lds + PG8_SA(b, h) + aoff + m * 2048 + k * 1024); } while (0)
; #define PG8_LDB(dst, b, h) do { _Pragma("unroll") for (int n = 0; n < 2; ++n) _Pragma("unroll") for (int k = 0; k < 2; ++k) dst[n][k] = *(const PG8_LAS bf16x8*)(lds + PG8_SB(b, h) + boff + n * 2048 + k * 1024); } while (0)
; #define PG8_MMA(ai, bj, At, Bt) do { __builtin_amdgcn_s_setprio(1); _Pragma("unroll") for (int m = 0; m < 4; ++m) _Pragma("unroll") for (int n = 0; n < 2; ++n) _Pragma("unroll") for (int k = 0; k < 2; ++k) \
;         acc[ai][bj][m][n] = __builtin_amdgcn_mfma_f32_16x16x32_bf16(Bt[n][k], At[m][k], acc[ai][bj][m][n], 0, 0, 0); __builtin_amdgcn_s_setprio(0); } while (0)
; #define PG8_WAIT_V(n) asm volatile("s_waitcnt vmcnt(" #n ")" ::: "memory")
; #define PG8_WAIT_L(n) asm volatile("s_waitcnt lgkmcnt(" #n ")" ::: "memory")
; #define PG8_BAR __builtin_amdgcn_s_barrier()
; #define PG8_SCHED __builtin_amdgcn_sched_barrier(0)
; template <class Epi, class Sched, bool ALIGN_EPI = false, bool SP2 = false>
; __device__ __forceinline__ void gemm_phase(PG8_LAS unsigned char* lds, const Gemm g, const Sched& S, const Epi& E) {
;     ...
;             PG8_LDB(B0, 0, 0); PG8_LDB(B1, 0, 1); PG8_SCHED; PG8_LDA(At, 0, 0); PG8_STAGE(PG8_SA(1, 1), a1 + hstep, voffA);
;             PG8_WAIT_V(8); PG8_WAIT_L(0); PG8_BAR; PG8_MMA(0, 0, At, B0); PG8_MMA(0, 1, At, B1); PG8_BAR; PG8_SCHED;
;             PG8_LDA(At, 0, 1); PG8_STAGE(PG8_SB(0, 0), b2, voffB); PG8_STAGE(PG8_SB(0, 1), b2 + hstep, voffB); PG8_STAGE(PG8_SA(0, 0), a2, voffA);
;             PG8_WAIT_V(8); PG8_WAIT_L(0); PG8_BAR; PG8_MMA(1, 0, At, B0); PG8_MMA(1, 1, At, B1); PG8_BAR; PG8_SCHED;
	v_mfma_f32_16x16x32_bf16 v[124:127], v[128:131], v[184:187], v[124:127]
	v_mfma_f32_16x16x32_bf16 v[120:123], v[148:151], v[184:187], v[120:123]
	v_mfma_f32_16x16x32_bf16 v[108:111], v[128:131], v[192:195], v[108:111]
	v_mfma_f32_16x16x32_bf16 v[104:107], v[148:151], v[192:195], v[104:107]
	v_mfma_f32_16x16x32_bf16 v[92:95], v[128:131], v[200:203], v[92:95]
	v_mfma_f32_16x16x32_bf16 v[88:91], v[148:151], v[200:203], v[88:91]
	v_mfma_f32_16x16x32_bf16 v[76:79], v[128:131], v[218:221], v[76:79]
	v_mfma_f32_16x16x32_bf16 v[72:75], v[148:151], v[218:221], v[72:75]
	v_mfma_f32_16x16x32_bf16 v[124:127], v[144:147], v[188:191], v[124:127]
	v_mfma_f32_16x16x32_bf16 v[120:123], v[152:155], v[188:191], v[120:123]
	v_mfma_f32_16x16x32_bf16 v[108:111], v[144:147], v[196:199], v[108:111]
	v_mfma_f32_16x16x32_bf16 v[104:107], v[152:155], v[196:199], v[104:107]
	v_mfma_f32_16x16x32_bf16 v[92:95], v[144:147], v[204:207], v[92:95]
	v_mfma_f32_16x16x32_bf16 v[88:91], v[152:155], v[204:207], v[88:91]
	v_mfma_f32_16x16x32_bf16 v[76:79], v[144:147], v[222:225], v[76:79]
	v_mfma_f32_16x16x32_bf16 v[72:75], v[152:155], v[222:225], v[72:75]
	v_mfma_f32_16x16x32_bf16 v[116:119], v[156:159], v[184:187], v[116:119]
	v_mfma_f32_16x16x32_bf16 v[112:115], v[170:173], v[184:187], v[112:115]
	v_mfma_f32_16x16x32_bf16 v[100:103], v[156:159], v[192:195], v[100:103]
	v_mfma_f32_16x16x32_bf16 v[96:99], v[170:173], v[192:195], v[96:99]
	v_mfma_f32_16x16x32_bf16 v[84:87], v[156:159], v[200:203], v[84:87]
	v_mfma_f32_16x16x32_bf16 v[80:83], v[170:173], v[200:203], v[80:83]
	v_mfma_f32_16x16x32_bf16 v[68:71], v[156:159], v[218:221], v[68:71]
	v_mfma_f32_16x16x32_bf16 v[64:67], v[170:173], v[218:221], v[64:67]
	v_mfma_f32_16x16x32_bf16 v[116:119], v[160:163], v[188:191], v[116:119]
	v_mfma_f32_16x16x32_bf16 v[112:115], v[180:183], v[188:191], v[112:115]
	v_mfma_f32_16x16x32_bf16 v[100:103], v[160:163], v[196:199], v[100:103]
	v_mfma_f32_16x16x32_bf16 v[96:99], v[180:183], v[196:199], v[96:99]
	v_mfma_f32_16x16x32_bf16 v[84:87], v[160:163], v[204:207], v[84:87]
	v_mfma_f32_16x16x32_bf16 v[80:83], v[180:183], v[204:207], v[80:83]
	v_mfma_f32_16x16x32_bf16 v[68:71], v[160:163], v[222:225], v[68:71]
	v_mfma_f32_16x16x32_bf16 v[64:67], v[180:183], v[222:225], v[64:67]
	s_barrier
	s_setprio 0
	s_add_i32 s56, s56, s8
	v_lshl_add_u64 v[176:177], s[46:47], 0, v[174:175]
	s_mov_b32 m0, s56
	ds_read_b128 v[184:187], v168 offset:16384
	ds_read_b128 v[188:191], v168 offset:17408
	ds_read_b128 v[192:195], v168 offset:18432
	ds_read_b128 v[196:199], v168 offset:19456
	ds_read_b128 v[200:203], v168 offset:20480
	ds_read_b128 v[204:207], v168 offset:21504
	ds_read_b128 v[218:221], v168 offset:22528
	ds_read_b128 v[222:225], v168 offset:23552
	global_load_lds_dwordx4 v[176:177], off
	s_add_i32 m0, s56, 0x2000
	s_add_u32 s56, s46, 0x40000
	v_lshl_add_u64 v[178:179], s[46:47], 0, v[136:137]
	s_addc_u32 s57, s47, 0
	s_add_i32 vcc_hi, vcc_hi, s8
	global_load_lds_dwordx4 v[178:179], off
	v_lshl_add_u64 v[208:209], s[56:57], 0, v[174:175]
	s_mov_b32 m0, vcc_hi
	v_lshl_add_u64 v[226:227], s[48:49], 0, v[134:135]
	global_load_lds_dwordx4 v[208:209], off
	v_lshl_add_u64 v[208:209], s[56:57], 0, v[136:137]
	s_add_i32 m0, vcc_hi, 0x2000
	s_nop 0
	global_load_lds_dwordx4 v[208:209], off
	v_lshl_add_u64 v[208:209], s[48:49], 0, v[132:133]
	s_mov_b32 m0, s9
	s_nop 0
	global_load_lds_dwordx4 v[208:209], off
	s_mov_b32 m0, s79
	s_nop 0
	global_load_lds_dwordx4 v[226:227], off
	s_waitcnt vmcnt(8)
	s_waitcnt lgkmcnt(0)
	s_setprio 1
	s_barrier
	v_mfma_f32_16x16x32_bf16 v[60:63], v[128:131], v[184:187], v[60:63]
	v_mfma_f32_16x16x32_bf16 v[56:59], v[148:151], v[184:187], v[56:59]
	v_mfma_f32_16x16x32_bf16 v[44:47], v[128:131], v[192:195], v[44:47]
	v_mfma_f32_16x16x32_bf16 v[40:43], v[148:151], v[192:195], v[40:43]
	v_mfma_f32_16x16x32_bf16 v[28:31], v[128:131], v[200:203], v[28:31]
	v_mfma_f32_16x16x32_bf16 v[24:27], v[148:151], v[200:203], v[24:27]
	v_mfma_f32_16x16x32_bf16 v[12:15], v[128:131], v[218:221], v[12:15]
	v_mfma_f32_16x16x32_bf16 v[8:11], v[148:151], v[218:221], v[8:11]
	v_mfma_f32_16x16x32_bf16 v[60:63], v[144:147], v[188:191], v[60:63]
	v_mfma_f32_16x16x32_bf16 v[56:59], v[152:155], v[188:191], v[56:59]
	v_mfma_f32_16x16x32_bf16 v[44:47], v[144:147], v[196:199], v[44:47]
	v_mfma_f32_16x16x32_bf16 v[40:43], v[152:155], v[196:199], v[40:43]
	v_mfma_f32_16x16x32_bf16 v[28:31], v[144:147], v[204:207], v[28:31]
	v_mfma_f32_16x16x32_bf16 v[24:27], v[152:155], v[204:207], v[24:27]
	v_mfma_f32_16x16x32_bf16 v[12:15], v[144:147], v[222:225], v[12:15]
	v_mfma_f32_16x16x32_bf16 v[8:11], v[152:155], v[222:225], v[8:11]
	v_mfma_f32_16x16x32_bf16 v[52:55], v[156:159], v[184:187], v[52:55]
	v_mfma_f32_16x16x32_bf16 v[48:51], v[170:173], v[184:187], v[48:51]
	v_mfma_f32_16x16x32_bf16 v[36:39], v[156:159], v[192:195], v[36:39]
	v_mfma_f32_16x16x32_bf16 v[32:35], v[170:173], v[192:195], v[32:35]
	v_mfma_f32_16x16x32_bf16 v[20:23], v[156:159], v[200:203], v[20:23]
	v_mfma_f32_16x16x32_bf16 v[16:19], v[170:173], v[200:203], v[16:19]
	v_mfma_f32_16x16x32_bf16 v[4:7], v[156:159], v[218:221], v[4:7]
	v_mfma_f32_16x16x32_bf16 v[0:3], v[170:173], v[218:221], v[0:3]
	v_mfma_f32_16x16x32_bf16 v[52:55], v[160:163], v[188:191], v[52:55]
	v_mfma_f32_16x16x32_bf16 v[48:51], v[180:183], v[188:191], v[48:51]
	v_mfma_f32_16x16x32_bf16 v[36:39], v[160:163], v[196:199], v[36:39]
	v_mfma_f32_16x16x32_bf16 v[32:35], v[180:183], v[196:199], v[32:35]
	v_mfma_f32_16x16x32_bf16 v[20:23], v[160:163], v[204:207], v[20:23]
	v_mfma_f32_16x16x32_bf16 v[16:19], v[180:183], v[204:207], v[16:19]
	v_mfma_f32_16x16x32_bf16 v[4:7], v[160:163], v[222:225], v[4:7]
	v_mfma_f32_16x16x32_bf16 v[0:3], v[180:183], v[222:225], v[0:3]
	s_barrier
; #define PG8_STAGE(bufoff, gbase, voff) do { _Pragma("unroll") for (int _i = 0; _i < 2; ++_i) \
;         __builtin_amdgcn_global_load_lds((const unsigned*)((const char*)(gbase) + (voff)[_i]), (PG8_LAS unsigned*)(lds + (bufoff) + ldsw + _i * 8192), 16, 0, 0); } while (0)
; #define PG8_LDA(dst, b, h) do { _Pragma("unroll") for (int m = 0; m < 4; ++m) _Pragma("unroll") for (int k = 0; k < 2; ++k) dst[m][k] = *(const PG8_LAS bf16x8*)(lds + PG8_SA(b, h) + aoff + m * 2048 + k * 1024); } while (0)
; #define PG8_LDB(dst, b, h) do { _Pragma("unroll") for (int n = 0; n < 2; ++n) _Pragma("unroll") for (int k = 0; k < 2; ++k) dst[n][k] = *(const PG8_LAS bf16x8*)(lds + PG8_SB(b, h) + boff + n * 2048 + k * 1024); } while (0)
; #define PG8_MMA(ai, bj, At, Bt) do { __builtin_amdgcn_s_setprio(1); _Pragma("unroll") for (int m = 0; m < 4; ++m) _Pragma("unroll") for (int n = 0; n < 2; ++n) _Pragma("unroll") for (int k = 0; k < 2; ++k) \
;         acc[ai][bj][m][n] = __builtin_amdgcn_mfma_f32_16x16x32_bf16(Bt[n][k], At[m][k], acc[ai][bj][m][n], 0, 0, 0); __builtin_amdgcn_s_setprio(0); } while (0)
; #define PG8_WAIT_V(n) asm volatile("s_waitcnt vmcnt(" #n ")" ::: "memory")
; #define PG8_WAIT_L(n) asm volatile("s_waitcnt lgkmcnt(" #n ")" ::: "memory")
; #define PG8_BAR __builtin_amdgcn_s_barrier()
; #define PG8_SCHED __builtin_amdgcn_sched_barrier(0)
; template <class Epi, class Sched, bool ALIGN_EPI = false, bool SP2 = false>
; __device__ __forceinline__ void gemm_phase(PG8_LAS unsigned char* lds, const Gemm g, const Sched& S, const Epi& E) {
;     ...
;             PG8_WAIT_V(8); PG8_WAIT_L(0); PG8_BAR; PG8_MMA(1, 0, At, B0); PG8_MMA(1, 1, At, B1); PG8_BAR; PG8_SCHED;
;             PG8_LDB(B0, 1, 0); PG8_LDB(B1, 1, 1); PG8_SCHED; PG8_LDA(At, 1, 0); PG8_STAGE(PG8_SA(0, 1), a2 + hstep, voffA);
;             PG8_WAIT_V(8); PG8_WAIT_L(0); PG8_BAR; PG8_MMA(0, 0, At, B0); PG8_MMA(0, 1, At, B1); PG8_BAR; PG8_SCHED;
	s_setprio 0
	s_add_i32 s56, 0, 0x18000
	s_add_i32 s57, 0, 0x1c000
	v_add_u32_e32 v152, s56, v165
	v_add_u32_e32 v169, s57, v165
	ds_read_b128 v[128:131], v152
	ds_read_b128 v[144:147], v152 offset:1024
	ds_read_b128 v[148:151], v152 offset:2048
	ds_read_b128 v[152:155], v152 offset:3072
	ds_read_b128 v[156:159], v169
	ds_read_b128 v[160:163], v169 offset:1024
	ds_read_b128 v[170:173], v169 offset:2048
	ds_read_b128 v[180:183], v169 offset:3072
	s_add_u32 s48, s48, 0x40000
	s_addc_u32 s49, s49, 0
	s_mov_b32 m0, s54
	v_lshl_add_u64 v[228:229], s[48:49], 0, v[132:133]
	ds_read_b128 v[184:187], v168 offset:32768
	ds_read_b128 v[188:191], v168 offset:33792
	ds_read_b128 v[192:195], v168 offset:34816
	ds_read_b128 v[196:199], v168 offset:35840
	ds_read_b128 v[200:203], v168 offset:36864
	ds_read_b128 v[204:207], v168 offset:37888
	ds_read_b128 v[218:221], v168 offset:38912
	ds_read_b128 v[222:225], v168 offset:39936
	global_load_lds_dwordx4 v[228:229], off
	v_lshl_add_u64 v[228:229], s[48:49], 0, v[134:135]
	s_mov_b32 m0, s55
	s_nop 0
	global_load_lds_dwordx4 v[228:229], off
	s_waitcnt vmcnt(8)
	s_waitcnt lgkmcnt(0)
	s_setprio 1
	s_barrier
	v_mfma_f32_16x16x32_bf16 v[124:127], v[128:131], v[184:187], v[124:127]
	v_mfma_f32_16x16x32_bf16 v[120:123], v[148:151], v[184:187], v[120:123]
	v_mfma_f32_16x16x32_bf16 v[108:111], v[128:131], v[192:195], v[108:111]
	v_mfma_f32_16x16x32_bf16 v[104:107], v[148:151], v[192:195], v[104:107]
	v_mfma_f32_16x16x32_bf16 v[92:95], v[128:131], v[200:203], v[92:95]
	v_mfma_f32_16x16x32_bf16 v[88:91], v[148:151], v[200:203], v[88:91]
	v_mfma_f32_16x16x32_bf16 v[76:79], v[128:131], v[218:221], v[76:79]
	v_mfma_f32_16x16x32_bf16 v[72:75], v[148:151], v[218:221], v[72:75]
	v_mfma_f32_16x16x32_bf16 v[124:127], v[144:147], v[188:191], v[124:127]
	v_mfma_f32_16x16x32_bf16 v[120:123], v[152:155], v[188:191], v[120:123]
	v_mfma_f32_16x16x32_bf16 v[108:111], v[144:147], v[196:199], v[108:111]
	v_mfma_f32_16x16x32_bf16 v[104:107], v[152:155], v[196:199], v[104:107]
	v_mfma_f32_16x16x32_bf16 v[92:95], v[144:147], v[204:207], v[92:95]
	v_mfma_f32_16x16x32_bf16 v[88:91], v[152:155], v[204:207], v[88:91]
	v_mfma_f32_16x16x32_bf16 v[76:79], v[144:147], v[222:225], v[76:79]
	v_mfma_f32_16x16x32_bf16 v[72:75], v[152:155], v[222:225], v[72:75]
	v_mfma_f32_16x16x32_bf16 v[116:119], v[156:159], v[184:187], v[116:119]
	v_mfma_f32_16x16x32_bf16 v[112:115], v[170:173], v[184:187], v[112:115]
	v_mfma_f32_16x16x32_bf16 v[100:103], v[156:159], v[192:195], v[100:103]
	v_mfma_f32_16x16x32_bf16 v[96:99], v[170:173], v[192:195], v[96:99]
	v_mfma_f32_16x16x32_bf16 v[84:87], v[156:159], v[200:203], v[84:87]
	v_mfma_f32_16x16x32_bf16 v[80:83], v[170:173], v[200:203], v[80:83]
	v_mfma_f32_16x16x32_bf16 v[68:71], v[156:159], v[218:221], v[68:71]
	v_mfma_f32_16x16x32_bf16 v[64:67], v[170:173], v[218:221], v[64:67]
	v_mfma_f32_16x16x32_bf16 v[116:119], v[160:163], v[188:191], v[116:119]
	v_mfma_f32_16x16x32_bf16 v[112:115], v[180:183], v[188:191], v[112:115]
	v_mfma_f32_16x16x32_bf16 v[100:103], v[160:163], v[196:199], v[100:103]
	v_mfma_f32_16x16x32_bf16 v[96:99], v[180:183], v[196:199], v[96:99]
	v_mfma_f32_16x16x32_bf16 v[84:87], v[160:163], v[204:207], v[84:87]
	v_mfma_f32_16x16x32_bf16 v[80:83], v[180:183], v[204:207], v[80:83]
	v_mfma_f32_16x16x32_bf16 v[68:71], v[160:163], v[222:225], v[68:71]
	v_mfma_f32_16x16x32_bf16 v[64:67], v[180:183], v[222:225], v[64:67]
	s_barrier
; #define PG8_STAGE(bufoff, gbase, voff) do { _Pragma("unroll") for (int _i = 0; _i < 2; ++_i) \
;         __builtin_amdgcn_global_load_lds((const unsigned*)((const char*)(gbase) + (voff)[_i]), (PG8_LAS unsigned*)(lds + (bufoff) + ldsw + _i * 8192), 16, 0, 0); } while (0)
; #define PG8_LDA(dst, b, h) do { _Pragma("unroll") for (int m = 0; m < 4; ++m) _Pragma("unroll") for (int k = 0; k < 2; ++k) dst[m][k] = *(const PG8_LAS bf16x8*)(lds + PG8_SA(b, h) + aoff + m * 2048 + k * 1024); } while (0)
; #define PG8_MMA(ai, bj, At, Bt) do { __builtin_amdgcn_s_setprio(1); _Pragma("unroll") for (int m = 0; m < 4; ++m) _Pragma("unroll") for (int n = 0; n < 2; ++n) _Pragma("unroll") for (int k = 0; k < 2; ++k) \
;         acc[ai][bj][m][n] = __builtin_amdgcn_mfma_f32_16x16x32_bf16(Bt[n][k], At[m][k], acc[ai][bj][m][n], 0, 0, 0); __builtin_amdgcn_s_setprio(0); } while (0)
; #define PG8_WAIT_V(n) asm volatile("s_waitcnt vmcnt(" #n ")" ::: "memory")
; #define PG8_WAIT_L(n) asm volatile("s_waitcnt lgkmcnt(" #n ")" ::: "memory")
; #define PG8_BAR __builtin_amdgcn_s_barrier()
; #define PG8_SCHED __builtin_amdgcn_sched_barrier(0)
; template <class Epi, class Sched, bool ALIGN_EPI = false, bool SP2 = false>
; __device__ __forceinline__ void gemm_phase(PG8_LAS unsigned char* lds, const Gemm g, const Sched& S, const Epi& E) {
;     ...
;             PG8_WAIT_V(8); PG8_WAIT_L(0); PG8_BAR; PG8_MMA(0, 0, At, B0); PG8_MMA(0, 1, At, B1); PG8_BAR; PG8_SCHED;
;             PG8_LDA(At, 1, 1); PG8_STAGE(PG8_SB(1, 0), b3, voffB); PG8_STAGE(PG8_SB(1, 1), b3 + hstep, voffB); PG8_STAGE(PG8_SA(1, 0), a3, voffA);
;             PG8_WAIT_V(8); PG8_WAIT_L(0); PG8_BAR; PG8_MMA(1, 0, At, B0); PG8_MMA(1, 1, At, B1); PG8_BAR; PG8_SCHED;
;     ...
;         if constexpr (ALIGN_EPI) { if (wr == 0) PG8_BAR; }
	s_setprio 0
	s_add_i32 s48, s56, s8
	v_lshl_add_u64 v[176:177], v[176:177], 0, s[4:5]
	s_mov_b32 m0, s48
	ds_read_b128 v[184:187], v168 offset:49152
	ds_read_b128 v[188:191], v168 offset:50176
	ds_read_b128 v[192:195], v168 offset:51200
	ds_read_b128 v[196:199], v168 offset:52224
	ds_read_b128 v[200:203], v168 offset:53248
	ds_read_b128 v[204:207], v168 offset:54272
	ds_read_b128 v[218:221], v168 offset:55296
	ds_read_b128 v[222:225], v168 offset:56320
	global_load_lds_dwordx4 v[176:177], off
	s_add_i32 m0, s48, 0x2000
	s_add_u32 s46, s46, 0x40080
	v_lshl_add_u64 v[176:177], v[178:179], 0, s[4:5]
	s_addc_u32 s47, s47, 0
	s_add_i32 s48, s57, s8
	global_load_lds_dwordx4 v[176:177], off
	v_lshl_add_u64 v[176:177], s[46:47], 0, v[174:175]
	s_mov_b32 m0, s48
	s_nop 0
	global_load_lds_dwordx4 v[176:177], off
	v_lshl_add_u64 v[176:177], s[46:47], 0, v[136:137]
	s_add_i32 m0, s48, 0x2000
	s_nop 0
	global_load_lds_dwordx4 v[176:177], off
	v_lshl_add_u64 v[176:177], v[208:209], 0, s[4:5]
	s_mov_b32 m0, s93
	s_nop 0
	global_load_lds_dwordx4 v[176:177], off
	v_lshl_add_u64 v[176:177], v[226:227], 0, s[4:5]
	s_mov_b32 m0, s66
	s_nop 0
	global_load_lds_dwordx4 v[176:177], off
	s_waitcnt vmcnt(8)
	s_waitcnt lgkmcnt(0)
	s_setprio 1
	s_barrier
	v_mfma_f32_16x16x32_bf16 v[60:63], v[128:131], v[184:187], v[60:63]
	v_mfma_f32_16x16x32_bf16 v[56:59], v[148:151], v[184:187], v[56:59]
	v_mfma_f32_16x16x32_bf16 v[44:47], v[128:131], v[192:195], v[44:47]
	v_mfma_f32_16x16x32_bf16 v[40:43], v[148:151], v[192:195], v[40:43]
	v_mfma_f32_16x16x32_bf16 v[28:31], v[128:131], v[200:203], v[28:31]
	v_mfma_f32_16x16x32_bf16 v[24:27], v[148:151], v[200:203], v[24:27]
	v_mfma_f32_16x16x32_bf16 v[12:15], v[128:131], v[218:221], v[12:15]
	v_mfma_f32_16x16x32_bf16 v[8:11], v[148:151], v[218:221], v[8:11]
	v_mfma_f32_16x16x32_bf16 v[60:63], v[144:147], v[188:191], v[60:63]
	v_mfma_f32_16x16x32_bf16 v[56:59], v[152:155], v[188:191], v[56:59]
	v_mfma_f32_16x16x32_bf16 v[44:47], v[144:147], v[196:199], v[44:47]
	v_mfma_f32_16x16x32_bf16 v[40:43], v[152:155], v[196:199], v[40:43]
	v_mfma_f32_16x16x32_bf16 v[28:31], v[144:147], v[204:207], v[28:31]
	v_mfma_f32_16x16x32_bf16 v[24:27], v[152:155], v[204:207], v[24:27]
	v_mfma_f32_16x16x32_bf16 v[12:15], v[144:147], v[222:225], v[12:15]
	v_mfma_f32_16x16x32_bf16 v[8:11], v[152:155], v[222:225], v[8:11]
	v_mfma_f32_16x16x32_bf16 v[52:55], v[156:159], v[184:187], v[52:55]
	v_mfma_f32_16x16x32_bf16 v[48:51], v[170:173], v[184:187], v[48:51]
	v_mfma_f32_16x16x32_bf16 v[36:39], v[156:159], v[192:195], v[36:39]
	v_mfma_f32_16x16x32_bf16 v[32:35], v[170:173], v[192:195], v[32:35]
	v_mfma_f32_16x16x32_bf16 v[20:23], v[156:159], v[200:203], v[20:23]
	v_mfma_f32_16x16x32_bf16 v[16:19], v[170:173], v[200:203], v[16:19]
	v_mfma_f32_16x16x32_bf16 v[4:7], v[156:159], v[218:221], v[4:7]
	v_mfma_f32_16x16x32_bf16 v[0:3], v[170:173], v[218:221], v[0:3]
	v_mfma_f32_16x16x32_bf16 v[52:55], v[160:163], v[188:191], v[52:55]
	v_mfma_f32_16x16x32_bf16 v[48:51], v[180:183], v[188:191], v[48:51]
	v_mfma_f32_16x16x32_bf16 v[36:39], v[160:163], v[196:199], v[36:39]
	v_mfma_f32_16x16x32_bf16 v[32:35], v[180:183], v[196:199], v[32:35]
	v_mfma_f32_16x16x32_bf16 v[20:23], v[160:163], v[204:207], v[20:23]
	v_mfma_f32_16x16x32_bf16 v[16:19], v[180:183], v[204:207], v[16:19]
	v_mfma_f32_16x16x32_bf16 v[4:7], v[160:163], v[222:225], v[4:7]
	v_mfma_f32_16x16x32_bf16 v[0:3], v[180:183], v[222:225], v[0:3]
	s_barrier
	s_setprio 0
	s_add_i32 vcc_lo, vcc_lo, 2
	s_add_u32 s38, s38, 0x100
	s_addc_u32 s39, s39, 0
	s_add_u32 s71, s71, 0x100
	s_addc_u32 s73, s73, 0
	s_cmp_gt_u32 vcc_lo, 13
	s_cbranch_scc0 .LBB0_219
	s_and_b64 vcc, exec, s[68:69]
	s_cbranch_vccz .LBB0_222
	s_barrier

; #define PG8_STAGE(bufoff, gbase, voff) do { _Pragma("unroll") for (int _i = 0; _i < 2; ++_i) \
;         __builtin_amdgcn_global_load_lds((const unsigned*)((const char*)(gbase) + (voff)[_i]), (PG8_LAS unsigned*)(lds + (bufoff) + ldsw + _i * 8192), 16, 0, 0); } while (0)
; #define PG8_LDA(dst, b, h) do { _Pragma("unroll") for (int m = 0; m < 4; ++m) _Pragma("unroll") for (int k = 0; k < 2; ++k) dst[m][k] = *(const PG8_LAS bf16x8*)(lds + PG8_SA(b, h) + aoff + m * 2048 + k * 1024); } while (0)
; #define PG8_LDB(dst, b, h) do { _Pragma("unroll") for (int n = 0; n < 2; ++n) _Pragma("unroll") for (int k = 0; k < 2; ++k) dst[n][k] = *(const PG8_LAS bf16x8*)(lds + PG8_SB(b, h) + boff + n * 2048 + k * 1024); } while (0)
; #define PG8_WAIT_V(n) asm volatile("s_waitcnt vmcnt(" #n ")" ::: "memory")
; #define PG8_WAIT_L(n) asm volatile("s_waitcnt lgkmcnt(" #n ")" ::: "memory")
; #define PG8_BAR __builtin_amdgcn_s_barrier()
; #define PG8_SCHED __builtin_amdgcn_sched_barrier(0)
; template <class Epi, class Sched, bool ALIGN_EPI = false, bool SP2 = false>
; __device__ __forceinline__ void gemm_phase(PG8_LAS unsigned char* lds, const Gemm g, const Sched& S, const Epi& E) {
;     ...
;         const bool has_next = S.next(ui + 1, nxt);
;         const char* nA = has_next ? (const char*)g.A + (size_t)nxt.pm * tstep + (size_t)nxt.pn * g.a_gs : cA; const char* nB = has_next ? (const char*)g.Bt + (size_t)nxt.pn * tstep : cB;
;         for (int t = 0; t < nt; t += 2) {
;             const bool last = (t == nt - 2);
;             const char* a1 = cA + (size_t)(t + 1) * kstep;
;             const char* a2 = last ? nA : cA + (size_t)(t + 2) * kstep; const char* b2 = last ? nB : cB + (size_t)(t + 2) * kstep;
;             const char* a3 = a2 + kstep; const char* b3 = b2 + kstep;
;             if (last && has_next) S.a_ready(nxt);
;             if constexpr (SP2) {
;             PG8_LDB(B0, 0, 0); PG8_LDB(B1, 0, 1); PG8_SCHED; PG8_LDA(At, 0, 0); PG8_STAGE(PG8_SA(1, 1), a1 + hstep, voffA);
;             PG8_WAIT_V(8); PG8_WAIT_L(0); PG8_BAR; PG8_MMA(0, 0, At, B0); PG8_MMA(0, 1, At, B1); PG8_BAR; PG8_SCHED;
;             PG8_LDA(At, 0, 1); PG8_STAGE(PG8_SB(0, 0), b2, voffB); PG8_STAGE(PG8_SB(0, 1), b2 + hstep, voffB); PG8_STAGE(PG8_SA(0, 0), a2, voffA);
;             PG8_WAIT_V(8); PG8_WAIT_L(0); PG8_BAR; PG8_MMA(1, 0, At, B0); PG8_MMA(1, 1, At, B1); PG8_BAR; PG8_SCHED;
.LBB0_1640:
	s_add_u32 s0, s0, 0x80
	s_addc_u32 s1, s1, 0
	s_add_u32 s44, s38, 0x100
	s_addc_u32 s45, s39, 0
	s_mov_b32 s38, 0
	s_add_i32 s78, s38, 2
	s_add_u32 s79, s0, 0x80
	s_addc_u32 s39, s1, 0
	s_add_i32 s93, 0, 0x10000
	s_cmp_eq_u32 s75, s38
	s_cselect_b32 s39, s63, s39
	s_cselect_b32 s38, s62, s79
	s_cselect_b32 s95, s65, s45
	s_cselect_b32 s94, s64, s44
	s_add_i32 s79, 0, 0x14000
	v_add_u32_e32 v68, s93, v218
	v_add_u32_e32 v156, s79, v218
	ds_read_b128 v[56:59], v68
	ds_read_b128 v[60:63], v68 offset:1024
	ds_read_b128 v[64:67], v68 offset:2048
	ds_read_b128 v[68:71], v68 offset:3072
	ds_read_b128 v[144:147], v156
	ds_read_b128 v[148:151], v156 offset:1024
	ds_read_b128 v[152:155], v156 offset:2048
	ds_read_b128 v[156:159], v156 offset:3072
	v_lshl_add_u64 v[172:173], s[0:1], 0, v[186:187]
	s_add_i32 m0, s9, 0xc000
	ds_read_b128 v[160:163], v220
	ds_read_b128 v[164:167], v220 offset:1024
	ds_read_b128 v[168:171], v220 offset:2048
	ds_read_b128 v[176:179], v220 offset:3072
	ds_read_b128 v[190:193], v220 offset:4096
	ds_read_b128 v[194:197], v220 offset:5120
	ds_read_b128 v[198:201], v220 offset:6144
	ds_read_b128 v[202:205], v220 offset:7168
	global_load_lds_dwordx4 v[172:173], off
	v_lshl_add_u64 v[172:173], s[0:1], 0, v[188:189]
	s_add_i32 m0, s9, 0xe000
	s_nop 0
	global_load_lds_dwordx4 v[172:173], off
	s_waitcnt vmcnt(8)
	s_waitcnt lgkmcnt(0)
	s_setprio 1
	s_barrier
	v_mfma_f32_16x16x32_bf16 v[140:143], v[56:59], v[160:163], 0
	v_mfma_f32_16x16x32_bf16 v[136:139], v[64:67], v[160:163], 0
	v_mfma_f32_16x16x32_bf16 v[124:127], v[56:59], v[168:171], 0
	v_mfma_f32_16x16x32_bf16 v[120:123], v[64:67], v[168:171], 0
	v_mfma_f32_16x16x32_bf16 v[108:111], v[56:59], v[190:193], 0
	v_mfma_f32_16x16x32_bf16 v[104:107], v[64:67], v[190:193], 0
	v_mfma_f32_16x16x32_bf16 v[92:95], v[56:59], v[198:201], 0
	v_mfma_f32_16x16x32_bf16 v[88:91], v[64:67], v[198:201], 0
	v_mfma_f32_16x16x32_bf16 v[140:143], v[60:63], v[164:167], v[140:143]
	v_mfma_f32_16x16x32_bf16 v[136:139], v[68:71], v[164:167], v[136:139]
	v_mfma_f32_16x16x32_bf16 v[124:127], v[60:63], v[176:179], v[124:127]
	v_mfma_f32_16x16x32_bf16 v[120:123], v[68:71], v[176:179], v[120:123]
	v_mfma_f32_16x16x32_bf16 v[108:111], v[60:63], v[194:197], v[108:111]
	v_mfma_f32_16x16x32_bf16 v[104:107], v[68:71], v[194:197], v[104:107]
	v_mfma_f32_16x16x32_bf16 v[92:95], v[60:63], v[202:205], v[92:95]
	v_mfma_f32_16x16x32_bf16 v[88:91], v[68:71], v[202:205], v[88:91]
	v_mfma_f32_16x16x32_bf16 v[132:135], v[144:147], v[160:163], 0
	v_mfma_f32_16x16x32_bf16 v[128:131], v[152:155], v[160:163], 0
	v_mfma_f32_16x16x32_bf16 v[116:119], v[144:147], v[168:171], 0
	v_mfma_f32_16x16x32_bf16 v[112:115], v[152:155], v[168:171], 0
	v_mfma_f32_16x16x32_bf16 v[100:103], v[144:147], v[190:193], 0
	v_mfma_f32_16x16x32_bf16 v[96:99], v[152:155], v[190:193], 0
	v_mfma_f32_16x16x32_bf16 v[84:87], v[144:147], v[198:201], 0
	v_mfma_f32_16x16x32_bf16 v[80:83], v[152:155], v[198:201], 0
	v_mfma_f32_16x16x32_bf16 v[132:135], v[148:151], v[164:167], v[132:135]
	v_mfma_f32_16x16x32_bf16 v[128:131], v[156:159], v[164:167], v[128:131]
	v_mfma_f32_16x16x32_bf16 v[116:119], v[148:151], v[176:179], v[116:119]
	v_mfma_f32_16x16x32_bf16 v[112:115], v[156:159], v[176:179], v[112:115]
	v_mfma_f32_16x16x32_bf16 v[100:103], v[148:151], v[194:197], v[100:103]
	v_mfma_f32_16x16x32_bf16 v[96:99], v[156:159], v[194:197], v[96:99]
	v_mfma_f32_16x16x32_bf16 v[84:87], v[148:151], v[202:205], v[84:87]
	v_mfma_f32_16x16x32_bf16 v[80:83], v[156:159], v[202:205], v[80:83]
	s_barrier
	s_setprio 0
	s_add_i32 s93, s93, s8
	v_lshl_add_u64 v[172:173], s[94:95], 0, v[174:175]
	s_mov_b32 m0, s93
	ds_read_b128 v[160:163], v220 offset:16384
	ds_read_b128 v[164:167], v220 offset:17408
	ds_read_b128 v[168:171], v220 offset:18432
	ds_read_b128 v[176:179], v220 offset:19456
	ds_read_b128 v[190:193], v220 offset:20480
	ds_read_b128 v[194:197], v220 offset:21504
	ds_read_b128 v[198:201], v220 offset:22528
	ds_read_b128 v[202:205], v220 offset:23552
	global_load_lds_dwordx4 v[172:173], off
	s_add_i32 m0, s93, 0x2000
	v_lshl_add_u64 v[206:207], s[94:95], 0, v[180:181]
	s_add_u32 s94, s94, s50
	s_addc_u32 s95, s95, 0
	s_add_i32 s79, s79, s8
	global_load_lds_dwordx4 v[206:207], off
	v_lshl_add_u64 v[208:209], s[94:95], 0, v[174:175]
	s_mov_b32 m0, s79
	v_lshl_add_u64 v[222:223], s[94:95], 0, v[180:181]
	global_load_lds_dwordx4 v[208:209], off
	s_add_i32 m0, s79, 0x2000
	v_lshl_add_u64 v[224:225], s[38:39], 0, v[184:185]
	global_load_lds_dwordx4 v[222:223], off
	s_mov_b32 m0, s9
	v_lshl_add_u64 v[226:227], s[38:39], 0, v[182:183]
	global_load_lds_dwordx4 v[224:225], off
	s_mov_b32 m0, s67
	s_nop 0
	global_load_lds_dwordx4 v[226:227], off
	s_waitcnt vmcnt(8)
	s_waitcnt lgkmcnt(0)
	s_setprio 1
	s_barrier
; #define PG8_STAGE(bufoff, gbase, voff) do { _Pragma("unroll") for (int _i = 0; _i < 2; ++_i) \
;         __builtin_amdgcn_global_load_lds((const unsigned*)((const char*)(gbase) + (voff)[_i]), (PG8_LAS unsigned*)(lds + (bufoff) + ldsw + _i * 8192), 16, 0, 0); } while (0)
; #define PG8_LDA(dst, b, h) do { _Pragma("unroll") for (int m = 0; m < 4; ++m) _Pragma("unroll") for (int k = 0; k < 2; ++k) dst[m][k] = *(const PG8_LAS bf16x8*)(lds + PG8_SA(b, h) + aoff + m * 2048 + k * 1024); } while (0)
; #define PG8_LDB(dst, b, h) do { _Pragma("unroll") for (int n = 0; n < 2; ++n) _Pragma("unroll") for (int k = 0; k < 2; ++k) dst[n][k] = *(const PG8_LAS bf16x8*)(lds + PG8_SB(b, h) + boff + n * 2048 + k * 1024); } while (0)
; #define PG8_MMA(ai, bj, At, Bt) do { __builtin_amdgcn_s_setprio(1); _Pragma("unroll") for (int m = 0; m < 4; ++m) _Pragma("unroll") for (int n = 0; n < 2; ++n) _Pragma("unroll") for (int k = 0; k < 2; ++k) \
;         acc[ai][bj][m][n] = __builtin_amdgcn_mfma_f32_16x16x32_bf16(Bt[n][k], At[m][k], acc[ai][bj][m][n], 0, 0, 0); __builtin_amdgcn_s_setprio(0); } while (0)
; #define PG8_WAIT_V(n) asm volatile("s_waitcnt vmcnt(" #n ")" ::: "memory")
; #define PG8_WAIT_L(n) asm volatile("s_waitcnt lgkmcnt(" #n ")" ::: "memory")
; #define PG8_BAR __builtin_amdgcn_s_barrier()
; #define PG8_SCHED __builtin_amdgcn_sched_barrier(0)
; template <class Epi, class Sched, bool ALIGN_EPI = false, bool SP2 = false>
; __device__ __forceinline__ void gemm_phase(PG8_LAS unsigned char* lds, const Gemm g, const Sched& S, const Epi& E) {
;     ...
;             PG8_WAIT_V(8); PG8_WAIT_L(0); PG8_BAR; PG8_MMA(0, 0, At, B0); PG8_MMA(0, 1, At, B1); PG8_BAR; PG8_SCHED;
;             PG8_LDA(At, 0, 1); PG8_STAGE(PG8_SB(0, 0), b2, voffB); PG8_STAGE(PG8_SB(0, 1), b2 + hstep, voffB); PG8_STAGE(PG8_SA(0, 0), a2, voffA);
;             PG8_WAIT_V(8); PG8_WAIT_L(0); PG8_BAR; PG8_MMA(1, 0, At, B0); PG8_MMA(1, 1, At, B1); PG8_BAR; PG8_SCHED;
;             PG8_LDB(B0, 1, 0); PG8_LDB(B1, 1, 1); PG8_SCHED; PG8_LDA(At, 1, 0); PG8_STAGE(PG8_SA(0, 1), a2 + hstep, voffA);
;             PG8_WAIT_V(8); PG8_WAIT_L(0); PG8_BAR; PG8_MMA(0, 0, At, B0); PG8_MMA(0, 1, At, B1); PG8_BAR; PG8_SCHED;
	v_mfma_f32_16x16x32_bf16 v[76:79], v[56:59], v[160:163], 0
	v_mfma_f32_16x16x32_bf16 v[72:75], v[64:67], v[160:163], 0
	v_mfma_f32_16x16x32_bf16 v[44:47], v[56:59], v[168:171], 0
	v_mfma_f32_16x16x32_bf16 v[40:43], v[64:67], v[168:171], 0
	v_mfma_f32_16x16x32_bf16 v[28:31], v[56:59], v[190:193], 0
	v_mfma_f32_16x16x32_bf16 v[24:27], v[64:67], v[190:193], 0
	v_mfma_f32_16x16x32_bf16 v[12:15], v[56:59], v[198:201], 0
	v_mfma_f32_16x16x32_bf16 v[8:11], v[64:67], v[198:201], 0
	v_mfma_f32_16x16x32_bf16 v[76:79], v[60:63], v[164:167], v[76:79]
	v_mfma_f32_16x16x32_bf16 v[72:75], v[68:71], v[164:167], v[72:75]
	v_mfma_f32_16x16x32_bf16 v[44:47], v[60:63], v[176:179], v[44:47]
	v_mfma_f32_16x16x32_bf16 v[40:43], v[68:71], v[176:179], v[40:43]
	v_mfma_f32_16x16x32_bf16 v[28:31], v[60:63], v[194:197], v[28:31]
	v_mfma_f32_16x16x32_bf16 v[24:27], v[68:71], v[194:197], v[24:27]
	v_mfma_f32_16x16x32_bf16 v[12:15], v[60:63], v[202:205], v[12:15]
	v_mfma_f32_16x16x32_bf16 v[8:11], v[68:71], v[202:205], v[8:11]
	v_mfma_f32_16x16x32_bf16 v[52:55], v[144:147], v[160:163], 0
	v_mfma_f32_16x16x32_bf16 v[48:51], v[152:155], v[160:163], 0
	v_mfma_f32_16x16x32_bf16 v[36:39], v[144:147], v[168:171], 0
	v_mfma_f32_16x16x32_bf16 v[32:35], v[152:155], v[168:171], 0
	v_mfma_f32_16x16x32_bf16 v[20:23], v[144:147], v[190:193], 0
	v_mfma_f32_16x16x32_bf16 v[16:19], v[152:155], v[190:193], 0
	v_mfma_f32_16x16x32_bf16 v[4:7], v[144:147], v[198:201], 0
	v_mfma_f32_16x16x32_bf16 v[0:3], v[152:155], v[198:201], 0
	v_mfma_f32_16x16x32_bf16 v[52:55], v[148:151], v[164:167], v[52:55]
	v_mfma_f32_16x16x32_bf16 v[48:51], v[156:159], v[164:167], v[48:51]
	v_mfma_f32_16x16x32_bf16 v[36:39], v[148:151], v[176:179], v[36:39]
	v_mfma_f32_16x16x32_bf16 v[32:35], v[156:159], v[176:179], v[32:35]
	v_mfma_f32_16x16x32_bf16 v[20:23], v[148:151], v[194:197], v[20:23]
	v_mfma_f32_16x16x32_bf16 v[16:19], v[156:159], v[194:197], v[16:19]
	v_mfma_f32_16x16x32_bf16 v[4:7], v[148:151], v[202:205], v[4:7]
	v_mfma_f32_16x16x32_bf16 v[0:3], v[156:159], v[202:205], v[0:3]
	s_barrier
	s_setprio 0
	s_add_i32 s79, 0, 0x18000
	s_add_i32 s93, 0, 0x1c000
	v_add_u32_e32 v68, s79, v218
	v_add_u32_e32 v156, s93, v218
	ds_read_b128 v[56:59], v68
	ds_read_b128 v[60:63], v68 offset:1024
	ds_read_b128 v[64:67], v68 offset:2048
	ds_read_b128 v[68:71], v68 offset:3072
	ds_read_b128 v[144:147], v156
	ds_read_b128 v[148:151], v156 offset:1024
	ds_read_b128 v[152:155], v156 offset:2048
	ds_read_b128 v[156:159], v156 offset:3072
	s_add_u32 s38, s38, s50
	s_addc_u32 s39, s39, 0
	s_mov_b32 m0, s68
	v_lshl_add_u64 v[228:229], s[38:39], 0, v[184:185]
	ds_read_b128 v[160:163], v220 offset:32768
	ds_read_b128 v[164:167], v220 offset:33792
	ds_read_b128 v[168:171], v220 offset:34816
	ds_read_b128 v[176:179], v220 offset:35840
	ds_read_b128 v[190:193], v220 offset:36864
	ds_read_b128 v[194:197], v220 offset:37888
	ds_read_b128 v[198:201], v220 offset:38912
	ds_read_b128 v[202:205], v220 offset:39936
	global_load_lds_dwordx4 v[228:229], off
	v_lshl_add_u64 v[228:229], s[38:39], 0, v[182:183]
	s_mov_b32 m0, s69
	s_nop 0
	global_load_lds_dwordx4 v[228:229], off
	s_waitcnt vmcnt(8)
	s_waitcnt lgkmcnt(0)
	s_setprio 1
	s_barrier
	v_mfma_f32_16x16x32_bf16 v[140:143], v[56:59], v[160:163], v[140:143]
	v_mfma_f32_16x16x32_bf16 v[136:139], v[64:67], v[160:163], v[136:139]
	v_mfma_f32_16x16x32_bf16 v[124:127], v[56:59], v[168:171], v[124:127]
	v_mfma_f32_16x16x32_bf16 v[120:123], v[64:67], v[168:171], v[120:123]
	v_mfma_f32_16x16x32_bf16 v[108:111], v[56:59], v[190:193], v[108:111]
	v_mfma_f32_16x16x32_bf16 v[104:107], v[64:67], v[190:193], v[104:107]
	v_mfma_f32_16x16x32_bf16 v[92:95], v[56:59], v[198:201], v[92:95]
	v_mfma_f32_16x16x32_bf16 v[88:91], v[64:67], v[198:201], v[88:91]
	v_mfma_f32_16x16x32_bf16 v[140:143], v[60:63], v[164:167], v[140:143]
	v_mfma_f32_16x16x32_bf16 v[136:139], v[68:71], v[164:167], v[136:139]
	v_mfma_f32_16x16x32_bf16 v[124:127], v[60:63], v[176:179], v[124:127]
	v_mfma_f32_16x16x32_bf16 v[120:123], v[68:71], v[176:179], v[120:123]
	v_mfma_f32_16x16x32_bf16 v[108:111], v[60:63], v[194:197], v[108:111]
	v_mfma_f32_16x16x32_bf16 v[104:107], v[68:71], v[194:197], v[104:107]
	v_mfma_f32_16x16x32_bf16 v[92:95], v[60:63], v[202:205], v[92:95]
	v_mfma_f32_16x16x32_bf16 v[88:91], v[68:71], v[202:205], v[88:91]
	v_mfma_f32_16x16x32_bf16 v[132:135], v[144:147], v[160:163], v[132:135]
	v_mfma_f32_16x16x32_bf16 v[128:131], v[152:155], v[160:163], v[128:131]
	v_mfma_f32_16x16x32_bf16 v[116:119], v[144:147], v[168:171], v[116:119]
	v_mfma_f32_16x16x32_bf16 v[112:115], v[152:155], v[168:171], v[112:115]
	v_mfma_f32_16x16x32_bf16 v[100:103], v[144:147], v[190:193], v[100:103]
	v_mfma_f32_16x16x32_bf16 v[96:99], v[152:155], v[190:193], v[96:99]
	v_mfma_f32_16x16x32_bf16 v[84:87], v[144:147], v[198:201], v[84:87]
	v_mfma_f32_16x16x32_bf16 v[80:83], v[152:155], v[198:201], v[80:83]
	v_mfma_f32_16x16x32_bf16 v[132:135], v[148:151], v[164:167], v[132:135]
	v_mfma_f32_16x16x32_bf16 v[128:131], v[156:159], v[164:167], v[128:131]
	v_mfma_f32_16x16x32_bf16 v[116:119], v[148:151], v[176:179], v[116:119]
	v_mfma_f32_16x16x32_bf16 v[112:115], v[156:159], v[176:179], v[112:115]
	v_mfma_f32_16x16x32_bf16 v[100:103], v[148:151], v[194:197], v[100:103]
	v_mfma_f32_16x16x32_bf16 v[96:99], v[156:159], v[194:197], v[96:99]
	v_mfma_f32_16x16x32_bf16 v[84:87], v[148:151], v[202:205], v[84:87]
	v_mfma_f32_16x16x32_bf16 v[80:83], v[156:159], v[202:205], v[80:83]
	s_barrier
; #define PG8_STAGE(bufoff, gbase, voff) do { _Pragma("unroll") for (int _i = 0; _i < 2; ++_i) \
;         __builtin_amdgcn_global_load_lds((const unsigned*)((const char*)(gbase) + (voff)[_i]), (PG8_LAS unsigned*)(lds + (bufoff) + ldsw + _i * 8192), 16, 0, 0); } while (0)
; #define PG8_LDA(dst, b, h) do { _Pragma("unroll") for (int m = 0; m < 4; ++m) _Pragma("unroll") for (int k = 0; k < 2; ++k) dst[m][k] = *(const PG8_LAS bf16x8*)(lds + PG8_SA(b, h) + aoff + m * 2048 + k * 1024); } while (0)
; #define PG8_LDB(dst, b, h) do { _Pragma("unroll") for (int n = 0; n < 2; ++n) _Pragma("unroll") for (int k = 0; k < 2; ++k) dst[n][k] = *(const PG8_LAS bf16x8*)(lds + PG8_SB(b, h) + boff + n * 2048 + k * 1024); } while (0)
; #define PG8_MMA(ai, bj, At, Bt) do { __builtin_amdgcn_s_setprio(1); _Pragma("unroll") for (int m = 0; m < 4; ++m) _Pragma("unroll") for (int n = 0; n < 2; ++n) _Pragma("unroll") for (int k = 0; k < 2; ++k) \
;         acc[ai][bj][m][n] = __builtin_amdgcn_mfma_f32_16x16x32_bf16(Bt[n][k], At[m][k], acc[ai][bj][m][n], 0, 0, 0); __builtin_amdgcn_s_setprio(0); } while (0)
; #define PG8_WAIT_V(n) asm volatile("s_waitcnt vmcnt(" #n ")" ::: "memory")
; #define PG8_WAIT_L(n) asm volatile("s_waitcnt lgkmcnt(" #n ")" ::: "memory")
; #define PG8_BAR __builtin_amdgcn_s_barrier()
; #define PG8_SCHED __builtin_amdgcn_sched_barrier(0)
; template <class Epi, class Sched, bool ALIGN_EPI = false, bool SP2 = false>
; __device__ __forceinline__ void gemm_phase(PG8_LAS unsigned char* lds, const Gemm g, const Sched& S, const Epi& E) {
;     ...
;             PG8_LDB(B0, 0, 0); PG8_LDB(B1, 0, 1); PG8_SCHED; PG8_LDA(At, 0, 0); PG8_STAGE(PG8_SA(1, 1), a1 + hstep, voffA);
;             PG8_WAIT_V(8); PG8_WAIT_L(0); PG8_BAR; PG8_MMA(0, 0, At, B0); PG8_MMA(0, 1, At, B1); PG8_BAR; PG8_SCHED;
;     ...
;             PG8_LDA(At, 1, 1); PG8_STAGE(PG8_SB(1, 0), b3, voffB); PG8_STAGE(PG8_SB(1, 1), b3 + hstep, voffB); PG8_STAGE(PG8_SA(1, 0), a3, voffA);
;             PG8_WAIT_V(8); PG8_WAIT_L(0); PG8_BAR; PG8_MMA(1, 0, At, B0); PG8_MMA(1, 1, At, B1); PG8_BAR; PG8_SCHED;
	s_setprio 0
	s_add_i32 s38, s79, s8
	v_lshl_add_u64 v[172:173], v[172:173], 0, s[4:5]
	s_mov_b32 m0, s38
	ds_read_b128 v[160:163], v220 offset:49152
	ds_read_b128 v[164:167], v220 offset:50176
	ds_read_b128 v[168:171], v220 offset:51200
	ds_read_b128 v[176:179], v220 offset:52224
	ds_read_b128 v[190:193], v220 offset:53248
	ds_read_b128 v[194:197], v220 offset:54272
	ds_read_b128 v[198:201], v220 offset:55296
	ds_read_b128 v[202:205], v220 offset:56320
	global_load_lds_dwordx4 v[172:173], off
	v_lshl_add_u64 v[172:173], v[206:207], 0, s[4:5]
	s_add_i32 m0, s38, 0x2000
	s_add_i32 s38, s93, s8
	global_load_lds_dwordx4 v[172:173], off
	v_lshl_add_u64 v[172:173], v[208:209], 0, s[4:5]
	s_mov_b32 m0, s38
	s_nop 0
	global_load_lds_dwordx4 v[172:173], off
	v_lshl_add_u64 v[172:173], v[222:223], 0, s[4:5]
	s_add_i32 m0, s38, 0x2000
	s_nop 0
	global_load_lds_dwordx4 v[172:173], off
	v_lshl_add_u64 v[172:173], v[224:225], 0, s[4:5]
	s_mov_b32 m0, s73
	s_nop 0
	global_load_lds_dwordx4 v[172:173], off
	v_lshl_add_u64 v[172:173], v[226:227], 0, s[4:5]
	s_mov_b32 m0, s74
	s_nop 0
	global_load_lds_dwordx4 v[172:173], off
	s_waitcnt vmcnt(8)
	s_waitcnt lgkmcnt(0)
	s_setprio 1
	s_barrier
	v_mfma_f32_16x16x32_bf16 v[76:79], v[56:59], v[160:163], v[76:79]
	v_mfma_f32_16x16x32_bf16 v[72:75], v[64:67], v[160:163], v[72:75]
	v_mfma_f32_16x16x32_bf16 v[44:47], v[56:59], v[168:171], v[44:47]
	v_mfma_f32_16x16x32_bf16 v[40:43], v[64:67], v[168:171], v[40:43]
	v_mfma_f32_16x16x32_bf16 v[28:31], v[56:59], v[190:193], v[28:31]
	v_mfma_f32_16x16x32_bf16 v[24:27], v[64:67], v[190:193], v[24:27]
	v_mfma_f32_16x16x32_bf16 v[12:15], v[56:59], v[198:201], v[12:15]
	v_mfma_f32_16x16x32_bf16 v[8:11], v[64:67], v[198:201], v[8:11]
	v_mfma_f32_16x16x32_bf16 v[76:79], v[60:63], v[164:167], v[76:79]
	v_mfma_f32_16x16x32_bf16 v[72:75], v[68:71], v[164:167], v[72:75]
	v_mfma_f32_16x16x32_bf16 v[44:47], v[60:63], v[176:179], v[44:47]
	v_mfma_f32_16x16x32_bf16 v[40:43], v[68:71], v[176:179], v[40:43]
	v_mfma_f32_16x16x32_bf16 v[28:31], v[60:63], v[194:197], v[28:31]
	v_mfma_f32_16x16x32_bf16 v[24:27], v[68:71], v[194:197], v[24:27]
	v_mfma_f32_16x16x32_bf16 v[12:15], v[60:63], v[202:205], v[12:15]
	v_mfma_f32_16x16x32_bf16 v[8:11], v[68:71], v[202:205], v[8:11]
	v_mfma_f32_16x16x32_bf16 v[52:55], v[144:147], v[160:163], v[52:55]
	v_mfma_f32_16x16x32_bf16 v[48:51], v[152:155], v[160:163], v[48:51]
	v_mfma_f32_16x16x32_bf16 v[36:39], v[144:147], v[168:171], v[36:39]
	v_mfma_f32_16x16x32_bf16 v[32:35], v[152:155], v[168:171], v[32:35]
	v_mfma_f32_16x16x32_bf16 v[20:23], v[144:147], v[190:193], v[20:23]
	v_mfma_f32_16x16x32_bf16 v[16:19], v[152:155], v[190:193], v[16:19]
	v_mfma_f32_16x16x32_bf16 v[4:7], v[144:147], v[198:201], v[4:7]
	v_mfma_f32_16x16x32_bf16 v[0:3], v[152:155], v[198:201], v[0:3]
	v_mfma_f32_16x16x32_bf16 v[52:55], v[148:151], v[164:167], v[52:55]
	v_mfma_f32_16x16x32_bf16 v[48:51], v[156:159], v[164:167], v[48:51]
	v_mfma_f32_16x16x32_bf16 v[36:39], v[148:151], v[176:179], v[36:39]
	v_mfma_f32_16x16x32_bf16 v[32:35], v[156:159], v[176:179], v[32:35]
	v_mfma_f32_16x16x32_bf16 v[20:23], v[148:151], v[194:197], v[20:23]
	v_mfma_f32_16x16x32_bf16 v[16:19], v[156:159], v[194:197], v[16:19]
	v_mfma_f32_16x16x32_bf16 v[4:7], v[148:151], v[202:205], v[4:7]
	v_mfma_f32_16x16x32_bf16 v[0:3], v[156:159], v[202:205], v[0:3]
	s_barrier
	s_setprio 0
	s_add_u32 s0, s0, 0x100
	s_addc_u32 s1, s1, 0
	s_add_u32 s44, s44, 0x100
	s_addc_u32 s45, s45, 0
	s_cmp_ge_u32 s78, s72
	s_mov_b32 s38, s78
	s_cbranch_scc0 .LBB0_1641
.LBB0_1641:
	s_add_i32 s78, s38, 2
	s_add_u32 s79, s0, 0x80
	s_addc_u32 s39, s1, 0
	s_add_i32 s93, 0, 0x10000
	s_cmp_eq_u32 s75, s38
	s_cselect_b32 s39, s63, s39
	s_cselect_b32 s38, s62, s79
	s_cselect_b32 s95, s65, s45
	s_cselect_b32 s94, s64, s44
	s_add_i32 s79, 0, 0x14000
	v_add_u32_e32 v68, s93, v218
	v_add_u32_e32 v156, s79, v218
	ds_read_b128 v[56:59], v68
	ds_read_b128 v[60:63], v68 offset:1024
	ds_read_b128 v[64:67], v68 offset:2048
	ds_read_b128 v[68:71], v68 offset:3072
	ds_read_b128 v[144:147], v156
	ds_read_b128 v[148:151], v156 offset:1024
	ds_read_b128 v[152:155], v156 offset:2048
	ds_read_b128 v[156:159], v156 offset:3072
	v_lshl_add_u64 v[172:173], s[0:1], 0, v[186:187]
	s_add_i32 m0, s9, 0xc000
	ds_read_b128 v[160:163], v220
	ds_read_b128 v[164:167], v220 offset:1024
	ds_read_b128 v[168:171], v220 offset:2048
	ds_read_b128 v[176:179], v220 offset:3072
	ds_read_b128 v[190:193], v220 offset:4096
	ds_read_b128 v[194:197], v220 offset:5120
	ds_read_b128 v[198:201], v220 offset:6144
	ds_read_b128 v[202:205], v220 offset:7168
	global_load_lds_dwordx4 v[172:173], off
	v_lshl_add_u64 v[172:173], s[0:1], 0, v[188:189]
	s_add_i32 m0, s9, 0xe000
	s_nop 0
	global_load_lds_dwordx4 v[172:173], off
	s_waitcnt vmcnt(8)
	s_waitcnt lgkmcnt(0)
	s_setprio 1
	s_barrier
; #define PG8_STAGE(bufoff, gbase, voff) do { _Pragma("unroll") for (int _i = 0; _i < 2; ++_i) \
;         __builtin_amdgcn_global_load_lds((const unsigned*)((const char*)(gbase) + (voff)[_i]), (PG8_LAS unsigned*)(lds + (bufoff) + ldsw + _i * 8192), 16, 0, 0); } while (0)
; #define PG8_LDA(dst, b, h) do { _Pragma("unroll") for (int m = 0; m < 4; ++m) _Pragma("unroll") for (int k = 0; k < 2; ++k) dst[m][k] = *(const PG8_LAS bf16x8*)(lds + PG8_SA(b, h) + aoff + m * 2048 + k * 1024); } while (0)
; #define PG8_LDB(dst, b, h) do { _Pragma("unroll") for (int n = 0; n < 2; ++n) _Pragma("unroll") for (int k = 0; k < 2; ++k) dst[n][k] = *(const PG8_LAS bf16x8*)(lds + PG8_SB(b, h) + boff + n * 2048 + k * 1024); } while (0)
; #define PG8_MMA(ai, bj, At, Bt) do { __builtin_amdgcn_s_setprio(1); _Pragma("unroll") for (int m = 0; m < 4; ++m) _Pragma("unroll") for (int n = 0; n < 2; ++n) _Pragma("unroll") for (int k = 0; k < 2; ++k) \
;         acc[ai][bj][m][n] = __builtin_amdgcn_mfma_f32_16x16x32_bf16(Bt[n][k], At[m][k], acc[ai][bj][m][n], 0, 0, 0); __builtin_amdgcn_s_setprio(0); } while (0)
; #define PG8_WAIT_V(n) asm volatile("s_waitcnt vmcnt(" #n ")" ::: "memory")
; #define PG8_WAIT_L(n) asm volatile("s_waitcnt lgkmcnt(" #n ")" ::: "memory")
; #define PG8_BAR __builtin_amdgcn_s_barrier()
; #define PG8_SCHED __builtin_amdgcn_sched_barrier(0)
; template <class Epi, class Sched, bool ALIGN_EPI = false, bool SP2 = false>
; __device__ __forceinline__ void gemm_phase(PG8_LAS unsigned char* lds, const Gemm g, const Sched& S, const Epi& E) {
;     ...
;             PG8_LDB(B0, 0, 0); PG8_LDB(B1, 0, 1); PG8_SCHED; PG8_LDA(At, 0, 0); PG8_STAGE(PG8_SA(1, 1), a1 + hstep, voffA);
;             PG8_WAIT_V(8); PG8_WAIT_L(0); PG8_BAR; PG8_MMA(0, 0, At, B0); PG8_MMA(0, 1, At, B1); PG8_BAR; PG8_SCHED;
;             PG8_LDA(At, 0, 1); PG8_STAGE(PG8_SB(0, 0), b2, voffB); PG8_STAGE(PG8_SB(0, 1), b2 + hstep, voffB); PG8_STAGE(PG8_SA(0, 0), a2, voffA);
;             PG8_WAIT_V(8); PG8_WAIT_L(0); PG8_BAR; PG8_MMA(1, 0, At, B0); PG8_MMA(1, 1, At, B1); PG8_BAR; PG8_SCHED;
	v_mfma_f32_16x16x32_bf16 v[140:143], v[56:59], v[160:163], v[140:143]
	v_mfma_f32_16x16x32_bf16 v[136:139], v[64:67], v[160:163], v[136:139]
	v_mfma_f32_16x16x32_bf16 v[124:127], v[56:59], v[168:171], v[124:127]
	v_mfma_f32_16x16x32_bf16 v[120:123], v[64:67], v[168:171], v[120:123]
	v_mfma_f32_16x16x32_bf16 v[108:111], v[56:59], v[190:193], v[108:111]
	v_mfma_f32_16x16x32_bf16 v[104:107], v[64:67], v[190:193], v[104:107]
	v_mfma_f32_16x16x32_bf16 v[92:95], v[56:59], v[198:201], v[92:95]
	v_mfma_f32_16x16x32_bf16 v[88:91], v[64:67], v[198:201], v[88:91]
	v_mfma_f32_16x16x32_bf16 v[140:143], v[60:63], v[164:167], v[140:143]
	v_mfma_f32_16x16x32_bf16 v[136:139], v[68:71], v[164:167], v[136:139]
	v_mfma_f32_16x16x32_bf16 v[124:127], v[60:63], v[176:179], v[124:127]
	v_mfma_f32_16x16x32_bf16 v[120:123], v[68:71], v[176:179], v[120:123]
	v_mfma_f32_16x16x32_bf16 v[108:111], v[60:63], v[194:197], v[108:111]
	v_mfma_f32_16x16x32_bf16 v[104:107], v[68:71], v[194:197], v[104:107]
	v_mfma_f32_16x16x32_bf16 v[92:95], v[60:63], v[202:205], v[92:95]
	v_mfma_f32_16x16x32_bf16 v[88:91], v[68:71], v[202:205], v[88:91]
	v_mfma_f32_16x16x32_bf16 v[132:135], v[144:147], v[160:163], v[132:135]
	v_mfma_f32_16x16x32_bf16 v[128:131], v[152:155], v[160:163], v[128:131]
	v_mfma_f32_16x16x32_bf16 v[116:119], v[144:147], v[168:171], v[116:119]
	v_mfma_f32_16x16x32_bf16 v[112:115], v[152:155], v[168:171], v[112:115]
	v_mfma_f32_16x16x32_bf16 v[100:103], v[144:147], v[190:193], v[100:103]
	v_mfma_f32_16x16x32_bf16 v[96:99], v[152:155], v[190:193], v[96:99]
	v_mfma_f32_16x16x32_bf16 v[84:87], v[144:147], v[198:201], v[84:87]
	v_mfma_f32_16x16x32_bf16 v[80:83], v[152:155], v[198:201], v[80:83]
	v_mfma_f32_16x16x32_bf16 v[132:135], v[148:151], v[164:167], v[132:135]
	v_mfma_f32_16x16x32_bf16 v[128:131], v[156:159], v[164:167], v[128:131]
	v_mfma_f32_16x16x32_bf16 v[116:119], v[148:151], v[176:179], v[116:119]
	v_mfma_f32_16x16x32_bf16 v[112:115], v[156:159], v[176:179], v[112:115]
	v_mfma_f32_16x16x32_bf16 v[100:103], v[148:151], v[194:197], v[100:103]
	v_mfma_f32_16x16x32_bf16 v[96:99], v[156:159], v[194:197], v[96:99]
	v_mfma_f32_16x16x32_bf16 v[84:87], v[148:151], v[202:205], v[84:87]
	v_mfma_f32_16x16x32_bf16 v[80:83], v[156:159], v[202:205], v[80:83]
	s_barrier
	s_setprio 0
	s_add_i32 s93, s93, s8
	v_lshl_add_u64 v[172:173], s[94:95], 0, v[174:175]
	s_mov_b32 m0, s93
	ds_read_b128 v[160:163], v220 offset:16384
	ds_read_b128 v[164:167], v220 offset:17408
	ds_read_b128 v[168:171], v220 offset:18432
	ds_read_b128 v[176:179], v220 offset:19456
	ds_read_b128 v[190:193], v220 offset:20480
	ds_read_b128 v[194:197], v220 offset:21504
	ds_read_b128 v[198:201], v220 offset:22528
	ds_read_b128 v[202:205], v220 offset:23552
	global_load_lds_dwordx4 v[172:173], off
	s_add_i32 m0, s93, 0x2000
	v_lshl_add_u64 v[206:207], s[94:95], 0, v[180:181]
	s_add_u32 s94, s94, s50
	s_addc_u32 s95, s95, 0
	s_add_i32 s79, s79, s8
	global_load_lds_dwordx4 v[206:207], off
	v_lshl_add_u64 v[208:209], s[94:95], 0, v[174:175]
	s_mov_b32 m0, s79
	v_lshl_add_u64 v[222:223], s[94:95], 0, v[180:181]
	global_load_lds_dwordx4 v[208:209], off
	s_add_i32 m0, s79, 0x2000
	v_lshl_add_u64 v[224:225], s[38:39], 0, v[184:185]
	global_load_lds_dwordx4 v[222:223], off
	s_mov_b32 m0, s9
	v_lshl_add_u64 v[226:227], s[38:39], 0, v[182:183]
	global_load_lds_dwordx4 v[224:225], off
	s_mov_b32 m0, s67
	s_nop 0
	global_load_lds_dwordx4 v[226:227], off
	s_waitcnt vmcnt(8)
	s_waitcnt lgkmcnt(0)
	s_setprio 1
	s_barrier
	v_mfma_f32_16x16x32_bf16 v[76:79], v[56:59], v[160:163], v[76:79]
	v_mfma_f32_16x16x32_bf16 v[72:75], v[64:67], v[160:163], v[72:75]
	v_mfma_f32_16x16x32_bf16 v[44:47], v[56:59], v[168:171], v[44:47]
	v_mfma_f32_16x16x32_bf16 v[40:43], v[64:67], v[168:171], v[40:43]
	v_mfma_f32_16x16x32_bf16 v[28:31], v[56:59], v[190:193], v[28:31]
	v_mfma_f32_16x16x32_bf16 v[24:27], v[64:67], v[190:193], v[24:27]
	v_mfma_f32_16x16x32_bf16 v[12:15], v[56:59], v[198:201], v[12:15]
	v_mfma_f32_16x16x32_bf16 v[8:11], v[64:67], v[198:201], v[8:11]
	v_mfma_f32_16x16x32_bf16 v[76:79], v[60:63], v[164:167], v[76:79]
	v_mfma_f32_16x16x32_bf16 v[72:75], v[68:71], v[164:167], v[72:75]
	v_mfma_f32_16x16x32_bf16 v[44:47], v[60:63], v[176:179], v[44:47]
	v_mfma_f32_16x16x32_bf16 v[40:43], v[68:71], v[176:179], v[40:43]
	v_mfma_f32_16x16x32_bf16 v[28:31], v[60:63], v[194:197], v[28:31]
	v_mfma_f32_16x16x32_bf16 v[24:27], v[68:71], v[194:197], v[24:27]
	v_mfma_f32_16x16x32_bf16 v[12:15], v[60:63], v[202:205], v[12:15]
	v_mfma_f32_16x16x32_bf16 v[8:11], v[68:71], v[202:205], v[8:11]
	v_mfma_f32_16x16x32_bf16 v[52:55], v[144:147], v[160:163], v[52:55]
	v_mfma_f32_16x16x32_bf16 v[48:51], v[152:155], v[160:163], v[48:51]
	v_mfma_f32_16x16x32_bf16 v[36:39], v[144:147], v[168:171], v[36:39]
	v_mfma_f32_16x16x32_bf16 v[32:35], v[152:155], v[168:171], v[32:35]
	v_mfma_f32_16x16x32_bf16 v[20:23], v[144:147], v[190:193], v[20:23]
	v_mfma_f32_16x16x32_bf16 v[16:19], v[152:155], v[190:193], v[16:19]
	v_mfma_f32_16x16x32_bf16 v[4:7], v[144:147], v[198:201], v[4:7]
	v_mfma_f32_16x16x32_bf16 v[0:3], v[152:155], v[198:201], v[0:3]
	v_mfma_f32_16x16x32_bf16 v[52:55], v[148:151], v[164:167], v[52:55]
	v_mfma_f32_16x16x32_bf16 v[48:51], v[156:159], v[164:167], v[48:51]
	v_mfma_f32_16x16x32_bf16 v[36:39], v[148:151], v[176:179], v[36:39]
	v_mfma_f32_16x16x32_bf16 v[32:35], v[156:159], v[176:179], v[32:35]
	v_mfma_f32_16x16x32_bf16 v[20:23], v[148:151], v[194:197], v[20:23]
	v_mfma_f32_16x16x32_bf16 v[16:19], v[156:159], v[194:197], v[16:19]
	v_mfma_f32_16x16x32_bf16 v[4:7], v[148:151], v[202:205], v[4:7]
	v_mfma_f32_16x16x32_bf16 v[0:3], v[156:159], v[202:205], v[0:3]
	s_barrier
; #define PG8_STAGE(bufoff, gbase, voff) do { _Pragma("unroll") for (int _i = 0; _i < 2; ++_i) \
;         __builtin_amdgcn_global_load_lds((const unsigned*)((const char*)(gbase) + (voff)[_i]), (PG8_LAS unsigned*)(lds + (bufoff) + ldsw + _i * 8192), 16, 0, 0); } while (0)
; #define PG8_LDA(dst, b, h) do { _Pragma("unroll") for (int m = 0; m < 4; ++m) _Pragma("unroll") for (int k = 0; k < 2; ++k) dst[m][k] = *(const PG8_LAS bf16x8*)(lds + PG8_SA(b, h) + aoff + m * 2048 + k * 1024); } while (0)
; #define PG8_LDB(dst, b, h) do { _Pragma("unroll") for (int n = 0; n < 2; ++n) _Pragma("unroll") for (int k = 0; k < 2; ++k) dst[n][k] = *(const PG8_LAS bf16x8*)(lds + PG8_SB(b, h) + boff + n * 2048 + k * 1024); } while (0)
; #define PG8_MMA(ai, bj, At, Bt) do { __builtin_amdgcn_s_setprio(1); _Pragma("unroll") for (int m = 0; m < 4; ++m) _Pragma("unroll") for (int n = 0; n < 2; ++n) _Pragma("unroll") for (int k = 0; k < 2; ++k) \
;         acc[ai][bj][m][n] = __builtin_amdgcn_mfma_f32_16x16x32_bf16(Bt[n][k], At[m][k], acc[ai][bj][m][n], 0, 0, 0); __builtin_amdgcn_s_setprio(0); } while (0)
; #define PG8_WAIT_V(n) asm volatile("s_waitcnt vmcnt(" #n ")" ::: "memory")
; #define PG8_WAIT_L(n) asm volatile("s_waitcnt lgkmcnt(" #n ")" ::: "memory")
; #define PG8_BAR __builtin_amdgcn_s_barrier()
; #define PG8_SCHED __builtin_amdgcn_sched_barrier(0)
; template <class Epi, class Sched, bool ALIGN_EPI = false, bool SP2 = false>
; __device__ __forceinline__ void gemm_phase(PG8_LAS unsigned char* lds, const Gemm g, const Sched& S, const Epi& E) {
;     ...
;             PG8_LDB(B0, 1, 0); PG8_LDB(B1, 1, 1); PG8_SCHED; PG8_LDA(At, 1, 0); PG8_STAGE(PG8_SA(0, 1), a2 + hstep, voffA);
;             PG8_WAIT_V(8); PG8_WAIT_L(0); PG8_BAR; PG8_MMA(0, 0, At, B0); PG8_MMA(0, 1, At, B1); PG8_BAR; PG8_SCHED;
;             PG8_LDA(At, 1, 1); PG8_STAGE(PG8_SB(1, 0), b3, voffB); PG8_STAGE(PG8_SB(1, 1), b3 + hstep, voffB); PG8_STAGE(PG8_SA(1, 0), a3, voffA);
;             PG8_WAIT_V(8); PG8_WAIT_L(0); PG8_BAR; PG8_MMA(1, 0, At, B0); PG8_MMA(1, 1, At, B1); PG8_BAR; PG8_SCHED;
;     ...
;         if constexpr (ALIGN_EPI) { if (wr == 0) PG8_BAR; }
	s_setprio 0
	s_add_i32 s79, 0, 0x18000
	s_add_i32 s93, 0, 0x1c000
	v_add_u32_e32 v68, s79, v218
	v_add_u32_e32 v156, s93, v218
	ds_read_b128 v[56:59], v68
	ds_read_b128 v[60:63], v68 offset:1024
	ds_read_b128 v[64:67], v68 offset:2048
	ds_read_b128 v[68:71], v68 offset:3072
	ds_read_b128 v[144:147], v156
	ds_read_b128 v[148:151], v156 offset:1024
	ds_read_b128 v[152:155], v156 offset:2048
	ds_read_b128 v[156:159], v156 offset:3072
	s_add_u32 s38, s38, s50
	s_addc_u32 s39, s39, 0
	s_mov_b32 m0, s68
	v_lshl_add_u64 v[228:229], s[38:39], 0, v[184:185]
	ds_read_b128 v[160:163], v220 offset:32768
	ds_read_b128 v[164:167], v220 offset:33792
	ds_read_b128 v[168:171], v220 offset:34816
	ds_read_b128 v[176:179], v220 offset:35840
	ds_read_b128 v[190:193], v220 offset:36864
	ds_read_b128 v[194:197], v220 offset:37888
	ds_read_b128 v[198:201], v220 offset:38912
	ds_read_b128 v[202:205], v220 offset:39936
	global_load_lds_dwordx4 v[228:229], off
	v_lshl_add_u64 v[228:229], s[38:39], 0, v[182:183]
	s_mov_b32 m0, s69
	s_nop 0
	global_load_lds_dwordx4 v[228:229], off
	s_waitcnt vmcnt(8)
	s_waitcnt lgkmcnt(0)
	s_setprio 1
	s_barrier
	v_mfma_f32_16x16x32_bf16 v[140:143], v[56:59], v[160:163], v[140:143]
	v_mfma_f32_16x16x32_bf16 v[136:139], v[64:67], v[160:163], v[136:139]
	v_mfma_f32_16x16x32_bf16 v[124:127], v[56:59], v[168:171], v[124:127]
	v_mfma_f32_16x16x32_bf16 v[120:123], v[64:67], v[168:171], v[120:123]
	v_mfma_f32_16x16x32_bf16 v[108:111], v[56:59], v[190:193], v[108:111]
	v_mfma_f32_16x16x32_bf16 v[104:107], v[64:67], v[190:193], v[104:107]
	v_mfma_f32_16x16x32_bf16 v[92:95], v[56:59], v[198:201], v[92:95]
	v_mfma_f32_16x16x32_bf16 v[88:91], v[64:67], v[198:201], v[88:91]
	v_mfma_f32_16x16x32_bf16 v[140:143], v[60:63], v[164:167], v[140:143]
	v_mfma_f32_16x16x32_bf16 v[136:139], v[68:71], v[164:167], v[136:139]
	v_mfma_f32_16x16x32_bf16 v[124:127], v[60:63], v[176:179], v[124:127]
	v_mfma_f32_16x16x32_bf16 v[120:123], v[68:71], v[176:179], v[120:123]
	v_mfma_f32_16x16x32_bf16 v[108:111], v[60:63], v[194:197], v[108:111]
	v_mfma_f32_16x16x32_bf16 v[104:107], v[68:71], v[194:197], v[104:107]
	v_mfma_f32_16x16x32_bf16 v[92:95], v[60:63], v[202:205], v[92:95]
	v_mfma_f32_16x16x32_bf16 v[88:91], v[68:71], v[202:205], v[88:91]
	v_mfma_f32_16x16x32_bf16 v[132:135], v[144:147], v[160:163], v[132:135]
	v_mfma_f32_16x16x32_bf16 v[128:131], v[152:155], v[160:163], v[128:131]
	v_mfma_f32_16x16x32_bf16 v[116:119], v[144:147], v[168:171], v[116:119]
	v_mfma_f32_16x16x32_bf16 v[112:115], v[152:155], v[168:171], v[112:115]
	v_mfma_f32_16x16x32_bf16 v[100:103], v[144:147], v[190:193], v[100:103]
	v_mfma_f32_16x16x32_bf16 v[96:99], v[152:155], v[190:193], v[96:99]
	v_mfma_f32_16x16x32_bf16 v[84:87], v[144:147], v[198:201], v[84:87]
	v_mfma_f32_16x16x32_bf16 v[80:83], v[152:155], v[198:201], v[80:83]
	v_mfma_f32_16x16x32_bf16 v[132:135], v[148:151], v[164:167], v[132:135]
	v_mfma_f32_16x16x32_bf16 v[128:131], v[156:159], v[164:167], v[128:131]
	v_mfma_f32_16x16x32_bf16 v[116:119], v[148:151], v[176:179], v[116:119]
	v_mfma_f32_16x16x32_bf16 v[112:115], v[156:159], v[176:179], v[112:115]
	v_mfma_f32_16x16x32_bf16 v[100:103], v[148:151], v[194:197], v[100:103]
	v_mfma_f32_16x16x32_bf16 v[96:99], v[156:159], v[194:197], v[96:99]
	v_mfma_f32_16x16x32_bf16 v[84:87], v[148:151], v[202:205], v[84:87]
	v_mfma_f32_16x16x32_bf16 v[80:83], v[156:159], v[202:205], v[80:83]
	s_barrier
	s_setprio 0
	s_add_i32 s38, s79, s8
	v_lshl_add_u64 v[172:173], v[172:173], 0, s[4:5]
	s_mov_b32 m0, s38
	ds_read_b128 v[160:163], v220 offset:49152
	ds_read_b128 v[164:167], v220 offset:50176
	ds_read_b128 v[168:171], v220 offset:51200
	ds_read_b128 v[176:179], v220 offset:52224
	ds_read_b128 v[190:193], v220 offset:53248
	ds_read_b128 v[194:197], v220 offset:54272
	ds_read_b128 v[198:201], v220 offset:55296
	ds_read_b128 v[202:205], v220 offset:56320
	global_load_lds_dwordx4 v[172:173], off
	v_lshl_add_u64 v[172:173], v[206:207], 0, s[4:5]
	s_add_i32 m0, s38, 0x2000
	s_add_i32 s38, s93, s8
	global_load_lds_dwordx4 v[172:173], off
	v_lshl_add_u64 v[172:173], v[208:209], 0, s[4:5]
	s_mov_b32 m0, s38
	s_nop 0
	global_load_lds_dwordx4 v[172:173], off
	v_lshl_add_u64 v[172:173], v[222:223], 0, s[4:5]
	s_add_i32 m0, s38, 0x2000
	s_nop 0
	global_load_lds_dwordx4 v[172:173], off
	v_lshl_add_u64 v[172:173], v[224:225], 0, s[4:5]
	s_mov_b32 m0, s73
	s_nop 0
	global_load_lds_dwordx4 v[172:173], off
	v_lshl_add_u64 v[172:173], v[226:227], 0, s[4:5]
	s_mov_b32 m0, s74
	s_nop 0
	global_load_lds_dwordx4 v[172:173], off
	s_waitcnt vmcnt(8)
	s_waitcnt lgkmcnt(0)
	s_setprio 1
	s_barrier
	v_mfma_f32_16x16x32_bf16 v[76:79], v[56:59], v[160:163], v[76:79]
	v_mfma_f32_16x16x32_bf16 v[72:75], v[64:67], v[160:163], v[72:75]
	v_mfma_f32_16x16x32_bf16 v[44:47], v[56:59], v[168:171], v[44:47]
	v_mfma_f32_16x16x32_bf16 v[40:43], v[64:67], v[168:171], v[40:43]
	v_mfma_f32_16x16x32_bf16 v[28:31], v[56:59], v[190:193], v[28:31]
	v_mfma_f32_16x16x32_bf16 v[24:27], v[64:67], v[190:193], v[24:27]
	v_mfma_f32_16x16x32_bf16 v[12:15], v[56:59], v[198:201], v[12:15]
	v_mfma_f32_16x16x32_bf16 v[8:11], v[64:67], v[198:201], v[8:11]
	v_mfma_f32_16x16x32_bf16 v[76:79], v[60:63], v[164:167], v[76:79]
	v_mfma_f32_16x16x32_bf16 v[72:75], v[68:71], v[164:167], v[72:75]
	v_mfma_f32_16x16x32_bf16 v[44:47], v[60:63], v[176:179], v[44:47]
	v_mfma_f32_16x16x32_bf16 v[40:43], v[68:71], v[176:179], v[40:43]
	v_mfma_f32_16x16x32_bf16 v[28:31], v[60:63], v[194:197], v[28:31]
	v_mfma_f32_16x16x32_bf16 v[24:27], v[68:71], v[194:197], v[24:27]
	v_mfma_f32_16x16x32_bf16 v[12:15], v[60:63], v[202:205], v[12:15]
	v_mfma_f32_16x16x32_bf16 v[8:11], v[68:71], v[202:205], v[8:11]
	v_mfma_f32_16x16x32_bf16 v[52:55], v[144:147], v[160:163], v[52:55]
	v_mfma_f32_16x16x32_bf16 v[48:51], v[152:155], v[160:163], v[48:51]
	v_mfma_f32_16x16x32_bf16 v[36:39], v[144:147], v[168:171], v[36:39]
	v_mfma_f32_16x16x32_bf16 v[32:35], v[152:155], v[168:171], v[32:35]
	v_mfma_f32_16x16x32_bf16 v[20:23], v[144:147], v[190:193], v[20:23]
	v_mfma_f32_16x16x32_bf16 v[16:19], v[152:155], v[190:193], v[16:19]
	v_mfma_f32_16x16x32_bf16 v[4:7], v[144:147], v[198:201], v[4:7]
	v_mfma_f32_16x16x32_bf16 v[0:3], v[152:155], v[198:201], v[0:3]
	v_mfma_f32_16x16x32_bf16 v[52:55], v[148:151], v[164:167], v[52:55]
	v_mfma_f32_16x16x32_bf16 v[48:51], v[156:159], v[164:167], v[48:51]
	v_mfma_f32_16x16x32_bf16 v[36:39], v[148:151], v[176:179], v[36:39]
	v_mfma_f32_16x16x32_bf16 v[32:35], v[156:159], v[176:179], v[32:35]
	v_mfma_f32_16x16x32_bf16 v[20:23], v[148:151], v[194:197], v[20:23]
	v_mfma_f32_16x16x32_bf16 v[16:19], v[156:159], v[194:197], v[16:19]
	v_mfma_f32_16x16x32_bf16 v[4:7], v[148:151], v[202:205], v[4:7]
	v_mfma_f32_16x16x32_bf16 v[0:3], v[156:159], v[202:205], v[0:3]
	s_barrier
	s_setprio 0
	s_add_u32 s0, s0, 0x100
	s_addc_u32 s1, s1, 0
	s_add_u32 s44, s44, 0x100
	s_addc_u32 s45, s45, 0
	s_cmp_ge_u32 s78, s72
	s_mov_b32 s38, s78
	s_cbranch_scc0 .LBB0_1641
	s_and_b64 vcc, exec, s[58:59]
	s_cbranch_vccz .LBB0_1644
	s_barrier

; #define PG8_STAGE(bufoff, gbase, voff) do { _Pragma("unroll") for (int _i = 0; _i < 2; ++_i) \
;         __builtin_amdgcn_global_load_lds((const unsigned*)((const char*)(gbase) + (voff)[_i]), (PG8_LAS unsigned*)(lds + (bufoff) + ldsw + _i * 8192), 16, 0, 0); } while (0)
; #define PG8_LDA(dst, b, h) do { _Pragma("unroll") for (int m = 0; m < 4; ++m) _Pragma("unroll") for (int k = 0; k < 2; ++k) dst[m][k] = *(const PG8_LAS bf16x8*)(lds + PG8_SA(b, h) + aoff + m * 2048 + k * 1024); } while (0)
; #define PG8_LDB(dst, b, h) do { _Pragma("unroll") for (int n = 0; n < 2; ++n) _Pragma("unroll") for (int k = 0; k < 2; ++k) dst[n][k] = *(const PG8_LAS bf16x8*)(lds + PG8_SB(b, h) + boff + n * 2048 + k * 1024); } while (0)
; #define PG8_WAIT_V(n) asm volatile("s_waitcnt vmcnt(" #n ")" ::: "memory")
; #define PG8_WAIT_L(n) asm volatile("s_waitcnt lgkmcnt(" #n ")" ::: "memory")
; #define PG8_BAR __builtin_amdgcn_s_barrier()
; #define PG8_SCHED __builtin_amdgcn_sched_barrier(0)
; template <class Epi, class Sched, bool ALIGN_EPI = false, bool SP2 = false>
; __device__ __forceinline__ void gemm_phase(PG8_LAS unsigned char* lds, const Gemm g, const Sched& S, const Epi& E) {
;     ...
;         const bool has_next = S.next(ui + 1, nxt);
;         const char* nA = has_next ? (const char*)g.A + (size_t)nxt.pm * tstep + (size_t)nxt.pn * g.a_gs : cA; const char* nB = has_next ? (const char*)g.Bt + (size_t)nxt.pn * tstep : cB;
;         for (int t = 0; t < nt; t += 2) {
;             const bool last = (t == nt - 2);
;             const char* a1 = cA + (size_t)(t + 1) * kstep;
;             const char* a2 = last ? nA : cA + (size_t)(t + 2) * kstep; const char* b2 = last ? nB : cB + (size_t)(t + 2) * kstep;
;             const char* a3 = a2 + kstep; const char* b3 = b2 + kstep;
;             if (last && has_next) S.a_ready(nxt);
;             if constexpr (SP2) {
;             PG8_LDB(B0, 0, 0); PG8_LDB(B1, 0, 1); PG8_SCHED; PG8_LDA(At, 0, 0); PG8_STAGE(PG8_SA(1, 1), a1 + hstep, voffA);
;             PG8_WAIT_V(8); PG8_WAIT_L(0); PG8_BAR; PG8_MMA(0, 0, At, B0); PG8_MMA(0, 1, At, B1); PG8_BAR; PG8_SCHED;
;             PG8_LDA(At, 0, 1); PG8_STAGE(PG8_SB(0, 0), b2, voffB); PG8_STAGE(PG8_SB(0, 1), b2 + hstep, voffB); PG8_STAGE(PG8_SA(0, 0), a2, voffA);
;             PG8_WAIT_V(8); PG8_WAIT_L(0); PG8_BAR; PG8_MMA(1, 0, At, B0); PG8_MMA(1, 1, At, B1); PG8_BAR; PG8_SCHED;
.LBB0_1751:
	s_ashr_i32 s51, s50, 31
	s_lshl_b64 s[52:53], s[50:51], 19
	s_add_u32 s52, s10, s52
	s_addc_u32 s53, s11, s53
	s_and_b64 s[54:55], s[42:43], exec
	s_cselect_b32 s51, s53, s1
	s_cselect_b32 s69, s52, s0
	s_ashr_i32 s49, s48, 31
	s_lshl_b64 s[54:55], s[48:49], 19
	s_add_u32 s54, s9, s54
	s_addc_u32 s55, s16, s55
	s_and_b64 s[56:57], s[42:43], exec
	s_cselect_b32 s49, s55, s39
	s_cselect_b32 s70, s54, s38
	s_add_u32 s0, s0, 0x40080
	s_addc_u32 s1, s1, 0
	s_add_u32 s71, s38, 0x100
	s_addc_u32 s72, s39, 0
	s_mov_b32 s73, -2
	s_add_u32 s38, s0, 0xfffc0080
	s_addc_u32 s39, s1, -1
	s_add_i32 s74, 0, 0x10000
	s_cmp_eq_u32 s73, 12
	s_cselect_b32 s57, s51, s39
	s_cselect_b32 s56, s69, s38
	v_add_u32_e32 v151, s74, v147
	s_cselect_b32 s39, s49, s72
	s_cselect_b32 s38, s70, s71
	s_add_i32 s76, 0, 0x14000
	ds_read_b128 v[138:141], v151
	ds_read_b128 v[142:145], v151 offset:1024
	ds_read_b128 v[152:155], v151 offset:2048
	ds_read_b128 v[156:159], v151 offset:3072
	v_add_u32_e32 v151, s76, v147
	ds_read_b128 v[160:163], v151
	ds_read_b128 v[164:167], v151 offset:1024
	ds_read_b128 v[168:171], v151 offset:2048
	ds_read_b128 v[176:179], v151 offset:3072
	v_lshl_add_u64 v[172:173], s[0:1], 0, v[134:135]
	s_add_i32 m0, s58, 0xc000
	ds_read_b128 v[180:183], v150
	ds_read_b128 v[184:187], v150 offset:1024
	ds_read_b128 v[188:191], v150 offset:2048
	ds_read_b128 v[192:195], v150 offset:3072
	ds_read_b128 v[196:199], v150 offset:4096
	ds_read_b128 v[200:203], v150 offset:5120
	ds_read_b128 v[204:207], v150 offset:6144
	ds_read_b128 v[218:221], v150 offset:7168
	global_load_lds_dwordx4 v[172:173], off
	v_lshl_add_u64 v[172:173], s[0:1], 0, v[136:137]
	s_add_i32 m0, s58, 0xe000
	s_nop 0
	global_load_lds_dwordx4 v[172:173], off
	s_waitcnt vmcnt(8)
	s_waitcnt lgkmcnt(0)
	s_setprio 1
	s_barrier
	v_mfma_f32_16x16x32_bf16 v[124:127], v[138:141], v[180:183], 0
	v_mfma_f32_16x16x32_bf16 v[120:123], v[152:155], v[180:183], 0
	v_mfma_f32_16x16x32_bf16 v[108:111], v[138:141], v[188:191], 0
	v_mfma_f32_16x16x32_bf16 v[104:107], v[152:155], v[188:191], 0
	v_mfma_f32_16x16x32_bf16 v[92:95], v[138:141], v[196:199], 0
	v_mfma_f32_16x16x32_bf16 v[88:91], v[152:155], v[196:199], 0
	v_mfma_f32_16x16x32_bf16 v[76:79], v[138:141], v[204:207], 0
	v_mfma_f32_16x16x32_bf16 v[72:75], v[152:155], v[204:207], 0
	v_mfma_f32_16x16x32_bf16 v[124:127], v[142:145], v[184:187], v[124:127]
	v_mfma_f32_16x16x32_bf16 v[120:123], v[156:159], v[184:187], v[120:123]
	v_mfma_f32_16x16x32_bf16 v[108:111], v[142:145], v[192:195], v[108:111]
	v_mfma_f32_16x16x32_bf16 v[104:107], v[156:159], v[192:195], v[104:107]
	v_mfma_f32_16x16x32_bf16 v[92:95], v[142:145], v[200:203], v[92:95]
	v_mfma_f32_16x16x32_bf16 v[88:91], v[156:159], v[200:203], v[88:91]
	v_mfma_f32_16x16x32_bf16 v[76:79], v[142:145], v[218:221], v[76:79]
	v_mfma_f32_16x16x32_bf16 v[72:75], v[156:159], v[218:221], v[72:75]
	v_mfma_f32_16x16x32_bf16 v[116:119], v[160:163], v[180:183], 0
	v_mfma_f32_16x16x32_bf16 v[112:115], v[168:171], v[180:183], 0
	v_mfma_f32_16x16x32_bf16 v[100:103], v[160:163], v[188:191], 0
	v_mfma_f32_16x16x32_bf16 v[96:99], v[168:171], v[188:191], 0
	v_mfma_f32_16x16x32_bf16 v[84:87], v[160:163], v[196:199], 0
	v_mfma_f32_16x16x32_bf16 v[80:83], v[168:171], v[196:199], 0
	v_mfma_f32_16x16x32_bf16 v[68:71], v[160:163], v[204:207], 0
	v_mfma_f32_16x16x32_bf16 v[64:67], v[168:171], v[204:207], 0
	v_mfma_f32_16x16x32_bf16 v[116:119], v[164:167], v[184:187], v[116:119]
	v_mfma_f32_16x16x32_bf16 v[112:115], v[176:179], v[184:187], v[112:115]
	v_mfma_f32_16x16x32_bf16 v[100:103], v[164:167], v[192:195], v[100:103]
	v_mfma_f32_16x16x32_bf16 v[96:99], v[176:179], v[192:195], v[96:99]
	v_mfma_f32_16x16x32_bf16 v[84:87], v[164:167], v[200:203], v[84:87]
	v_mfma_f32_16x16x32_bf16 v[80:83], v[176:179], v[200:203], v[80:83]
	v_mfma_f32_16x16x32_bf16 v[68:71], v[164:167], v[218:221], v[68:71]
	v_mfma_f32_16x16x32_bf16 v[64:67], v[176:179], v[218:221], v[64:67]
	s_barrier
	s_setprio 0
	s_add_i32 s74, s74, s8
	v_lshl_add_u64 v[172:173], s[38:39], 0, v[174:175]
	s_mov_b32 m0, s74
	ds_read_b128 v[180:183], v150 offset:16384
	ds_read_b128 v[184:187], v150 offset:17408
	ds_read_b128 v[188:191], v150 offset:18432
	ds_read_b128 v[192:195], v150 offset:19456
	ds_read_b128 v[196:199], v150 offset:20480
	ds_read_b128 v[200:203], v150 offset:21504
	ds_read_b128 v[204:207], v150 offset:22528
	ds_read_b128 v[218:221], v150 offset:23552
	global_load_lds_dwordx4 v[172:173], off
	s_add_i32 m0, s74, 0x2000
	s_add_u32 s74, s38, 0x40000
	v_lshl_add_u64 v[208:209], s[38:39], 0, v[128:129]
	s_addc_u32 s75, s39, 0
	s_add_i32 s76, s76, s8
	global_load_lds_dwordx4 v[208:209], off
	v_lshl_add_u64 v[222:223], s[74:75], 0, v[174:175]
	s_mov_b32 m0, s76
	v_lshl_add_u64 v[224:225], s[56:57], 0, v[130:131]
	global_load_lds_dwordx4 v[222:223], off
	v_lshl_add_u64 v[222:223], s[74:75], 0, v[128:129]
	s_add_i32 m0, s76, 0x2000
	s_nop 0
	global_load_lds_dwordx4 v[222:223], off
	v_lshl_add_u64 v[222:223], s[56:57], 0, v[132:133]
	s_mov_b32 m0, s58
	s_nop 0
	global_load_lds_dwordx4 v[222:223], off
	s_mov_b32 m0, s59
	s_nop 0
	global_load_lds_dwordx4 v[224:225], off
	s_waitcnt vmcnt(8)
	s_waitcnt lgkmcnt(0)
	s_setprio 1
	s_barrier
; #define PG8_STAGE(bufoff, gbase, voff) do { _Pragma("unroll") for (int _i = 0; _i < 2; ++_i) \
;         __builtin_amdgcn_global_load_lds((const unsigned*)((const char*)(gbase) + (voff)[_i]), (PG8_LAS unsigned*)(lds + (bufoff) + ldsw + _i * 8192), 16, 0, 0); } while (0)
; #define PG8_LDA(dst, b, h) do { _Pragma("unroll") for (int m = 0; m < 4; ++m) _Pragma("unroll") for (int k = 0; k < 2; ++k) dst[m][k] = *(const PG8_LAS bf16x8*)(lds + PG8_SA(b, h) + aoff + m * 2048 + k * 1024); } while (0)
; #define PG8_LDB(dst, b, h) do { _Pragma("unroll") for (int n = 0; n < 2; ++n) _Pragma("unroll") for (int k = 0; k < 2; ++k) dst[n][k] = *(const PG8_LAS bf16x8*)(lds + PG8_SB(b, h) + boff + n * 2048 + k * 1024); } while (0)
; #define PG8_MMA(ai, bj, At, Bt) do { __builtin_amdgcn_s_setprio(1); _Pragma("unroll") for (int m = 0; m < 4; ++m) _Pragma("unroll") for (int n = 0; n < 2; ++n) _Pragma("unroll") for (int k = 0; k < 2; ++k) \
;         acc[ai][bj][m][n] = __builtin_amdgcn_mfma_f32_16x16x32_bf16(Bt[n][k], At[m][k], acc[ai][bj][m][n], 0, 0, 0); __builtin_amdgcn_s_setprio(0); } while (0)
; #define PG8_WAIT_V(n) asm volatile("s_waitcnt vmcnt(" #n ")" ::: "memory")
; #define PG8_WAIT_L(n) asm volatile("s_waitcnt lgkmcnt(" #n ")" ::: "memory")
; #define PG8_BAR __builtin_amdgcn_s_barrier()
; #define PG8_SCHED __builtin_amdgcn_sched_barrier(0)
; template <class Epi, class Sched, bool ALIGN_EPI = false, bool SP2 = false>
; __device__ __forceinline__ void gemm_phase(PG8_LAS unsigned char* lds, const Gemm g, const Sched& S, const Epi& E) {
;     ...
;             PG8_WAIT_V(8); PG8_WAIT_L(0); PG8_BAR; PG8_MMA(1, 0, At, B0); PG8_MMA(1, 1, At, B1); PG8_BAR; PG8_SCHED;
;             PG8_LDB(B0, 1, 0); PG8_LDB(B1, 1, 1); PG8_SCHED; PG8_LDA(At, 1, 0); PG8_STAGE(PG8_SA(0, 1), a2 + hstep, voffA);
;             PG8_WAIT_V(8); PG8_WAIT_L(0); PG8_BAR; PG8_MMA(0, 0, At, B0); PG8_MMA(0, 1, At, B1); PG8_BAR; PG8_SCHED;
	v_mfma_f32_16x16x32_bf16 v[60:63], v[138:141], v[180:183], 0
	v_mfma_f32_16x16x32_bf16 v[56:59], v[152:155], v[180:183], 0
	v_mfma_f32_16x16x32_bf16 v[44:47], v[138:141], v[188:191], 0
	v_mfma_f32_16x16x32_bf16 v[40:43], v[152:155], v[188:191], 0
	v_mfma_f32_16x16x32_bf16 v[28:31], v[138:141], v[196:199], 0
	v_mfma_f32_16x16x32_bf16 v[24:27], v[152:155], v[196:199], 0
	v_mfma_f32_16x16x32_bf16 v[12:15], v[138:141], v[204:207], 0
	v_mfma_f32_16x16x32_bf16 v[8:11], v[152:155], v[204:207], 0
	v_mfma_f32_16x16x32_bf16 v[60:63], v[142:145], v[184:187], v[60:63]
	v_mfma_f32_16x16x32_bf16 v[56:59], v[156:159], v[184:187], v[56:59]
	v_mfma_f32_16x16x32_bf16 v[44:47], v[142:145], v[192:195], v[44:47]
	v_mfma_f32_16x16x32_bf16 v[40:43], v[156:159], v[192:195], v[40:43]
	v_mfma_f32_16x16x32_bf16 v[28:31], v[142:145], v[200:203], v[28:31]
	v_mfma_f32_16x16x32_bf16 v[24:27], v[156:159], v[200:203], v[24:27]
	v_mfma_f32_16x16x32_bf16 v[12:15], v[142:145], v[218:221], v[12:15]
	v_mfma_f32_16x16x32_bf16 v[8:11], v[156:159], v[218:221], v[8:11]
	v_mfma_f32_16x16x32_bf16 v[52:55], v[160:163], v[180:183], 0
	v_mfma_f32_16x16x32_bf16 v[48:51], v[168:171], v[180:183], 0
	v_mfma_f32_16x16x32_bf16 v[36:39], v[160:163], v[188:191], 0
	v_mfma_f32_16x16x32_bf16 v[32:35], v[168:171], v[188:191], 0
	v_mfma_f32_16x16x32_bf16 v[20:23], v[160:163], v[196:199], 0
	v_mfma_f32_16x16x32_bf16 v[16:19], v[168:171], v[196:199], 0
	v_mfma_f32_16x16x32_bf16 v[4:7], v[160:163], v[204:207], 0
	v_mfma_f32_16x16x32_bf16 v[0:3], v[168:171], v[204:207], 0
	v_mfma_f32_16x16x32_bf16 v[52:55], v[164:167], v[184:187], v[52:55]
	v_mfma_f32_16x16x32_bf16 v[48:51], v[176:179], v[184:187], v[48:51]
	v_mfma_f32_16x16x32_bf16 v[36:39], v[164:167], v[192:195], v[36:39]
	v_mfma_f32_16x16x32_bf16 v[32:35], v[176:179], v[192:195], v[32:35]
	v_mfma_f32_16x16x32_bf16 v[20:23], v[164:167], v[200:203], v[20:23]
	v_mfma_f32_16x16x32_bf16 v[16:19], v[176:179], v[200:203], v[16:19]
	v_mfma_f32_16x16x32_bf16 v[4:7], v[164:167], v[218:221], v[4:7]
	v_mfma_f32_16x16x32_bf16 v[0:3], v[176:179], v[218:221], v[0:3]
	s_barrier
	s_setprio 0
	s_add_i32 s74, 0, 0x18000
	v_add_u32_e32 v151, s74, v147
	s_add_i32 s75, 0, 0x1c000
	ds_read_b128 v[138:141], v151
	ds_read_b128 v[142:145], v151 offset:1024
	ds_read_b128 v[152:155], v151 offset:2048
	ds_read_b128 v[156:159], v151 offset:3072
	v_add_u32_e32 v151, s75, v147
	ds_read_b128 v[160:163], v151
	ds_read_b128 v[164:167], v151 offset:1024
	ds_read_b128 v[168:171], v151 offset:2048
	ds_read_b128 v[176:179], v151 offset:3072
	s_add_u32 s56, s56, 0x40000
	s_addc_u32 s57, s57, 0
	s_mov_b32 m0, s60
	v_lshl_add_u64 v[226:227], s[56:57], 0, v[132:133]
	ds_read_b128 v[180:183], v150 offset:32768
	ds_read_b128 v[184:187], v150 offset:33792
	ds_read_b128 v[188:191], v150 offset:34816
	ds_read_b128 v[192:195], v150 offset:35840
	ds_read_b128 v[196:199], v150 offset:36864
	ds_read_b128 v[200:203], v150 offset:37888
	ds_read_b128 v[204:207], v150 offset:38912
	ds_read_b128 v[218:221], v150 offset:39936
	global_load_lds_dwordx4 v[226:227], off
	v_lshl_add_u64 v[226:227], s[56:57], 0, v[130:131]
	s_mov_b32 m0, s61
	s_nop 0
	global_load_lds_dwordx4 v[226:227], off
	s_waitcnt vmcnt(8)
	s_waitcnt lgkmcnt(0)
	s_setprio 1
	s_barrier
	v_mfma_f32_16x16x32_bf16 v[124:127], v[138:141], v[180:183], v[124:127]
	v_mfma_f32_16x16x32_bf16 v[120:123], v[152:155], v[180:183], v[120:123]
	v_mfma_f32_16x16x32_bf16 v[108:111], v[138:141], v[188:191], v[108:111]
	v_mfma_f32_16x16x32_bf16 v[104:107], v[152:155], v[188:191], v[104:107]
	v_mfma_f32_16x16x32_bf16 v[92:95], v[138:141], v[196:199], v[92:95]
	v_mfma_f32_16x16x32_bf16 v[88:91], v[152:155], v[196:199], v[88:91]
	v_mfma_f32_16x16x32_bf16 v[76:79], v[138:141], v[204:207], v[76:79]
	v_mfma_f32_16x16x32_bf16 v[72:75], v[152:155], v[204:207], v[72:75]
	v_mfma_f32_16x16x32_bf16 v[124:127], v[142:145], v[184:187], v[124:127]
	v_mfma_f32_16x16x32_bf16 v[120:123], v[156:159], v[184:187], v[120:123]
	v_mfma_f32_16x16x32_bf16 v[108:111], v[142:145], v[192:195], v[108:111]
	v_mfma_f32_16x16x32_bf16 v[104:107], v[156:159], v[192:195], v[104:107]
	v_mfma_f32_16x16x32_bf16 v[92:95], v[142:145], v[200:203], v[92:95]
	v_mfma_f32_16x16x32_bf16 v[88:91], v[156:159], v[200:203], v[88:91]
	v_mfma_f32_16x16x32_bf16 v[76:79], v[142:145], v[218:221], v[76:79]
	v_mfma_f32_16x16x32_bf16 v[72:75], v[156:159], v[218:221], v[72:75]
	v_mfma_f32_16x16x32_bf16 v[116:119], v[160:163], v[180:183], v[116:119]
	v_mfma_f32_16x16x32_bf16 v[112:115], v[168:171], v[180:183], v[112:115]
	v_mfma_f32_16x16x32_bf16 v[100:103], v[160:163], v[188:191], v[100:103]
	v_mfma_f32_16x16x32_bf16 v[96:99], v[168:171], v[188:191], v[96:99]
	v_mfma_f32_16x16x32_bf16 v[84:87], v[160:163], v[196:199], v[84:87]
	v_mfma_f32_16x16x32_bf16 v[80:83], v[168:171], v[196:199], v[80:83]
	v_mfma_f32_16x16x32_bf16 v[68:71], v[160:163], v[204:207], v[68:71]
	v_mfma_f32_16x16x32_bf16 v[64:67], v[168:171], v[204:207], v[64:67]
	v_mfma_f32_16x16x32_bf16 v[116:119], v[164:167], v[184:187], v[116:119]
	v_mfma_f32_16x16x32_bf16 v[112:115], v[176:179], v[184:187], v[112:115]
	v_mfma_f32_16x16x32_bf16 v[100:103], v[164:167], v[192:195], v[100:103]
	v_mfma_f32_16x16x32_bf16 v[96:99], v[176:179], v[192:195], v[96:99]
	v_mfma_f32_16x16x32_bf16 v[84:87], v[164:167], v[200:203], v[84:87]
	v_mfma_f32_16x16x32_bf16 v[80:83], v[176:179], v[200:203], v[80:83]
	v_mfma_f32_16x16x32_bf16 v[68:71], v[164:167], v[218:221], v[68:71]
	v_mfma_f32_16x16x32_bf16 v[64:67], v[176:179], v[218:221], v[64:67]
	s_barrier
; #define PG8_STAGE(bufoff, gbase, voff) do { _Pragma("unroll") for (int _i = 0; _i < 2; ++_i) \
;         __builtin_amdgcn_global_load_lds((const unsigned*)((const char*)(gbase) + (voff)[_i]), (PG8_LAS unsigned*)(lds + (bufoff) + ldsw + _i * 8192), 16, 0, 0); } while (0)
; #define PG8_LDA(dst, b, h) do { _Pragma("unroll") for (int m = 0; m < 4; ++m) _Pragma("unroll") for (int k = 0; k < 2; ++k) dst[m][k] = *(const PG8_LAS bf16x8*)(lds + PG8_SA(b, h) + aoff + m * 2048 + k * 1024); } while (0)
; #define PG8_LDB(dst, b, h) do { _Pragma("unroll") for (int n = 0; n < 2; ++n) _Pragma("unroll") for (int k = 0; k < 2; ++k) dst[n][k] = *(const PG8_LAS bf16x8*)(lds + PG8_SB(b, h) + boff + n * 2048 + k * 1024); } while (0)
; #define PG8_MMA(ai, bj, At, Bt) do { __builtin_amdgcn_s_setprio(1); _Pragma("unroll") for (int m = 0; m < 4; ++m) _Pragma("unroll") for (int n = 0; n < 2; ++n) _Pragma("unroll") for (int k = 0; k < 2; ++k) \
;         acc[ai][bj][m][n] = __builtin_amdgcn_mfma_f32_16x16x32_bf16(Bt[n][k], At[m][k], acc[ai][bj][m][n], 0, 0, 0); __builtin_amdgcn_s_setprio(0); } while (0)
; template <class Epi, class Sched, bool ALIGN_EPI = false, bool SP2 = false>
; __device__ __forceinline__ void gemm_phase(PG8_LAS unsigned char* lds, const Gemm g, const Sched& S, const Epi& E) {
;     ...
;         for (int t = 0; t < nt; t += 2) {
;             const bool last = (t == nt - 2);
;             const char* a1 = cA + (size_t)(t + 1) * kstep;
;             const char* a2 = last ? nA : cA + (size_t)(t + 2) * kstep; const char* b2 = last ? nB : cB + (size_t)(t + 2) * kstep;
;             const char* a3 = a2 + kstep; const char* b3 = b2 + kstep;
;             if (last && has_next) S.a_ready(nxt);
;             if constexpr (SP2) {
;             PG8_LDB(B0, 0, 0); PG8_LDB(B1, 0, 1); PG8_SCHED; PG8_LDA(At, 0, 0); PG8_STAGE(PG8_SA(1, 1), a1 + hstep, voffA);
;             PG8_WAIT_V(8); PG8_WAIT_L(0); PG8_BAR; PG8_MMA(0, 0, At, B0); PG8_MMA(0, 1, At, B1); PG8_BAR; PG8_SCHED;
;             PG8_LDA(At, 0, 1); PG8_STAGE(PG8_SB(0, 0), b2, voffB); PG8_STAGE(PG8_SB(0, 1), b2 + hstep, voffB); PG8_STAGE(PG8_SA(0, 0), a2, voffA);
;     ...
;             PG8_LDA(At, 1, 1); PG8_STAGE(PG8_SB(1, 0), b3, voffB); PG8_STAGE(PG8_SB(1, 1), b3 + hstep, voffB); PG8_STAGE(PG8_SA(1, 0), a3, voffA);
;             PG8_WAIT_V(8); PG8_WAIT_L(0); PG8_BAR; PG8_MMA(1, 0, At, B0); PG8_MMA(1, 1, At, B1); PG8_BAR; PG8_SCHED;
	s_setprio 0
	s_add_i32 s56, s74, s8
	v_lshl_add_u64 v[172:173], v[172:173], 0, s[4:5]
	s_mov_b32 m0, s56
	ds_read_b128 v[180:183], v150 offset:49152
	ds_read_b128 v[184:187], v150 offset:50176
	ds_read_b128 v[188:191], v150 offset:51200
	ds_read_b128 v[192:195], v150 offset:52224
	ds_read_b128 v[196:199], v150 offset:53248
	ds_read_b128 v[200:203], v150 offset:54272
	ds_read_b128 v[204:207], v150 offset:55296
	ds_read_b128 v[218:221], v150 offset:56320
	global_load_lds_dwordx4 v[172:173], off
	s_add_i32 m0, s56, 0x2000
	s_add_u32 s38, s38, 0x40080
	v_lshl_add_u64 v[172:173], v[208:209], 0, s[4:5]
	s_addc_u32 s39, s39, 0
	s_add_i32 s56, s75, s8
	global_load_lds_dwordx4 v[172:173], off
	v_lshl_add_u64 v[172:173], s[38:39], 0, v[174:175]
	s_mov_b32 m0, s56
	s_nop 0
	global_load_lds_dwordx4 v[172:173], off
	v_lshl_add_u64 v[172:173], s[38:39], 0, v[128:129]
	s_add_i32 m0, s56, 0x2000
	s_nop 0
	global_load_lds_dwordx4 v[172:173], off
	v_lshl_add_u64 v[172:173], v[222:223], 0, s[4:5]
	s_mov_b32 m0, s62
	s_nop 0
	global_load_lds_dwordx4 v[172:173], off
	v_lshl_add_u64 v[172:173], v[224:225], 0, s[4:5]
	s_mov_b32 m0, s63
	s_nop 0
	global_load_lds_dwordx4 v[172:173], off
	s_waitcnt vmcnt(8)
	s_waitcnt lgkmcnt(0)
	s_setprio 1
	s_barrier
	v_mfma_f32_16x16x32_bf16 v[60:63], v[138:141], v[180:183], v[60:63]
	v_mfma_f32_16x16x32_bf16 v[56:59], v[152:155], v[180:183], v[56:59]
	v_mfma_f32_16x16x32_bf16 v[44:47], v[138:141], v[188:191], v[44:47]
	v_mfma_f32_16x16x32_bf16 v[40:43], v[152:155], v[188:191], v[40:43]
	v_mfma_f32_16x16x32_bf16 v[28:31], v[138:141], v[196:199], v[28:31]
	v_mfma_f32_16x16x32_bf16 v[24:27], v[152:155], v[196:199], v[24:27]
	v_mfma_f32_16x16x32_bf16 v[12:15], v[138:141], v[204:207], v[12:15]
	v_mfma_f32_16x16x32_bf16 v[8:11], v[152:155], v[204:207], v[8:11]
	v_mfma_f32_16x16x32_bf16 v[60:63], v[142:145], v[184:187], v[60:63]
	v_mfma_f32_16x16x32_bf16 v[56:59], v[156:159], v[184:187], v[56:59]
	v_mfma_f32_16x16x32_bf16 v[44:47], v[142:145], v[192:195], v[44:47]
	v_mfma_f32_16x16x32_bf16 v[40:43], v[156:159], v[192:195], v[40:43]
	v_mfma_f32_16x16x32_bf16 v[28:31], v[142:145], v[200:203], v[28:31]
	v_mfma_f32_16x16x32_bf16 v[24:27], v[156:159], v[200:203], v[24:27]
	v_mfma_f32_16x16x32_bf16 v[12:15], v[142:145], v[218:221], v[12:15]
	v_mfma_f32_16x16x32_bf16 v[8:11], v[156:159], v[218:221], v[8:11]
	v_mfma_f32_16x16x32_bf16 v[52:55], v[160:163], v[180:183], v[52:55]
	v_mfma_f32_16x16x32_bf16 v[48:51], v[168:171], v[180:183], v[48:51]
	v_mfma_f32_16x16x32_bf16 v[36:39], v[160:163], v[188:191], v[36:39]
	v_mfma_f32_16x16x32_bf16 v[32:35], v[168:171], v[188:191], v[32:35]
	v_mfma_f32_16x16x32_bf16 v[20:23], v[160:163], v[196:199], v[20:23]
	v_mfma_f32_16x16x32_bf16 v[16:19], v[168:171], v[196:199], v[16:19]
	v_mfma_f32_16x16x32_bf16 v[4:7], v[160:163], v[204:207], v[4:7]
	v_mfma_f32_16x16x32_bf16 v[0:3], v[168:171], v[204:207], v[0:3]
	v_mfma_f32_16x16x32_bf16 v[52:55], v[164:167], v[184:187], v[52:55]
	v_mfma_f32_16x16x32_bf16 v[48:51], v[176:179], v[184:187], v[48:51]
	v_mfma_f32_16x16x32_bf16 v[36:39], v[164:167], v[192:195], v[36:39]
	v_mfma_f32_16x16x32_bf16 v[32:35], v[176:179], v[192:195], v[32:35]
	v_mfma_f32_16x16x32_bf16 v[20:23], v[164:167], v[200:203], v[20:23]
	v_mfma_f32_16x16x32_bf16 v[16:19], v[176:179], v[200:203], v[16:19]
	v_mfma_f32_16x16x32_bf16 v[4:7], v[164:167], v[218:221], v[4:7]
	v_mfma_f32_16x16x32_bf16 v[0:3], v[176:179], v[218:221], v[0:3]
	s_barrier
	s_setprio 0
	s_add_i32 s73, s73, 2
	s_add_u32 s0, s0, 0x100
	s_addc_u32 s1, s1, 0
	s_add_u32 s71, s71, 0x100
	s_addc_u32 s72, s72, 0
	s_cmp_gt_u32 s73, 13
	s_cbranch_scc0 .LBB0_1752
.LBB0_1752:
	s_add_u32 s38, s0, 0xfffc0080
	s_addc_u32 s39, s1, -1
	s_add_i32 s74, 0, 0x10000
	s_cmp_eq_u32 s73, 12
	s_cselect_b32 s57, s51, s39
	s_cselect_b32 s56, s69, s38
	v_add_u32_e32 v151, s74, v147
	s_cselect_b32 s39, s49, s72
	s_cselect_b32 s38, s70, s71
	s_add_i32 s76, 0, 0x14000
	ds_read_b128 v[138:141], v151
	ds_read_b128 v[142:145], v151 offset:1024
	ds_read_b128 v[152:155], v151 offset:2048
	ds_read_b128 v[156:159], v151 offset:3072
	v_add_u32_e32 v151, s76, v147
	ds_read_b128 v[160:163], v151
	ds_read_b128 v[164:167], v151 offset:1024
	ds_read_b128 v[168:171], v151 offset:2048
	ds_read_b128 v[176:179], v151 offset:3072
	v_lshl_add_u64 v[172:173], s[0:1], 0, v[134:135]
	s_add_i32 m0, s58, 0xc000
	ds_read_b128 v[180:183], v150
	ds_read_b128 v[184:187], v150 offset:1024
	ds_read_b128 v[188:191], v150 offset:2048
	ds_read_b128 v[192:195], v150 offset:3072
	ds_read_b128 v[196:199], v150 offset:4096
	ds_read_b128 v[200:203], v150 offset:5120
	ds_read_b128 v[204:207], v150 offset:6144
	ds_read_b128 v[218:221], v150 offset:7168
	global_load_lds_dwordx4 v[172:173], off
	v_lshl_add_u64 v[172:173], s[0:1], 0, v[136:137]
	s_add_i32 m0, s58, 0xe000
	s_nop 0
	global_load_lds_dwordx4 v[172:173], off
	s_waitcnt vmcnt(8)
	s_waitcnt lgkmcnt(0)
	s_setprio 1
	s_barrier
; #define PG8_STAGE(bufoff, gbase, voff) do { _Pragma("unroll") for (int _i = 0; _i < 2; ++_i) \
;         __builtin_amdgcn_global_load_lds((const unsigned*)((const char*)(gbase) + (voff)[_i]), (PG8_LAS unsigned*)(lds + (bufoff) + ldsw + _i * 8192), 16, 0, 0); } while (0)
; #define PG8_LDA(dst, b, h) do { _Pragma("unroll") for (int m = 0; m < 4; ++m) _Pragma("unroll") for (int k = 0; k < 2; ++k) dst[m][k] = *(const PG8_LAS bf16x8*)(lds + PG8_SA(b, h) + aoff + m * 2048 + k * 1024); } while (0)
; #define PG8_MMA(ai, bj, At, Bt) do { __builtin_amdgcn_s_setprio(1); _Pragma("unroll") for (int m = 0; m < 4; ++m) _Pragma("unroll") for (int n = 0; n < 2; ++n) _Pragma("unroll") for (int k = 0; k < 2; ++k) \
;         acc[ai][bj][m][n] = __builtin_amdgcn_mfma_f32_16x16x32_bf16(Bt[n][k], At[m][k], acc[ai][bj][m][n], 0, 0, 0); __builtin_amdgcn_s_setprio(0); } while (0)
; #define PG8_WAIT_V(n) asm volatile("s_waitcnt vmcnt(" #n ")" ::: "memory")
; #define PG8_WAIT_L(n) asm volatile("s_waitcnt lgkmcnt(" #n ")" ::: "memory")
; #define PG8_BAR __builtin_amdgcn_s_barrier()
; #define PG8_SCHED __builtin_amdgcn_sched_barrier(0)
; template <class Epi, class Sched, bool ALIGN_EPI = false, bool SP2 = false>
; __device__ __forceinline__ void gemm_phase(PG8_LAS unsigned char* lds, const Gemm g, const Sched& S, const Epi& E) {
;     ...
;             PG8_WAIT_V(8); PG8_WAIT_L(0); PG8_BAR; PG8_MMA(0, 0, At, B0); PG8_MMA(0, 1, At, B1); PG8_BAR; PG8_SCHED;
;             PG8_LDA(At, 0, 1); PG8_STAGE(PG8_SB(0, 0), b2, voffB); PG8_STAGE(PG8_SB(0, 1), b2 + hstep, voffB); PG8_STAGE(PG8_SA(0, 0), a2, voffA);
;             PG8_WAIT_V(8); PG8_WAIT_L(0); PG8_BAR; PG8_MMA(1, 0, At, B0); PG8_MMA(1, 1, At, B1); PG8_BAR; PG8_SCHED;
	v_mfma_f32_16x16x32_bf16 v[124:127], v[138:141], v[180:183], v[124:127]
	v_mfma_f32_16x16x32_bf16 v[120:123], v[152:155], v[180:183], v[120:123]
	v_mfma_f32_16x16x32_bf16 v[108:111], v[138:141], v[188:191], v[108:111]
	v_mfma_f32_16x16x32_bf16 v[104:107], v[152:155], v[188:191], v[104:107]
	v_mfma_f32_16x16x32_bf16 v[92:95], v[138:141], v[196:199], v[92:95]
	v_mfma_f32_16x16x32_bf16 v[88:91], v[152:155], v[196:199], v[88:91]
	v_mfma_f32_16x16x32_bf16 v[76:79], v[138:141], v[204:207], v[76:79]
	v_mfma_f32_16x16x32_bf16 v[72:75], v[152:155], v[204:207], v[72:75]
	v_mfma_f32_16x16x32_bf16 v[124:127], v[142:145], v[184:187], v[124:127]
	v_mfma_f32_16x16x32_bf16 v[120:123], v[156:159], v[184:187], v[120:123]
	v_mfma_f32_16x16x32_bf16 v[108:111], v[142:145], v[192:195], v[108:111]
	v_mfma_f32_16x16x32_bf16 v[104:107], v[156:159], v[192:195], v[104:107]
	v_mfma_f32_16x16x32_bf16 v[92:95], v[142:145], v[200:203], v[92:95]
	v_mfma_f32_16x16x32_bf16 v[88:91], v[156:159], v[200:203], v[88:91]
	v_mfma_f32_16x16x32_bf16 v[76:79], v[142:145], v[218:221], v[76:79]
	v_mfma_f32_16x16x32_bf16 v[72:75], v[156:159], v[218:221], v[72:75]
	v_mfma_f32_16x16x32_bf16 v[116:119], v[160:163], v[180:183], v[116:119]
	v_mfma_f32_16x16x32_bf16 v[112:115], v[168:171], v[180:183], v[112:115]
	v_mfma_f32_16x16x32_bf16 v[100:103], v[160:163], v[188:191], v[100:103]
	v_mfma_f32_16x16x32_bf16 v[96:99], v[168:171], v[188:191], v[96:99]
	v_mfma_f32_16x16x32_bf16 v[84:87], v[160:163], v[196:199], v[84:87]
	v_mfma_f32_16x16x32_bf16 v[80:83], v[168:171], v[196:199], v[80:83]
	v_mfma_f32_16x16x32_bf16 v[68:71], v[160:163], v[204:207], v[68:71]
	v_mfma_f32_16x16x32_bf16 v[64:67], v[168:171], v[204:207], v[64:67]
	v_mfma_f32_16x16x32_bf16 v[116:119], v[164:167], v[184:187], v[116:119]
	v_mfma_f32_16x16x32_bf16 v[112:115], v[176:179], v[184:187], v[112:115]
	v_mfma_f32_16x16x32_bf16 v[100:103], v[164:167], v[192:195], v[100:103]
	v_mfma_f32_16x16x32_bf16 v[96:99], v[176:179], v[192:195], v[96:99]
	v_mfma_f32_16x16x32_bf16 v[84:87], v[164:167], v[200:203], v[84:87]
	v_mfma_f32_16x16x32_bf16 v[80:83], v[176:179], v[200:203], v[80:83]
	v_mfma_f32_16x16x32_bf16 v[68:71], v[164:167], v[218:221], v[68:71]
	v_mfma_f32_16x16x32_bf16 v[64:67], v[176:179], v[218:221], v[64:67]
	s_barrier
	s_setprio 0
	s_add_i32 s74, s74, s8
	v_lshl_add_u64 v[172:173], s[38:39], 0, v[174:175]
	s_mov_b32 m0, s74
	ds_read_b128 v[180:183], v150 offset:16384
	ds_read_b128 v[184:187], v150 offset:17408
	ds_read_b128 v[188:191], v150 offset:18432
	ds_read_b128 v[192:195], v150 offset:19456
	ds_read_b128 v[196:199], v150 offset:20480
	ds_read_b128 v[200:203], v150 offset:21504
	ds_read_b128 v[204:207], v150 offset:22528
	ds_read_b128 v[218:221], v150 offset:23552
	global_load_lds_dwordx4 v[172:173], off
	s_add_i32 m0, s74, 0x2000
	s_add_u32 s74, s38, 0x40000
	v_lshl_add_u64 v[208:209], s[38:39], 0, v[128:129]
	s_addc_u32 s75, s39, 0
	s_add_i32 s76, s76, s8
	global_load_lds_dwordx4 v[208:209], off
	v_lshl_add_u64 v[222:223], s[74:75], 0, v[174:175]
	s_mov_b32 m0, s76
	v_lshl_add_u64 v[224:225], s[56:57], 0, v[130:131]
	global_load_lds_dwordx4 v[222:223], off
	v_lshl_add_u64 v[222:223], s[74:75], 0, v[128:129]
	s_add_i32 m0, s76, 0x2000
	s_nop 0
	global_load_lds_dwordx4 v[222:223], off
	v_lshl_add_u64 v[222:223], s[56:57], 0, v[132:133]
	s_mov_b32 m0, s58
	s_nop 0
	global_load_lds_dwordx4 v[222:223], off
	s_mov_b32 m0, s59
	s_nop 0
	global_load_lds_dwordx4 v[224:225], off
	s_waitcnt vmcnt(8)
	s_waitcnt lgkmcnt(0)
	s_setprio 1
	s_barrier
	v_mfma_f32_16x16x32_bf16 v[60:63], v[138:141], v[180:183], v[60:63]
	v_mfma_f32_16x16x32_bf16 v[56:59], v[152:155], v[180:183], v[56:59]
	v_mfma_f32_16x16x32_bf16 v[44:47], v[138:141], v[188:191], v[44:47]
	v_mfma_f32_16x16x32_bf16 v[40:43], v[152:155], v[188:191], v[40:43]
	v_mfma_f32_16x16x32_bf16 v[28:31], v[138:141], v[196:199], v[28:31]
	v_mfma_f32_16x16x32_bf16 v[24:27], v[152:155], v[196:199], v[24:27]
	v_mfma_f32_16x16x32_bf16 v[12:15], v[138:141], v[204:207], v[12:15]
	v_mfma_f32_16x16x32_bf16 v[8:11], v[152:155], v[204:207], v[8:11]
	v_mfma_f32_16x16x32_bf16 v[60:63], v[142:145], v[184:187], v[60:63]
	v_mfma_f32_16x16x32_bf16 v[56:59], v[156:159], v[184:187], v[56:59]
	v_mfma_f32_16x16x32_bf16 v[44:47], v[142:145], v[192:195], v[44:47]
	v_mfma_f32_16x16x32_bf16 v[40:43], v[156:159], v[192:195], v[40:43]
	v_mfma_f32_16x16x32_bf16 v[28:31], v[142:145], v[200:203], v[28:31]
	v_mfma_f32_16x16x32_bf16 v[24:27], v[156:159], v[200:203], v[24:27]
	v_mfma_f32_16x16x32_bf16 v[12:15], v[142:145], v[218:221], v[12:15]
	v_mfma_f32_16x16x32_bf16 v[8:11], v[156:159], v[218:221], v[8:11]
	v_mfma_f32_16x16x32_bf16 v[52:55], v[160:163], v[180:183], v[52:55]
	v_mfma_f32_16x16x32_bf16 v[48:51], v[168:171], v[180:183], v[48:51]
	v_mfma_f32_16x16x32_bf16 v[36:39], v[160:163], v[188:191], v[36:39]
	v_mfma_f32_16x16x32_bf16 v[32:35], v[168:171], v[188:191], v[32:35]
	v_mfma_f32_16x16x32_bf16 v[20:23], v[160:163], v[196:199], v[20:23]
	v_mfma_f32_16x16x32_bf16 v[16:19], v[168:171], v[196:199], v[16:19]
	v_mfma_f32_16x16x32_bf16 v[4:7], v[160:163], v[204:207], v[4:7]
	v_mfma_f32_16x16x32_bf16 v[0:3], v[168:171], v[204:207], v[0:3]
	v_mfma_f32_16x16x32_bf16 v[52:55], v[164:167], v[184:187], v[52:55]
	v_mfma_f32_16x16x32_bf16 v[48:51], v[176:179], v[184:187], v[48:51]
	v_mfma_f32_16x16x32_bf16 v[36:39], v[164:167], v[192:195], v[36:39]
	v_mfma_f32_16x16x32_bf16 v[32:35], v[176:179], v[192:195], v[32:35]
	v_mfma_f32_16x16x32_bf16 v[20:23], v[164:167], v[200:203], v[20:23]
	v_mfma_f32_16x16x32_bf16 v[16:19], v[176:179], v[200:203], v[16:19]
	v_mfma_f32_16x16x32_bf16 v[4:7], v[164:167], v[218:221], v[4:7]
	v_mfma_f32_16x16x32_bf16 v[0:3], v[176:179], v[218:221], v[0:3]
	s_barrier
; #define PG8_STAGE(bufoff, gbase, voff) do { _Pragma("unroll") for (int _i = 0; _i < 2; ++_i) \
;         __builtin_amdgcn_global_load_lds((const unsigned*)((const char*)(gbase) + (voff)[_i]), (PG8_LAS unsigned*)(lds + (bufoff) + ldsw + _i * 8192), 16, 0, 0); } while (0)
; #define PG8_LDA(dst, b, h) do { _Pragma("unroll") for (int m = 0; m < 4; ++m) _Pragma("unroll") for (int k = 0; k < 2; ++k) dst[m][k] = *(const PG8_LAS bf16x8*)(lds + PG8_SA(b, h) + aoff + m * 2048 + k * 1024); } while (0)
; #define PG8_LDB(dst, b, h) do { _Pragma("unroll") for (int n = 0; n < 2; ++n) _Pragma("unroll") for (int k = 0; k < 2; ++k) dst[n][k] = *(const PG8_LAS bf16x8*)(lds + PG8_SB(b, h) + boff + n * 2048 + k * 1024); } while (0)
; #define PG8_MMA(ai, bj, At, Bt) do { __builtin_amdgcn_s_setprio(1); _Pragma("unroll") for (int m = 0; m < 4; ++m) _Pragma("unroll") for (int n = 0; n < 2; ++n) _Pragma("unroll") for (int k = 0; k < 2; ++k) \
;         acc[ai][bj][m][n] = __builtin_amdgcn_mfma_f32_16x16x32_bf16(Bt[n][k], At[m][k], acc[ai][bj][m][n], 0, 0, 0); __builtin_amdgcn_s_setprio(0); } while (0)
; #define PG8_WAIT_V(n) asm volatile("s_waitcnt vmcnt(" #n ")" ::: "memory")
; #define PG8_WAIT_L(n) asm volatile("s_waitcnt lgkmcnt(" #n ")" ::: "memory")
; #define PG8_BAR __builtin_amdgcn_s_barrier()
; #define PG8_SCHED __builtin_amdgcn_sched_barrier(0)
; template <class Epi, class Sched, bool ALIGN_EPI = false, bool SP2 = false>
; __device__ __forceinline__ void gemm_phase(PG8_LAS unsigned char* lds, const Gemm g, const Sched& S, const Epi& E) {
;     ...
;             PG8_LDB(B0, 1, 0); PG8_LDB(B1, 1, 1); PG8_SCHED; PG8_LDA(At, 1, 0); PG8_STAGE(PG8_SA(0, 1), a2 + hstep, voffA);
;             PG8_WAIT_V(8); PG8_WAIT_L(0); PG8_BAR; PG8_MMA(0, 0, At, B0); PG8_MMA(0, 1, At, B1); PG8_BAR; PG8_SCHED;
	s_setprio 0
	s_add_i32 s74, 0, 0x18000
	v_add_u32_e32 v151, s74, v147
	s_add_i32 s75, 0, 0x1c000
	ds_read_b128 v[138:141], v151
	ds_read_b128 v[142:145], v151 offset:1024
	ds_read_b128 v[152:155], v151 offset:2048
	ds_read_b128 v[156:159], v151 offset:3072
	v_add_u32_e32 v151, s75, v147
	ds_read_b128 v[160:163], v151
	ds_read_b128 v[164:167], v151 offset:1024
	ds_read_b128 v[168:171], v151 offset:2048
	ds_read_b128 v[176:179], v151 offset:3072
	s_add_u32 s56, s56, 0x40000
	s_addc_u32 s57, s57, 0
	s_mov_b32 m0, s60
	v_lshl_add_u64 v[226:227], s[56:57], 0, v[132:133]
	ds_read_b128 v[180:183], v150 offset:32768
	ds_read_b128 v[184:187], v150 offset:33792
	ds_read_b128 v[188:191], v150 offset:34816
	ds_read_b128 v[192:195], v150 offset:35840
	ds_read_b128 v[196:199], v150 offset:36864
	ds_read_b128 v[200:203], v150 offset:37888
	ds_read_b128 v[204:207], v150 offset:38912
	ds_read_b128 v[218:221], v150 offset:39936
	global_load_lds_dwordx4 v[226:227], off
	v_lshl_add_u64 v[226:227], s[56:57], 0, v[130:131]
	s_mov_b32 m0, s61
	s_nop 0
	global_load_lds_dwordx4 v[226:227], off
	s_waitcnt vmcnt(8)
	s_waitcnt lgkmcnt(0)
	s_setprio 1
	s_barrier
	v_mfma_f32_16x16x32_bf16 v[124:127], v[138:141], v[180:183], v[124:127]
	v_mfma_f32_16x16x32_bf16 v[120:123], v[152:155], v[180:183], v[120:123]
	v_mfma_f32_16x16x32_bf16 v[108:111], v[138:141], v[188:191], v[108:111]
	v_mfma_f32_16x16x32_bf16 v[104:107], v[152:155], v[188:191], v[104:107]
	v_mfma_f32_16x16x32_bf16 v[92:95], v[138:141], v[196:199], v[92:95]
	v_mfma_f32_16x16x32_bf16 v[88:91], v[152:155], v[196:199], v[88:91]
	v_mfma_f32_16x16x32_bf16 v[76:79], v[138:141], v[204:207], v[76:79]
	v_mfma_f32_16x16x32_bf16 v[72:75], v[152:155], v[204:207], v[72:75]
	v_mfma_f32_16x16x32_bf16 v[124:127], v[142:145], v[184:187], v[124:127]
	v_mfma_f32_16x16x32_bf16 v[120:123], v[156:159], v[184:187], v[120:123]
	v_mfma_f32_16x16x32_bf16 v[108:111], v[142:145], v[192:195], v[108:111]
	v_mfma_f32_16x16x32_bf16 v[104:107], v[156:159], v[192:195], v[104:107]
	v_mfma_f32_16x16x32_bf16 v[92:95], v[142:145], v[200:203], v[92:95]
	v_mfma_f32_16x16x32_bf16 v[88:91], v[156:159], v[200:203], v[88:91]
	v_mfma_f32_16x16x32_bf16 v[76:79], v[142:145], v[218:221], v[76:79]
	v_mfma_f32_16x16x32_bf16 v[72:75], v[156:159], v[218:221], v[72:75]
	v_mfma_f32_16x16x32_bf16 v[116:119], v[160:163], v[180:183], v[116:119]
	v_mfma_f32_16x16x32_bf16 v[112:115], v[168:171], v[180:183], v[112:115]
	v_mfma_f32_16x16x32_bf16 v[100:103], v[160:163], v[188:191], v[100:103]
	v_mfma_f32_16x16x32_bf16 v[96:99], v[168:171], v[188:191], v[96:99]
	v_mfma_f32_16x16x32_bf16 v[84:87], v[160:163], v[196:199], v[84:87]
	v_mfma_f32_16x16x32_bf16 v[80:83], v[168:171], v[196:199], v[80:83]
	v_mfma_f32_16x16x32_bf16 v[68:71], v[160:163], v[204:207], v[68:71]
	v_mfma_f32_16x16x32_bf16 v[64:67], v[168:171], v[204:207], v[64:67]
	v_mfma_f32_16x16x32_bf16 v[116:119], v[164:167], v[184:187], v[116:119]
	v_mfma_f32_16x16x32_bf16 v[112:115], v[176:179], v[184:187], v[112:115]
	v_mfma_f32_16x16x32_bf16 v[100:103], v[164:167], v[192:195], v[100:103]
	v_mfma_f32_16x16x32_bf16 v[96:99], v[176:179], v[192:195], v[96:99]
	v_mfma_f32_16x16x32_bf16 v[84:87], v[164:167], v[200:203], v[84:87]
	v_mfma_f32_16x16x32_bf16 v[80:83], v[176:179], v[200:203], v[80:83]
	v_mfma_f32_16x16x32_bf16 v[68:71], v[164:167], v[218:221], v[68:71]
	v_mfma_f32_16x16x32_bf16 v[64:67], v[176:179], v[218:221], v[64:67]
	s_barrier
; #define PG8_STAGE(bufoff, gbase, voff) do { _Pragma("unroll") for (int _i = 0; _i < 2; ++_i) \
;         __builtin_amdgcn_global_load_lds((const unsigned*)((const char*)(gbase) + (voff)[_i]), (PG8_LAS unsigned*)(lds + (bufoff) + ldsw + _i * 8192), 16, 0, 0); } while (0)
; #define PG8_LDA(dst, b, h) do { _Pragma("unroll") for (int m = 0; m < 4; ++m) _Pragma("unroll") for (int k = 0; k < 2; ++k) dst[m][k] = *(const PG8_LAS bf16x8*)(lds + PG8_SA(b, h) + aoff + m * 2048 + k * 1024); } while (0)
; #define PG8_MMA(ai, bj, At, Bt) do { __builtin_amdgcn_s_setprio(1); _Pragma("unroll") for (int m = 0; m < 4; ++m) _Pragma("unroll") for (int n = 0; n < 2; ++n) _Pragma("unroll") for (int k = 0; k < 2; ++k) \
;         acc[ai][bj][m][n] = __builtin_amdgcn_mfma_f32_16x16x32_bf16(Bt[n][k], At[m][k], acc[ai][bj][m][n], 0, 0, 0); __builtin_amdgcn_s_setprio(0); } while (0)
; #define PG8_WAIT_V(n) asm volatile("s_waitcnt vmcnt(" #n ")" ::: "memory")
; #define PG8_WAIT_L(n) asm volatile("s_waitcnt lgkmcnt(" #n ")" ::: "memory")
; #define PG8_BAR __builtin_amdgcn_s_barrier()
; #define PG8_SCHED __builtin_amdgcn_sched_barrier(0)
; template <class Epi, class Sched, bool ALIGN_EPI = false, bool SP2 = false>
; __device__ __forceinline__ void gemm_phase(PG8_LAS unsigned char* lds, const Gemm g, const Sched& S, const Epi& E) {
;     ...
;             PG8_LDA(At, 1, 1); PG8_STAGE(PG8_SB(1, 0), b3, voffB); PG8_STAGE(PG8_SB(1, 1), b3 + hstep, voffB); PG8_STAGE(PG8_SA(1, 0), a3, voffA);
;             PG8_WAIT_V(8); PG8_WAIT_L(0); PG8_BAR; PG8_MMA(1, 0, At, B0); PG8_MMA(1, 1, At, B1); PG8_BAR; PG8_SCHED;
;     ...
;         if constexpr (ALIGN_EPI) { if (wr == 0) PG8_BAR; }
	s_setprio 0
	s_add_i32 s56, s74, s8
	v_lshl_add_u64 v[172:173], v[172:173], 0, s[4:5]
	s_mov_b32 m0, s56
	ds_read_b128 v[180:183], v150 offset:49152
	ds_read_b128 v[184:187], v150 offset:50176
	ds_read_b128 v[188:191], v150 offset:51200
	ds_read_b128 v[192:195], v150 offset:52224
	ds_read_b128 v[196:199], v150 offset:53248
	ds_read_b128 v[200:203], v150 offset:54272
	ds_read_b128 v[204:207], v150 offset:55296
	ds_read_b128 v[218:221], v150 offset:56320
	global_load_lds_dwordx4 v[172:173], off
	s_add_i32 m0, s56, 0x2000
	s_add_u32 s38, s38, 0x40080
	v_lshl_add_u64 v[172:173], v[208:209], 0, s[4:5]
	s_addc_u32 s39, s39, 0
	s_add_i32 s56, s75, s8
	global_load_lds_dwordx4 v[172:173], off
	v_lshl_add_u64 v[172:173], s[38:39], 0, v[174:175]
	s_mov_b32 m0, s56
	s_nop 0
	global_load_lds_dwordx4 v[172:173], off
	v_lshl_add_u64 v[172:173], s[38:39], 0, v[128:129]
	s_add_i32 m0, s56, 0x2000
	s_nop 0
	global_load_lds_dwordx4 v[172:173], off
	v_lshl_add_u64 v[172:173], v[222:223], 0, s[4:5]
	s_mov_b32 m0, s62
	s_nop 0
	global_load_lds_dwordx4 v[172:173], off
	v_lshl_add_u64 v[172:173], v[224:225], 0, s[4:5]
	s_mov_b32 m0, s63
	s_nop 0
	global_load_lds_dwordx4 v[172:173], off
	s_waitcnt vmcnt(8)
	s_waitcnt lgkmcnt(0)
	s_setprio 1
	s_barrier
	v_mfma_f32_16x16x32_bf16 v[60:63], v[138:141], v[180:183], v[60:63]
	v_mfma_f32_16x16x32_bf16 v[56:59], v[152:155], v[180:183], v[56:59]
	v_mfma_f32_16x16x32_bf16 v[44:47], v[138:141], v[188:191], v[44:47]
	v_mfma_f32_16x16x32_bf16 v[40:43], v[152:155], v[188:191], v[40:43]
	v_mfma_f32_16x16x32_bf16 v[28:31], v[138:141], v[196:199], v[28:31]
	v_mfma_f32_16x16x32_bf16 v[24:27], v[152:155], v[196:199], v[24:27]
	v_mfma_f32_16x16x32_bf16 v[12:15], v[138:141], v[204:207], v[12:15]
	v_mfma_f32_16x16x32_bf16 v[8:11], v[152:155], v[204:207], v[8:11]
	v_mfma_f32_16x16x32_bf16 v[60:63], v[142:145], v[184:187], v[60:63]
	v_mfma_f32_16x16x32_bf16 v[56:59], v[156:159], v[184:187], v[56:59]
	v_mfma_f32_16x16x32_bf16 v[44:47], v[142:145], v[192:195], v[44:47]
	v_mfma_f32_16x16x32_bf16 v[40:43], v[156:159], v[192:195], v[40:43]
	v_mfma_f32_16x16x32_bf16 v[28:31], v[142:145], v[200:203], v[28:31]
	v_mfma_f32_16x16x32_bf16 v[24:27], v[156:159], v[200:203], v[24:27]
	v_mfma_f32_16x16x32_bf16 v[12:15], v[142:145], v[218:221], v[12:15]
	v_mfma_f32_16x16x32_bf16 v[8:11], v[156:159], v[218:221], v[8:11]
	v_mfma_f32_16x16x32_bf16 v[52:55], v[160:163], v[180:183], v[52:55]
	v_mfma_f32_16x16x32_bf16 v[48:51], v[168:171], v[180:183], v[48:51]
	v_mfma_f32_16x16x32_bf16 v[36:39], v[160:163], v[188:191], v[36:39]
	v_mfma_f32_16x16x32_bf16 v[32:35], v[168:171], v[188:191], v[32:35]
	v_mfma_f32_16x16x32_bf16 v[20:23], v[160:163], v[196:199], v[20:23]
	v_mfma_f32_16x16x32_bf16 v[16:19], v[168:171], v[196:199], v[16:19]
	v_mfma_f32_16x16x32_bf16 v[4:7], v[160:163], v[204:207], v[4:7]
	v_mfma_f32_16x16x32_bf16 v[0:3], v[168:171], v[204:207], v[0:3]
	v_mfma_f32_16x16x32_bf16 v[52:55], v[164:167], v[184:187], v[52:55]
	v_mfma_f32_16x16x32_bf16 v[48:51], v[176:179], v[184:187], v[48:51]
	v_mfma_f32_16x16x32_bf16 v[36:39], v[164:167], v[192:195], v[36:39]
	v_mfma_f32_16x16x32_bf16 v[32:35], v[176:179], v[192:195], v[32:35]
	v_mfma_f32_16x16x32_bf16 v[20:23], v[164:167], v[200:203], v[20:23]
	v_mfma_f32_16x16x32_bf16 v[16:19], v[176:179], v[200:203], v[16:19]
	v_mfma_f32_16x16x32_bf16 v[4:7], v[164:167], v[218:221], v[4:7]
	v_mfma_f32_16x16x32_bf16 v[0:3], v[176:179], v[218:221], v[0:3]
	s_barrier
	s_setprio 0
	s_add_i32 s73, s73, 2
	s_add_u32 s0, s0, 0x100
	s_addc_u32 s1, s1, 0
	s_add_u32 s71, s71, 0x100
	s_addc_u32 s72, s72, 0
	s_cmp_gt_u32 s73, 13
	s_cbranch_scc0 .LBB0_1752
	s_and_b64 vcc, exec, s[46:47]
	s_cbranch_vccz .LBB0_1755
	s_barrier

; #define PG8_STAGE(bufoff, gbase, voff) do { _Pragma("unroll") for (int _i = 0; _i < 2; ++_i) \
;         __builtin_amdgcn_global_load_lds((const unsigned*)((const char*)(gbase) + (voff)[_i]), (PG8_LAS unsigned*)(lds + (bufoff) + ldsw + _i * 8192), 16, 0, 0); } while (0)
; #define PG8_LDA(dst, b, h) do { _Pragma("unroll") for (int m = 0; m < 4; ++m) _Pragma("unroll") for (int k = 0; k < 2; ++k) dst[m][k] = *(const PG8_LAS bf16x8*)(lds + PG8_SA(b, h) + aoff + m * 2048 + k * 1024); } while (0)
; #define PG8_LDB(dst, b, h) do { _Pragma("unroll") for (int n = 0; n < 2; ++n) _Pragma("unroll") for (int k = 0; k < 2; ++k) dst[n][k] = *(const PG8_LAS bf16x8*)(lds + PG8_SB(b, h) + boff + n * 2048 + k * 1024); } while (0)
; #define PG8_WAIT_V(n) asm volatile("s_waitcnt vmcnt(" #n ")" ::: "memory")
; #define PG8_WAIT_L(n) asm volatile("s_waitcnt lgkmcnt(" #n ")" ::: "memory")
; #define PG8_BAR __builtin_amdgcn_s_barrier()
; #define PG8_SCHED __builtin_amdgcn_sched_barrier(0)
; template <class Epi, class Sched, bool ALIGN_EPI = false, bool SP2 = false>
; __device__ __forceinline__ void gemm_phase(PG8_LAS unsigned char* lds, const Gemm g, const Sched& S, const Epi& E) {
;     ...
;         const bool has_next = S.next(ui + 1, nxt);
;         const char* nA = has_next ? (const char*)g.A + (size_t)nxt.pm * tstep + (size_t)nxt.pn * g.a_gs : cA; const char* nB = has_next ? (const char*)g.Bt + (size_t)nxt.pn * tstep : cB;
;         for (int t = 0; t < nt; t += 2) {
;             const bool last = (t == nt - 2);
;             const char* a1 = cA + (size_t)(t + 1) * kstep;
;             const char* a2 = last ? nA : cA + (size_t)(t + 2) * kstep; const char* b2 = last ? nB : cB + (size_t)(t + 2) * kstep;
;             const char* a3 = a2 + kstep; const char* b3 = b2 + kstep;
;             if (last && has_next) S.a_ready(nxt);
;             if constexpr (SP2) {
;             PG8_LDB(B0, 0, 0); PG8_LDB(B1, 0, 1); PG8_SCHED; PG8_LDA(At, 0, 0); PG8_STAGE(PG8_SA(1, 1), a1 + hstep, voffA);
;             PG8_WAIT_V(8); PG8_WAIT_L(0); PG8_BAR; PG8_MMA(0, 0, At, B0); PG8_MMA(0, 1, At, B1); PG8_BAR; PG8_SCHED;
;             PG8_LDA(At, 0, 1); PG8_STAGE(PG8_SB(0, 0), b2, voffB); PG8_STAGE(PG8_SB(0, 1), b2 + hstep, voffB); PG8_STAGE(PG8_SA(0, 0), a2, voffA);
;             PG8_WAIT_V(8); PG8_WAIT_L(0); PG8_BAR; PG8_MMA(1, 0, At, B0); PG8_MMA(1, 1, At, B1); PG8_BAR; PG8_SCHED;
.LBB0_1844:
	s_ashr_i32 s49, s48, 31
	s_lshl_b64 s[50:51], s[48:49], 21
	s_add_u32 s50, s14, s50
	s_addc_u32 s51, s15, s51
	s_and_b64 s[52:53], s[42:43], exec
	s_cselect_b32 s49, s51, s1
	s_cselect_b32 s69, s50, s0
	s_ashr_i32 s47, s46, 31
	s_lshl_b64 s[52:53], s[46:47], 21
	s_add_u32 s52, s8, s52
	s_addc_u32 s53, s9, s53
	s_and_b64 s[56:57], s[42:43], exec
	s_cselect_b32 s47, s53, s55
	s_cselect_b32 s70, s52, s54
	s_add_u32 s0, s0, 0x100080
	s_addc_u32 s1, s1, 0
	s_add_u32 s71, s54, 0x100
	s_addc_u32 s72, s55, 0
	s_mov_b32 s73, -2
	s_add_u32 s54, s0, 0xfff00080
	s_addc_u32 s55, s1, -1
	s_add_i32 s74, 0, 0x10000
	s_cmp_eq_u32 s73, 60
	s_cselect_b32 s57, s49, s55
	s_cselect_b32 s56, s69, s54
	s_cselect_b32 s55, s47, s72
	s_cselect_b32 s54, s70, s71
	s_add_i32 s76, 0, 0x14000
	v_add_u32_e32 v140, s74, v189
	v_add_u32_e32 v166, s76, v189
	ds_read_b128 v[128:131], v140
	ds_read_b128 v[132:135], v140 offset:1024
	ds_read_b128 v[136:139], v140 offset:2048
	ds_read_b128 v[140:143], v140 offset:3072
	ds_read_b128 v[144:147], v166
	ds_read_b128 v[148:151], v166 offset:1024
	ds_read_b128 v[162:165], v166 offset:2048
	ds_read_b128 v[166:169], v166 offset:3072
	v_lshl_add_u64 v[208:209], s[0:1], 0, v[158:159]
	s_add_i32 m0, s59, 0xc000
	ds_read_b128 v[170:173], v191
	ds_read_b128 v[176:179], v191 offset:1024
	ds_read_b128 v[180:183], v191 offset:2048
	ds_read_b128 v[184:187], v191 offset:3072
	ds_read_b128 v[192:195], v191 offset:4096
	ds_read_b128 v[196:199], v191 offset:5120
	ds_read_b128 v[200:203], v191 offset:6144
	ds_read_b128 v[204:207], v191 offset:7168
	global_load_lds_dwordx4 v[208:209], off
	v_lshl_add_u64 v[208:209], s[0:1], 0, v[160:161]
	s_add_i32 m0, s59, 0xe000
	s_nop 0
	global_load_lds_dwordx4 v[208:209], off
	s_waitcnt vmcnt(8)
	s_waitcnt lgkmcnt(0)
	s_setprio 1
	s_barrier
	v_mfma_f32_16x16x32_bf16 v[124:127], v[128:131], v[170:173], 0
	v_mfma_f32_16x16x32_bf16 v[120:123], v[136:139], v[170:173], 0
	v_mfma_f32_16x16x32_bf16 v[108:111], v[128:131], v[180:183], 0
	v_mfma_f32_16x16x32_bf16 v[104:107], v[136:139], v[180:183], 0
	v_mfma_f32_16x16x32_bf16 v[92:95], v[128:131], v[192:195], 0
	v_mfma_f32_16x16x32_bf16 v[88:91], v[136:139], v[192:195], 0
	v_mfma_f32_16x16x32_bf16 v[76:79], v[128:131], v[200:203], 0
	v_mfma_f32_16x16x32_bf16 v[72:75], v[136:139], v[200:203], 0
	v_mfma_f32_16x16x32_bf16 v[124:127], v[132:135], v[176:179], v[124:127]
	v_mfma_f32_16x16x32_bf16 v[120:123], v[140:143], v[176:179], v[120:123]
	v_mfma_f32_16x16x32_bf16 v[108:111], v[132:135], v[184:187], v[108:111]
	v_mfma_f32_16x16x32_bf16 v[104:107], v[140:143], v[184:187], v[104:107]
	v_mfma_f32_16x16x32_bf16 v[92:95], v[132:135], v[196:199], v[92:95]
	v_mfma_f32_16x16x32_bf16 v[88:91], v[140:143], v[196:199], v[88:91]
	v_mfma_f32_16x16x32_bf16 v[76:79], v[132:135], v[204:207], v[76:79]
	v_mfma_f32_16x16x32_bf16 v[72:75], v[140:143], v[204:207], v[72:75]
	v_mfma_f32_16x16x32_bf16 v[116:119], v[144:147], v[170:173], 0
	v_mfma_f32_16x16x32_bf16 v[112:115], v[162:165], v[170:173], 0
	v_mfma_f32_16x16x32_bf16 v[100:103], v[144:147], v[180:183], 0
	v_mfma_f32_16x16x32_bf16 v[96:99], v[162:165], v[180:183], 0
	v_mfma_f32_16x16x32_bf16 v[84:87], v[144:147], v[192:195], 0
	v_mfma_f32_16x16x32_bf16 v[80:83], v[162:165], v[192:195], 0
	v_mfma_f32_16x16x32_bf16 v[68:71], v[144:147], v[200:203], 0
	v_mfma_f32_16x16x32_bf16 v[64:67], v[162:165], v[200:203], 0
	v_mfma_f32_16x16x32_bf16 v[116:119], v[148:151], v[176:179], v[116:119]
	v_mfma_f32_16x16x32_bf16 v[112:115], v[166:169], v[176:179], v[112:115]
	v_mfma_f32_16x16x32_bf16 v[100:103], v[148:151], v[184:187], v[100:103]
	v_mfma_f32_16x16x32_bf16 v[96:99], v[166:169], v[184:187], v[96:99]
	v_mfma_f32_16x16x32_bf16 v[84:87], v[148:151], v[196:199], v[84:87]
	v_mfma_f32_16x16x32_bf16 v[80:83], v[166:169], v[196:199], v[80:83]
	v_mfma_f32_16x16x32_bf16 v[68:71], v[148:151], v[204:207], v[68:71]
	v_mfma_f32_16x16x32_bf16 v[64:67], v[166:169], v[204:207], v[64:67]
	s_barrier
	s_setprio 0
	s_add_i32 s74, s74, s58
	v_lshl_add_u64 v[208:209], s[54:55], 0, v[174:175]
	s_mov_b32 m0, s74
	ds_read_b128 v[170:173], v191 offset:16384
	ds_read_b128 v[176:179], v191 offset:17408
	ds_read_b128 v[180:183], v191 offset:18432
	ds_read_b128 v[184:187], v191 offset:19456
	ds_read_b128 v[192:195], v191 offset:20480
	ds_read_b128 v[196:199], v191 offset:21504
	ds_read_b128 v[200:203], v191 offset:22528
	ds_read_b128 v[204:207], v191 offset:23552
	global_load_lds_dwordx4 v[208:209], off
	s_add_i32 m0, s74, 0x2000
	s_add_u32 s74, s54, 0x100000
	v_lshl_add_u64 v[218:219], s[54:55], 0, v[152:153]
	s_addc_u32 s75, s55, 0
	s_add_i32 s76, s76, s58
	global_load_lds_dwordx4 v[218:219], off
	v_lshl_add_u64 v[220:221], s[74:75], 0, v[174:175]
	s_mov_b32 m0, s76
	v_lshl_add_u64 v[222:223], s[56:57], 0, v[154:155]
	global_load_lds_dwordx4 v[220:221], off
	v_lshl_add_u64 v[220:221], s[74:75], 0, v[152:153]
	s_add_i32 m0, s76, 0x2000
	s_nop 0
	global_load_lds_dwordx4 v[220:221], off
	v_lshl_add_u64 v[220:221], s[56:57], 0, v[156:157]
	s_mov_b32 m0, s59
	s_nop 0
	global_load_lds_dwordx4 v[220:221], off
	s_mov_b32 m0, s60
	s_nop 0
	global_load_lds_dwordx4 v[222:223], off
	s_waitcnt vmcnt(8)
	s_waitcnt lgkmcnt(0)
	s_setprio 1
	s_barrier
; #define PG8_STAGE(bufoff, gbase, voff) do { _Pragma("unroll") for (int _i = 0; _i < 2; ++_i) \
;         __builtin_amdgcn_global_load_lds((const unsigned*)((const char*)(gbase) + (voff)[_i]), (PG8_LAS unsigned*)(lds + (bufoff) + ldsw + _i * 8192), 16, 0, 0); } while (0)
; #define PG8_LDA(dst, b, h) do { _Pragma("unroll") for (int m = 0; m < 4; ++m) _Pragma("unroll") for (int k = 0; k < 2; ++k) dst[m][k] = *(const PG8_LAS bf16x8*)(lds + PG8_SA(b, h) + aoff + m * 2048 + k * 1024); } while (0)
; #define PG8_LDB(dst, b, h) do { _Pragma("unroll") for (int n = 0; n < 2; ++n) _Pragma("unroll") for (int k = 0; k < 2; ++k) dst[n][k] = *(const PG8_LAS bf16x8*)(lds + PG8_SB(b, h) + boff + n * 2048 + k * 1024); } while (0)
; #define PG8_MMA(ai, bj, At, Bt) do { __builtin_amdgcn_s_setprio(1); _Pragma("unroll") for (int m = 0; m < 4; ++m) _Pragma("unroll") for (int n = 0; n < 2; ++n) _Pragma("unroll") for (int k = 0; k < 2; ++k) \
;         acc[ai][bj][m][n] = __builtin_amdgcn_mfma_f32_16x16x32_bf16(Bt[n][k], At[m][k], acc[ai][bj][m][n], 0, 0, 0); __builtin_amdgcn_s_setprio(0); } while (0)
; #define PG8_WAIT_V(n) asm volatile("s_waitcnt vmcnt(" #n ")" ::: "memory")
; #define PG8_WAIT_L(n) asm volatile("s_waitcnt lgkmcnt(" #n ")" ::: "memory")
; #define PG8_BAR __builtin_amdgcn_s_barrier()
; #define PG8_SCHED __builtin_amdgcn_sched_barrier(0)
; template <class Epi, class Sched, bool ALIGN_EPI = false, bool SP2 = false>
; __device__ __forceinline__ void gemm_phase(PG8_LAS unsigned char* lds, const Gemm g, const Sched& S, const Epi& E) {
;     ...
;             PG8_WAIT_V(8); PG8_WAIT_L(0); PG8_BAR; PG8_MMA(1, 0, At, B0); PG8_MMA(1, 1, At, B1); PG8_BAR; PG8_SCHED;
;             PG8_LDB(B0, 1, 0); PG8_LDB(B1, 1, 1); PG8_SCHED; PG8_LDA(At, 1, 0); PG8_STAGE(PG8_SA(0, 1), a2 + hstep, voffA);
;             PG8_WAIT_V(8); PG8_WAIT_L(0); PG8_BAR; PG8_MMA(0, 0, At, B0); PG8_MMA(0, 1, At, B1); PG8_BAR; PG8_SCHED;
	v_mfma_f32_16x16x32_bf16 v[60:63], v[128:131], v[170:173], 0
	v_mfma_f32_16x16x32_bf16 v[56:59], v[136:139], v[170:173], 0
	v_mfma_f32_16x16x32_bf16 v[44:47], v[128:131], v[180:183], 0
	v_mfma_f32_16x16x32_bf16 v[40:43], v[136:139], v[180:183], 0
	v_mfma_f32_16x16x32_bf16 v[28:31], v[128:131], v[192:195], 0
	v_mfma_f32_16x16x32_bf16 v[24:27], v[136:139], v[192:195], 0
	v_mfma_f32_16x16x32_bf16 v[12:15], v[128:131], v[200:203], 0
	v_mfma_f32_16x16x32_bf16 v[8:11], v[136:139], v[200:203], 0
	v_mfma_f32_16x16x32_bf16 v[60:63], v[132:135], v[176:179], v[60:63]
	v_mfma_f32_16x16x32_bf16 v[56:59], v[140:143], v[176:179], v[56:59]
	v_mfma_f32_16x16x32_bf16 v[44:47], v[132:135], v[184:187], v[44:47]
	v_mfma_f32_16x16x32_bf16 v[40:43], v[140:143], v[184:187], v[40:43]
	v_mfma_f32_16x16x32_bf16 v[28:31], v[132:135], v[196:199], v[28:31]
	v_mfma_f32_16x16x32_bf16 v[24:27], v[140:143], v[196:199], v[24:27]
	v_mfma_f32_16x16x32_bf16 v[12:15], v[132:135], v[204:207], v[12:15]
	v_mfma_f32_16x16x32_bf16 v[8:11], v[140:143], v[204:207], v[8:11]
	v_mfma_f32_16x16x32_bf16 v[52:55], v[144:147], v[170:173], 0
	v_mfma_f32_16x16x32_bf16 v[48:51], v[162:165], v[170:173], 0
	v_mfma_f32_16x16x32_bf16 v[36:39], v[144:147], v[180:183], 0
	v_mfma_f32_16x16x32_bf16 v[32:35], v[162:165], v[180:183], 0
	v_mfma_f32_16x16x32_bf16 v[20:23], v[144:147], v[192:195], 0
	v_mfma_f32_16x16x32_bf16 v[16:19], v[162:165], v[192:195], 0
	v_mfma_f32_16x16x32_bf16 v[4:7], v[144:147], v[200:203], 0
	v_mfma_f32_16x16x32_bf16 v[0:3], v[162:165], v[200:203], 0
	v_mfma_f32_16x16x32_bf16 v[52:55], v[148:151], v[176:179], v[52:55]
	v_mfma_f32_16x16x32_bf16 v[48:51], v[166:169], v[176:179], v[48:51]
	v_mfma_f32_16x16x32_bf16 v[36:39], v[148:151], v[184:187], v[36:39]
	v_mfma_f32_16x16x32_bf16 v[32:35], v[166:169], v[184:187], v[32:35]
	v_mfma_f32_16x16x32_bf16 v[20:23], v[148:151], v[196:199], v[20:23]
	v_mfma_f32_16x16x32_bf16 v[16:19], v[166:169], v[196:199], v[16:19]
	v_mfma_f32_16x16x32_bf16 v[4:7], v[148:151], v[204:207], v[4:7]
	v_mfma_f32_16x16x32_bf16 v[0:3], v[166:169], v[204:207], v[0:3]
	s_barrier
	s_setprio 0
	s_add_i32 s74, 0, 0x18000
	s_add_i32 s75, 0, 0x1c000
	v_add_u32_e32 v140, s74, v189
	v_add_u32_e32 v166, s75, v189
	ds_read_b128 v[128:131], v140
	ds_read_b128 v[132:135], v140 offset:1024
	ds_read_b128 v[136:139], v140 offset:2048
	ds_read_b128 v[140:143], v140 offset:3072
	ds_read_b128 v[144:147], v166
	ds_read_b128 v[148:151], v166 offset:1024
	ds_read_b128 v[162:165], v166 offset:2048
	ds_read_b128 v[166:169], v166 offset:3072
	s_add_u32 s56, s56, 0x100000
	s_addc_u32 s57, s57, 0
	s_mov_b32 m0, s61
	v_lshl_add_u64 v[224:225], s[56:57], 0, v[156:157]
	ds_read_b128 v[170:173], v191 offset:32768
	ds_read_b128 v[176:179], v191 offset:33792
	ds_read_b128 v[180:183], v191 offset:34816
	ds_read_b128 v[184:187], v191 offset:35840
	ds_read_b128 v[192:195], v191 offset:36864
	ds_read_b128 v[196:199], v191 offset:37888
	ds_read_b128 v[200:203], v191 offset:38912
	ds_read_b128 v[204:207], v191 offset:39936
	global_load_lds_dwordx4 v[224:225], off
	v_lshl_add_u64 v[224:225], s[56:57], 0, v[154:155]
	s_mov_b32 m0, s62
	s_nop 0
	global_load_lds_dwordx4 v[224:225], off
	s_waitcnt vmcnt(8)
	s_waitcnt lgkmcnt(0)
	s_setprio 1
	s_barrier
	v_mfma_f32_16x16x32_bf16 v[124:127], v[128:131], v[170:173], v[124:127]
	v_mfma_f32_16x16x32_bf16 v[120:123], v[136:139], v[170:173], v[120:123]
	v_mfma_f32_16x16x32_bf16 v[108:111], v[128:131], v[180:183], v[108:111]
	v_mfma_f32_16x16x32_bf16 v[104:107], v[136:139], v[180:183], v[104:107]
	v_mfma_f32_16x16x32_bf16 v[92:95], v[128:131], v[192:195], v[92:95]
	v_mfma_f32_16x16x32_bf16 v[88:91], v[136:139], v[192:195], v[88:91]
	v_mfma_f32_16x16x32_bf16 v[76:79], v[128:131], v[200:203], v[76:79]
	v_mfma_f32_16x16x32_bf16 v[72:75], v[136:139], v[200:203], v[72:75]
	v_mfma_f32_16x16x32_bf16 v[124:127], v[132:135], v[176:179], v[124:127]
	v_mfma_f32_16x16x32_bf16 v[120:123], v[140:143], v[176:179], v[120:123]
	v_mfma_f32_16x16x32_bf16 v[108:111], v[132:135], v[184:187], v[108:111]
	v_mfma_f32_16x16x32_bf16 v[104:107], v[140:143], v[184:187], v[104:107]
	v_mfma_f32_16x16x32_bf16 v[92:95], v[132:135], v[196:199], v[92:95]
	v_mfma_f32_16x16x32_bf16 v[88:91], v[140:143], v[196:199], v[88:91]
	v_mfma_f32_16x16x32_bf16 v[76:79], v[132:135], v[204:207], v[76:79]
	v_mfma_f32_16x16x32_bf16 v[72:75], v[140:143], v[204:207], v[72:75]
	v_mfma_f32_16x16x32_bf16 v[116:119], v[144:147], v[170:173], v[116:119]
	v_mfma_f32_16x16x32_bf16 v[112:115], v[162:165], v[170:173], v[112:115]
	v_mfma_f32_16x16x32_bf16 v[100:103], v[144:147], v[180:183], v[100:103]
	v_mfma_f32_16x16x32_bf16 v[96:99], v[162:165], v[180:183], v[96:99]
	v_mfma_f32_16x16x32_bf16 v[84:87], v[144:147], v[192:195], v[84:87]
	v_mfma_f32_16x16x32_bf16 v[80:83], v[162:165], v[192:195], v[80:83]
	v_mfma_f32_16x16x32_bf16 v[68:71], v[144:147], v[200:203], v[68:71]
	v_mfma_f32_16x16x32_bf16 v[64:67], v[162:165], v[200:203], v[64:67]
	v_mfma_f32_16x16x32_bf16 v[116:119], v[148:151], v[176:179], v[116:119]
	v_mfma_f32_16x16x32_bf16 v[112:115], v[166:169], v[176:179], v[112:115]
	v_mfma_f32_16x16x32_bf16 v[100:103], v[148:151], v[184:187], v[100:103]
	v_mfma_f32_16x16x32_bf16 v[96:99], v[166:169], v[184:187], v[96:99]
	v_mfma_f32_16x16x32_bf16 v[84:87], v[148:151], v[196:199], v[84:87]
	v_mfma_f32_16x16x32_bf16 v[80:83], v[166:169], v[196:199], v[80:83]
	v_mfma_f32_16x16x32_bf16 v[68:71], v[148:151], v[204:207], v[68:71]
	v_mfma_f32_16x16x32_bf16 v[64:67], v[166:169], v[204:207], v[64:67]
	s_barrier
; #define PG8_STAGE(bufoff, gbase, voff) do { _Pragma("unroll") for (int _i = 0; _i < 2; ++_i) \
;         __builtin_amdgcn_global_load_lds((const unsigned*)((const char*)(gbase) + (voff)[_i]), (PG8_LAS unsigned*)(lds + (bufoff) + ldsw + _i * 8192), 16, 0, 0); } while (0)
; #define PG8_LDA(dst, b, h) do { _Pragma("unroll") for (int m = 0; m < 4; ++m) _Pragma("unroll") for (int k = 0; k < 2; ++k) dst[m][k] = *(const PG8_LAS bf16x8*)(lds + PG8_SA(b, h) + aoff + m * 2048 + k * 1024); } while (0)
; #define PG8_LDB(dst, b, h) do { _Pragma("unroll") for (int n = 0; n < 2; ++n) _Pragma("unroll") for (int k = 0; k < 2; ++k) dst[n][k] = *(const PG8_LAS bf16x8*)(lds + PG8_SB(b, h) + boff + n * 2048 + k * 1024); } while (0)
; #define PG8_MMA(ai, bj, At, Bt) do { __builtin_amdgcn_s_setprio(1); _Pragma("unroll") for (int m = 0; m < 4; ++m) _Pragma("unroll") for (int n = 0; n < 2; ++n) _Pragma("unroll") for (int k = 0; k < 2; ++k) \
;         acc[ai][bj][m][n] = __builtin_amdgcn_mfma_f32_16x16x32_bf16(Bt[n][k], At[m][k], acc[ai][bj][m][n], 0, 0, 0); __builtin_amdgcn_s_setprio(0); } while (0)
; template <class Epi, class Sched, bool ALIGN_EPI = false, bool SP2 = false>
; __device__ __forceinline__ void gemm_phase(PG8_LAS unsigned char* lds, const Gemm g, const Sched& S, const Epi& E) {
;     ...
;         for (int t = 0; t < nt; t += 2) {
;             const bool last = (t == nt - 2);
;             const char* a1 = cA + (size_t)(t + 1) * kstep;
;             const char* a2 = last ? nA : cA + (size_t)(t + 2) * kstep; const char* b2 = last ? nB : cB + (size_t)(t + 2) * kstep;
;             const char* a3 = a2 + kstep; const char* b3 = b2 + kstep;
;             if (last && has_next) S.a_ready(nxt);
;             if constexpr (SP2) {
;             PG8_LDB(B0, 0, 0); PG8_LDB(B1, 0, 1); PG8_SCHED; PG8_LDA(At, 0, 0); PG8_STAGE(PG8_SA(1, 1), a1 + hstep, voffA);
;             PG8_WAIT_V(8); PG8_WAIT_L(0); PG8_BAR; PG8_MMA(0, 0, At, B0); PG8_MMA(0, 1, At, B1); PG8_BAR; PG8_SCHED;
;             PG8_LDA(At, 0, 1); PG8_STAGE(PG8_SB(0, 0), b2, voffB); PG8_STAGE(PG8_SB(0, 1), b2 + hstep, voffB); PG8_STAGE(PG8_SA(0, 0), a2, voffA);
;     ...
;             PG8_LDA(At, 1, 1); PG8_STAGE(PG8_SB(1, 0), b3, voffB); PG8_STAGE(PG8_SB(1, 1), b3 + hstep, voffB); PG8_STAGE(PG8_SA(1, 0), a3, voffA);
;             PG8_WAIT_V(8); PG8_WAIT_L(0); PG8_BAR; PG8_MMA(1, 0, At, B0); PG8_MMA(1, 1, At, B1); PG8_BAR; PG8_SCHED;
	s_setprio 0
	s_add_i32 s56, s74, s58
	v_lshl_add_u64 v[208:209], v[208:209], 0, s[4:5]
	s_mov_b32 m0, s56
	ds_read_b128 v[170:173], v191 offset:49152
	ds_read_b128 v[176:179], v191 offset:50176
	ds_read_b128 v[180:183], v191 offset:51200
	ds_read_b128 v[184:187], v191 offset:52224
	ds_read_b128 v[192:195], v191 offset:53248
	ds_read_b128 v[196:199], v191 offset:54272
	ds_read_b128 v[200:203], v191 offset:55296
	ds_read_b128 v[204:207], v191 offset:56320
	global_load_lds_dwordx4 v[208:209], off
	s_add_i32 m0, s56, 0x2000
	s_add_u32 s54, s54, 0x100080
	v_lshl_add_u64 v[208:209], v[218:219], 0, s[4:5]
	s_addc_u32 s55, s55, 0
	s_add_i32 s56, s75, s58
	global_load_lds_dwordx4 v[208:209], off
	v_lshl_add_u64 v[208:209], s[54:55], 0, v[174:175]
	s_mov_b32 m0, s56
	s_nop 0
	global_load_lds_dwordx4 v[208:209], off
	v_lshl_add_u64 v[208:209], s[54:55], 0, v[152:153]
	s_add_i32 m0, s56, 0x2000
	s_nop 0
	global_load_lds_dwordx4 v[208:209], off
	v_lshl_add_u64 v[208:209], v[220:221], 0, s[4:5]
	s_mov_b32 m0, s64
	s_nop 0
	global_load_lds_dwordx4 v[208:209], off
	v_lshl_add_u64 v[208:209], v[222:223], 0, s[4:5]
	s_mov_b32 m0, s65
	s_nop 0
	global_load_lds_dwordx4 v[208:209], off
	s_waitcnt vmcnt(8)
	s_waitcnt lgkmcnt(0)
	s_setprio 1
	s_barrier
	v_mfma_f32_16x16x32_bf16 v[60:63], v[128:131], v[170:173], v[60:63]
	v_mfma_f32_16x16x32_bf16 v[56:59], v[136:139], v[170:173], v[56:59]
	v_mfma_f32_16x16x32_bf16 v[44:47], v[128:131], v[180:183], v[44:47]
	v_mfma_f32_16x16x32_bf16 v[40:43], v[136:139], v[180:183], v[40:43]
	v_mfma_f32_16x16x32_bf16 v[28:31], v[128:131], v[192:195], v[28:31]
	v_mfma_f32_16x16x32_bf16 v[24:27], v[136:139], v[192:195], v[24:27]
	v_mfma_f32_16x16x32_bf16 v[12:15], v[128:131], v[200:203], v[12:15]
	v_mfma_f32_16x16x32_bf16 v[8:11], v[136:139], v[200:203], v[8:11]
	v_mfma_f32_16x16x32_bf16 v[60:63], v[132:135], v[176:179], v[60:63]
	v_mfma_f32_16x16x32_bf16 v[56:59], v[140:143], v[176:179], v[56:59]
	v_mfma_f32_16x16x32_bf16 v[44:47], v[132:135], v[184:187], v[44:47]
	v_mfma_f32_16x16x32_bf16 v[40:43], v[140:143], v[184:187], v[40:43]
	v_mfma_f32_16x16x32_bf16 v[28:31], v[132:135], v[196:199], v[28:31]
	v_mfma_f32_16x16x32_bf16 v[24:27], v[140:143], v[196:199], v[24:27]
	v_mfma_f32_16x16x32_bf16 v[12:15], v[132:135], v[204:207], v[12:15]
	v_mfma_f32_16x16x32_bf16 v[8:11], v[140:143], v[204:207], v[8:11]
	v_mfma_f32_16x16x32_bf16 v[52:55], v[144:147], v[170:173], v[52:55]
	v_mfma_f32_16x16x32_bf16 v[48:51], v[162:165], v[170:173], v[48:51]
	v_mfma_f32_16x16x32_bf16 v[36:39], v[144:147], v[180:183], v[36:39]
	v_mfma_f32_16x16x32_bf16 v[32:35], v[162:165], v[180:183], v[32:35]
	v_mfma_f32_16x16x32_bf16 v[20:23], v[144:147], v[192:195], v[20:23]
	v_mfma_f32_16x16x32_bf16 v[16:19], v[162:165], v[192:195], v[16:19]
	v_mfma_f32_16x16x32_bf16 v[4:7], v[144:147], v[200:203], v[4:7]
	v_mfma_f32_16x16x32_bf16 v[0:3], v[162:165], v[200:203], v[0:3]
	v_mfma_f32_16x16x32_bf16 v[52:55], v[148:151], v[176:179], v[52:55]
	v_mfma_f32_16x16x32_bf16 v[48:51], v[166:169], v[176:179], v[48:51]
	v_mfma_f32_16x16x32_bf16 v[36:39], v[148:151], v[184:187], v[36:39]
	v_mfma_f32_16x16x32_bf16 v[32:35], v[166:169], v[184:187], v[32:35]
	v_mfma_f32_16x16x32_bf16 v[20:23], v[148:151], v[196:199], v[20:23]
	v_mfma_f32_16x16x32_bf16 v[16:19], v[166:169], v[196:199], v[16:19]
	v_mfma_f32_16x16x32_bf16 v[4:7], v[148:151], v[204:207], v[4:7]
	v_mfma_f32_16x16x32_bf16 v[0:3], v[166:169], v[204:207], v[0:3]
	s_barrier
	s_setprio 0
	s_add_i32 s73, s73, 2
	s_add_u32 s0, s0, 0x100
	s_addc_u32 s1, s1, 0
	s_add_u32 s71, s71, 0x100
	s_addc_u32 s72, s72, 0
	s_cmp_gt_u32 s73, 61
	s_cbranch_scc0 .LBB0_1845
.LBB0_1845:
	s_add_u32 s54, s0, 0xfff00080
	s_addc_u32 s55, s1, -1
	s_add_i32 s74, 0, 0x10000
	s_cmp_eq_u32 s73, 60
	s_cselect_b32 s57, s49, s55
	s_cselect_b32 s56, s69, s54
	s_cselect_b32 s55, s47, s72
	s_cselect_b32 s54, s70, s71
	s_add_i32 s76, 0, 0x14000
	v_add_u32_e32 v140, s74, v189
	v_add_u32_e32 v166, s76, v189
	ds_read_b128 v[128:131], v140
	ds_read_b128 v[132:135], v140 offset:1024
	ds_read_b128 v[136:139], v140 offset:2048
	ds_read_b128 v[140:143], v140 offset:3072
	ds_read_b128 v[144:147], v166
	ds_read_b128 v[148:151], v166 offset:1024
	ds_read_b128 v[162:165], v166 offset:2048
	ds_read_b128 v[166:169], v166 offset:3072
	v_lshl_add_u64 v[208:209], s[0:1], 0, v[158:159]
	s_add_i32 m0, s59, 0xc000
	ds_read_b128 v[170:173], v191
	ds_read_b128 v[176:179], v191 offset:1024
	ds_read_b128 v[180:183], v191 offset:2048
	ds_read_b128 v[184:187], v191 offset:3072
	ds_read_b128 v[192:195], v191 offset:4096
	ds_read_b128 v[196:199], v191 offset:5120
	ds_read_b128 v[200:203], v191 offset:6144
	ds_read_b128 v[204:207], v191 offset:7168
	global_load_lds_dwordx4 v[208:209], off
	v_lshl_add_u64 v[208:209], s[0:1], 0, v[160:161]
	s_add_i32 m0, s59, 0xe000
	s_nop 0
	global_load_lds_dwordx4 v[208:209], off
	s_waitcnt vmcnt(8)
	s_waitcnt lgkmcnt(0)
	s_setprio 1
	s_barrier
; #define PG8_STAGE(bufoff, gbase, voff) do { _Pragma("unroll") for (int _i = 0; _i < 2; ++_i) \
;         __builtin_amdgcn_global_load_lds((const unsigned*)((const char*)(gbase) + (voff)[_i]), (PG8_LAS unsigned*)(lds + (bufoff) + ldsw + _i * 8192), 16, 0, 0); } while (0)
; #define PG8_LDA(dst, b, h) do { _Pragma("unroll") for (int m = 0; m < 4; ++m) _Pragma("unroll") for (int k = 0; k < 2; ++k) dst[m][k] = *(const PG8_LAS bf16x8*)(lds + PG8_SA(b, h) + aoff + m * 2048 + k * 1024); } while (0)
; #define PG8_MMA(ai, bj, At, Bt) do { __builtin_amdgcn_s_setprio(1); _Pragma("unroll") for (int m = 0; m < 4; ++m) _Pragma("unroll") for (int n = 0; n < 2; ++n) _Pragma("unroll") for (int k = 0; k < 2; ++k) \
;         acc[ai][bj][m][n] = __builtin_amdgcn_mfma_f32_16x16x32_bf16(Bt[n][k], At[m][k], acc[ai][bj][m][n], 0, 0, 0); __builtin_amdgcn_s_setprio(0); } while (0)
; #define PG8_WAIT_V(n) asm volatile("s_waitcnt vmcnt(" #n ")" ::: "memory")
; #define PG8_WAIT_L(n) asm volatile("s_waitcnt lgkmcnt(" #n ")" ::: "memory")
; #define PG8_BAR __builtin_amdgcn_s_barrier()
; #define PG8_SCHED __builtin_amdgcn_sched_barrier(0)
; template <class Epi, class Sched, bool ALIGN_EPI = false, bool SP2 = false>
; __device__ __forceinline__ void gemm_phase(PG8_LAS unsigned char* lds, const Gemm g, const Sched& S, const Epi& E) {
;     ...
;             PG8_WAIT_V(8); PG8_WAIT_L(0); PG8_BAR; PG8_MMA(0, 0, At, B0); PG8_MMA(0, 1, At, B1); PG8_BAR; PG8_SCHED;
;             PG8_LDA(At, 0, 1); PG8_STAGE(PG8_SB(0, 0), b2, voffB); PG8_STAGE(PG8_SB(0, 1), b2 + hstep, voffB); PG8_STAGE(PG8_SA(0, 0), a2, voffA);
;             PG8_WAIT_V(8); PG8_WAIT_L(0); PG8_BAR; PG8_MMA(1, 0, At, B0); PG8_MMA(1, 1, At, B1); PG8_BAR; PG8_SCHED;
	v_mfma_f32_16x16x32_bf16 v[124:127], v[128:131], v[170:173], v[124:127]
	v_mfma_f32_16x16x32_bf16 v[120:123], v[136:139], v[170:173], v[120:123]
	v_mfma_f32_16x16x32_bf16 v[108:111], v[128:131], v[180:183], v[108:111]
	v_mfma_f32_16x16x32_bf16 v[104:107], v[136:139], v[180:183], v[104:107]
	v_mfma_f32_16x16x32_bf16 v[92:95], v[128:131], v[192:195], v[92:95]
	v_mfma_f32_16x16x32_bf16 v[88:91], v[136:139], v[192:195], v[88:91]
	v_mfma_f32_16x16x32_bf16 v[76:79], v[128:131], v[200:203], v[76:79]
	v_mfma_f32_16x16x32_bf16 v[72:75], v[136:139], v[200:203], v[72:75]
	v_mfma_f32_16x16x32_bf16 v[124:127], v[132:135], v[176:179], v[124:127]
	v_mfma_f32_16x16x32_bf16 v[120:123], v[140:143], v[176:179], v[120:123]
	v_mfma_f32_16x16x32_bf16 v[108:111], v[132:135], v[184:187], v[108:111]
	v_mfma_f32_16x16x32_bf16 v[104:107], v[140:143], v[184:187], v[104:107]
	v_mfma_f32_16x16x32_bf16 v[92:95], v[132:135], v[196:199], v[92:95]
	v_mfma_f32_16x16x32_bf16 v[88:91], v[140:143], v[196:199], v[88:91]
	v_mfma_f32_16x16x32_bf16 v[76:79], v[132:135], v[204:207], v[76:79]
	v_mfma_f32_16x16x32_bf16 v[72:75], v[140:143], v[204:207], v[72:75]
	v_mfma_f32_16x16x32_bf16 v[116:119], v[144:147], v[170:173], v[116:119]
	v_mfma_f32_16x16x32_bf16 v[112:115], v[162:165], v[170:173], v[112:115]
	v_mfma_f32_16x16x32_bf16 v[100:103], v[144:147], v[180:183], v[100:103]
	v_mfma_f32_16x16x32_bf16 v[96:99], v[162:165], v[180:183], v[96:99]
	v_mfma_f32_16x16x32_bf16 v[84:87], v[144:147], v[192:195], v[84:87]
	v_mfma_f32_16x16x32_bf16 v[80:83], v[162:165], v[192:195], v[80:83]
	v_mfma_f32_16x16x32_bf16 v[68:71], v[144:147], v[200:203], v[68:71]
	v_mfma_f32_16x16x32_bf16 v[64:67], v[162:165], v[200:203], v[64:67]
	v_mfma_f32_16x16x32_bf16 v[116:119], v[148:151], v[176:179], v[116:119]
	v_mfma_f32_16x16x32_bf16 v[112:115], v[166:169], v[176:179], v[112:115]
	v_mfma_f32_16x16x32_bf16 v[100:103], v[148:151], v[184:187], v[100:103]
	v_mfma_f32_16x16x32_bf16 v[96:99], v[166:169], v[184:187], v[96:99]
	v_mfma_f32_16x16x32_bf16 v[84:87], v[148:151], v[196:199], v[84:87]
	v_mfma_f32_16x16x32_bf16 v[80:83], v[166:169], v[196:199], v[80:83]
	v_mfma_f32_16x16x32_bf16 v[68:71], v[148:151], v[204:207], v[68:71]
	v_mfma_f32_16x16x32_bf16 v[64:67], v[166:169], v[204:207], v[64:67]
	s_barrier
	s_setprio 0
	s_add_i32 s74, s74, s58
	v_lshl_add_u64 v[208:209], s[54:55], 0, v[174:175]
	s_mov_b32 m0, s74
	ds_read_b128 v[170:173], v191 offset:16384
	ds_read_b128 v[176:179], v191 offset:17408
	ds_read_b128 v[180:183], v191 offset:18432
	ds_read_b128 v[184:187], v191 offset:19456
	ds_read_b128 v[192:195], v191 offset:20480
	ds_read_b128 v[196:199], v191 offset:21504
	ds_read_b128 v[200:203], v191 offset:22528
	ds_read_b128 v[204:207], v191 offset:23552
	global_load_lds_dwordx4 v[208:209], off
	s_add_i32 m0, s74, 0x2000
	s_add_u32 s74, s54, 0x100000
	v_lshl_add_u64 v[218:219], s[54:55], 0, v[152:153]
	s_addc_u32 s75, s55, 0
	s_add_i32 s76, s76, s58
	global_load_lds_dwordx4 v[218:219], off
	v_lshl_add_u64 v[220:221], s[74:75], 0, v[174:175]
	s_mov_b32 m0, s76
	v_lshl_add_u64 v[222:223], s[56:57], 0, v[154:155]
	global_load_lds_dwordx4 v[220:221], off
	v_lshl_add_u64 v[220:221], s[74:75], 0, v[152:153]
	s_add_i32 m0, s76, 0x2000
	s_nop 0
	global_load_lds_dwordx4 v[220:221], off
	v_lshl_add_u64 v[220:221], s[56:57], 0, v[156:157]
	s_mov_b32 m0, s59
	s_nop 0
	global_load_lds_dwordx4 v[220:221], off
	s_mov_b32 m0, s60
	s_nop 0
	global_load_lds_dwordx4 v[222:223], off
	s_waitcnt vmcnt(8)
	s_waitcnt lgkmcnt(0)
	s_setprio 1
	s_barrier
	v_mfma_f32_16x16x32_bf16 v[60:63], v[128:131], v[170:173], v[60:63]
	v_mfma_f32_16x16x32_bf16 v[56:59], v[136:139], v[170:173], v[56:59]
	v_mfma_f32_16x16x32_bf16 v[44:47], v[128:131], v[180:183], v[44:47]
	v_mfma_f32_16x16x32_bf16 v[40:43], v[136:139], v[180:183], v[40:43]
	v_mfma_f32_16x16x32_bf16 v[28:31], v[128:131], v[192:195], v[28:31]
	v_mfma_f32_16x16x32_bf16 v[24:27], v[136:139], v[192:195], v[24:27]
	v_mfma_f32_16x16x32_bf16 v[12:15], v[128:131], v[200:203], v[12:15]
	v_mfma_f32_16x16x32_bf16 v[8:11], v[136:139], v[200:203], v[8:11]
	v_mfma_f32_16x16x32_bf16 v[60:63], v[132:135], v[176:179], v[60:63]
	v_mfma_f32_16x16x32_bf16 v[56:59], v[140:143], v[176:179], v[56:59]
	v_mfma_f32_16x16x32_bf16 v[44:47], v[132:135], v[184:187], v[44:47]
	v_mfma_f32_16x16x32_bf16 v[40:43], v[140:143], v[184:187], v[40:43]
	v_mfma_f32_16x16x32_bf16 v[28:31], v[132:135], v[196:199], v[28:31]
	v_mfma_f32_16x16x32_bf16 v[24:27], v[140:143], v[196:199], v[24:27]
	v_mfma_f32_16x16x32_bf16 v[12:15], v[132:135], v[204:207], v[12:15]
	v_mfma_f32_16x16x32_bf16 v[8:11], v[140:143], v[204:207], v[8:11]
	v_mfma_f32_16x16x32_bf16 v[52:55], v[144:147], v[170:173], v[52:55]
	v_mfma_f32_16x16x32_bf16 v[48:51], v[162:165], v[170:173], v[48:51]
	v_mfma_f32_16x16x32_bf16 v[36:39], v[144:147], v[180:183], v[36:39]
	v_mfma_f32_16x16x32_bf16 v[32:35], v[162:165], v[180:183], v[32:35]
	v_mfma_f32_16x16x32_bf16 v[20:23], v[144:147], v[192:195], v[20:23]
	v_mfma_f32_16x16x32_bf16 v[16:19], v[162:165], v[192:195], v[16:19]
	v_mfma_f32_16x16x32_bf16 v[4:7], v[144:147], v[200:203], v[4:7]
	v_mfma_f32_16x16x32_bf16 v[0:3], v[162:165], v[200:203], v[0:3]
	v_mfma_f32_16x16x32_bf16 v[52:55], v[148:151], v[176:179], v[52:55]
	v_mfma_f32_16x16x32_bf16 v[48:51], v[166:169], v[176:179], v[48:51]
	v_mfma_f32_16x16x32_bf16 v[36:39], v[148:151], v[184:187], v[36:39]
	v_mfma_f32_16x16x32_bf16 v[32:35], v[166:169], v[184:187], v[32:35]
	v_mfma_f32_16x16x32_bf16 v[20:23], v[148:151], v[196:199], v[20:23]
	v_mfma_f32_16x16x32_bf16 v[16:19], v[166:169], v[196:199], v[16:19]
	v_mfma_f32_16x16x32_bf16 v[4:7], v[148:151], v[204:207], v[4:7]
	v_mfma_f32_16x16x32_bf16 v[0:3], v[166:169], v[204:207], v[0:3]
	s_barrier
; #define PG8_STAGE(bufoff, gbase, voff) do { _Pragma("unroll") for (int _i = 0; _i < 2; ++_i) \
;         __builtin_amdgcn_global_load_lds((const unsigned*)((const char*)(gbase) + (voff)[_i]), (PG8_LAS unsigned*)(lds + (bufoff) + ldsw + _i * 8192), 16, 0, 0); } while (0)
; #define PG8_LDA(dst, b, h) do { _Pragma("unroll") for (int m = 0; m < 4; ++m) _Pragma("unroll") for (int k = 0; k < 2; ++k) dst[m][k] = *(const PG8_LAS bf16x8*)(lds + PG8_SA(b, h) + aoff + m * 2048 + k * 1024); } while (0)
; #define PG8_LDB(dst, b, h) do { _Pragma("unroll") for (int n = 0; n < 2; ++n) _Pragma("unroll") for (int k = 0; k < 2; ++k) dst[n][k] = *(const PG8_LAS bf16x8*)(lds + PG8_SB(b, h) + boff + n * 2048 + k * 1024); } while (0)
; #define PG8_MMA(ai, bj, At, Bt) do { __builtin_amdgcn_s_setprio(1); _Pragma("unroll") for (int m = 0; m < 4; ++m) _Pragma("unroll") for (int n = 0; n < 2; ++n) _Pragma("unroll") for (int k = 0; k < 2; ++k) \
;         acc[ai][bj][m][n] = __builtin_amdgcn_mfma_f32_16x16x32_bf16(Bt[n][k], At[m][k], acc[ai][bj][m][n], 0, 0, 0); __builtin_amdgcn_s_setprio(0); } while (0)
; #define PG8_WAIT_V(n) asm volatile("s_waitcnt vmcnt(" #n ")" ::: "memory")
; #define PG8_WAIT_L(n) asm volatile("s_waitcnt lgkmcnt(" #n ")" ::: "memory")
; #define PG8_BAR __builtin_amdgcn_s_barrier()
; #define PG8_SCHED __builtin_amdgcn_sched_barrier(0)
; template <class Epi, class Sched, bool ALIGN_EPI = false, bool SP2 = false>
; __device__ __forceinline__ void gemm_phase(PG8_LAS unsigned char* lds, const Gemm g, const Sched& S, const Epi& E) {
;     ...
;             PG8_LDB(B0, 1, 0); PG8_LDB(B1, 1, 1); PG8_SCHED; PG8_LDA(At, 1, 0); PG8_STAGE(PG8_SA(0, 1), a2 + hstep, voffA);
;             PG8_WAIT_V(8); PG8_WAIT_L(0); PG8_BAR; PG8_MMA(0, 0, At, B0); PG8_MMA(0, 1, At, B1); PG8_BAR; PG8_SCHED;
	s_setprio 0
	s_add_i32 s74, 0, 0x18000
	s_add_i32 s75, 0, 0x1c000
	v_add_u32_e32 v140, s74, v189
	v_add_u32_e32 v166, s75, v189
	ds_read_b128 v[128:131], v140
	ds_read_b128 v[132:135], v140 offset:1024
	ds_read_b128 v[136:139], v140 offset:2048
	ds_read_b128 v[140:143], v140 offset:3072
	ds_read_b128 v[144:147], v166
	ds_read_b128 v[148:151], v166 offset:1024
	ds_read_b128 v[162:165], v166 offset:2048
	ds_read_b128 v[166:169], v166 offset:3072
	s_add_u32 s56, s56, 0x100000
	s_addc_u32 s57, s57, 0
	s_mov_b32 m0, s61
	v_lshl_add_u64 v[224:225], s[56:57], 0, v[156:157]
	ds_read_b128 v[170:173], v191 offset:32768
	ds_read_b128 v[176:179], v191 offset:33792
	ds_read_b128 v[180:183], v191 offset:34816
	ds_read_b128 v[184:187], v191 offset:35840
	ds_read_b128 v[192:195], v191 offset:36864
	ds_read_b128 v[196:199], v191 offset:37888
	ds_read_b128 v[200:203], v191 offset:38912
	ds_read_b128 v[204:207], v191 offset:39936
	global_load_lds_dwordx4 v[224:225], off
	v_lshl_add_u64 v[224:225], s[56:57], 0, v[154:155]
	s_mov_b32 m0, s62
	s_nop 0
	global_load_lds_dwordx4 v[224:225], off
	s_waitcnt vmcnt(8)
	s_waitcnt lgkmcnt(0)
	s_setprio 1
	s_barrier
	v_mfma_f32_16x16x32_bf16 v[124:127], v[128:131], v[170:173], v[124:127]
	v_mfma_f32_16x16x32_bf16 v[120:123], v[136:139], v[170:173], v[120:123]
	v_mfma_f32_16x16x32_bf16 v[108:111], v[128:131], v[180:183], v[108:111]
	v_mfma_f32_16x16x32_bf16 v[104:107], v[136:139], v[180:183], v[104:107]
	v_mfma_f32_16x16x32_bf16 v[92:95], v[128:131], v[192:195], v[92:95]
	v_mfma_f32_16x16x32_bf16 v[88:91], v[136:139], v[192:195], v[88:91]
	v_mfma_f32_16x16x32_bf16 v[76:79], v[128:131], v[200:203], v[76:79]
	v_mfma_f32_16x16x32_bf16 v[72:75], v[136:139], v[200:203], v[72:75]
	v_mfma_f32_16x16x32_bf16 v[124:127], v[132:135], v[176:179], v[124:127]
	v_mfma_f32_16x16x32_bf16 v[120:123], v[140:143], v[176:179], v[120:123]
	v_mfma_f32_16x16x32_bf16 v[108:111], v[132:135], v[184:187], v[108:111]
	v_mfma_f32_16x16x32_bf16 v[104:107], v[140:143], v[184:187], v[104:107]
	v_mfma_f32_16x16x32_bf16 v[92:95], v[132:135], v[196:199], v[92:95]
	v_mfma_f32_16x16x32_bf16 v[88:91], v[140:143], v[196:199], v[88:91]
	v_mfma_f32_16x16x32_bf16 v[76:79], v[132:135], v[204:207], v[76:79]
	v_mfma_f32_16x16x32_bf16 v[72:75], v[140:143], v[204:207], v[72:75]
	v_mfma_f32_16x16x32_bf16 v[116:119], v[144:147], v[170:173], v[116:119]
	v_mfma_f32_16x16x32_bf16 v[112:115], v[162:165], v[170:173], v[112:115]
	v_mfma_f32_16x16x32_bf16 v[100:103], v[144:147], v[180:183], v[100:103]
	v_mfma_f32_16x16x32_bf16 v[96:99], v[162:165], v[180:183], v[96:99]
	v_mfma_f32_16x16x32_bf16 v[84:87], v[144:147], v[192:195], v[84:87]
	v_mfma_f32_16x16x32_bf16 v[80:83], v[162:165], v[192:195], v[80:83]
	v_mfma_f32_16x16x32_bf16 v[68:71], v[144:147], v[200:203], v[68:71]
	v_mfma_f32_16x16x32_bf16 v[64:67], v[162:165], v[200:203], v[64:67]
	v_mfma_f32_16x16x32_bf16 v[116:119], v[148:151], v[176:179], v[116:119]
	v_mfma_f32_16x16x32_bf16 v[112:115], v[166:169], v[176:179], v[112:115]
	v_mfma_f32_16x16x32_bf16 v[100:103], v[148:151], v[184:187], v[100:103]
	v_mfma_f32_16x16x32_bf16 v[96:99], v[166:169], v[184:187], v[96:99]
	v_mfma_f32_16x16x32_bf16 v[84:87], v[148:151], v[196:199], v[84:87]
	v_mfma_f32_16x16x32_bf16 v[80:83], v[166:169], v[196:199], v[80:83]
	v_mfma_f32_16x16x32_bf16 v[68:71], v[148:151], v[204:207], v[68:71]
	v_mfma_f32_16x16x32_bf16 v[64:67], v[166:169], v[204:207], v[64:67]
	s_barrier
; #define PG8_STAGE(bufoff, gbase, voff) do { _Pragma("unroll") for (int _i = 0; _i < 2; ++_i) \
;         __builtin_amdgcn_global_load_lds((const unsigned*)((const char*)(gbase) + (voff)[_i]), (PG8_LAS unsigned*)(lds + (bufoff) + ldsw + _i * 8192), 16, 0, 0); } while (0)
; #define PG8_LDA(dst, b, h) do { _Pragma("unroll") for (int m = 0; m < 4; ++m) _Pragma("unroll") for (int k = 0; k < 2; ++k) dst[m][k] = *(const PG8_LAS bf16x8*)(lds + PG8_SA(b, h) + aoff + m * 2048 + k * 1024); } while (0)
; #define PG8_MMA(ai, bj, At, Bt) do { __builtin_amdgcn_s_setprio(1); _Pragma("unroll") for (int m = 0; m < 4; ++m) _Pragma("unroll") for (int n = 0; n < 2; ++n) _Pragma("unroll") for (int k = 0; k < 2; ++k) \
;         acc[ai][bj][m][n] = __builtin_amdgcn_mfma_f32_16x16x32_bf16(Bt[n][k], At[m][k], acc[ai][bj][m][n], 0, 0, 0); __builtin_amdgcn_s_setprio(0); } while (0)
; #define PG8_WAIT_V(n) asm volatile("s_waitcnt vmcnt(" #n ")" ::: "memory")
; #define PG8_WAIT_L(n) asm volatile("s_waitcnt lgkmcnt(" #n ")" ::: "memory")
; #define PG8_BAR __builtin_amdgcn_s_barrier()
; #define PG8_SCHED __builtin_amdgcn_sched_barrier(0)
; template <class Epi, class Sched, bool ALIGN_EPI = false, bool SP2 = false>
; __device__ __forceinline__ void gemm_phase(PG8_LAS unsigned char* lds, const Gemm g, const Sched& S, const Epi& E) {
;     ...
;             PG8_LDA(At, 1, 1); PG8_STAGE(PG8_SB(1, 0), b3, voffB); PG8_STAGE(PG8_SB(1, 1), b3 + hstep, voffB); PG8_STAGE(PG8_SA(1, 0), a3, voffA);
;             PG8_WAIT_V(8); PG8_WAIT_L(0); PG8_BAR; PG8_MMA(1, 0, At, B0); PG8_MMA(1, 1, At, B1); PG8_BAR; PG8_SCHED;
;     ...
;         if constexpr (ALIGN_EPI) { if (wr == 0) PG8_BAR; }
	s_setprio 0
	s_add_i32 s56, s74, s58
	v_lshl_add_u64 v[208:209], v[208:209], 0, s[4:5]
	s_mov_b32 m0, s56
	ds_read_b128 v[170:173], v191 offset:49152
	ds_read_b128 v[176:179], v191 offset:50176
	ds_read_b128 v[180:183], v191 offset:51200
	ds_read_b128 v[184:187], v191 offset:52224
	ds_read_b128 v[192:195], v191 offset:53248
	ds_read_b128 v[196:199], v191 offset:54272
	ds_read_b128 v[200:203], v191 offset:55296
	ds_read_b128 v[204:207], v191 offset:56320
	global_load_lds_dwordx4 v[208:209], off
	s_add_i32 m0, s56, 0x2000
	s_add_u32 s54, s54, 0x100080
	v_lshl_add_u64 v[208:209], v[218:219], 0, s[4:5]
	s_addc_u32 s55, s55, 0
	s_add_i32 s56, s75, s58
	global_load_lds_dwordx4 v[208:209], off
	v_lshl_add_u64 v[208:209], s[54:55], 0, v[174:175]
	s_mov_b32 m0, s56
	s_nop 0
	global_load_lds_dwordx4 v[208:209], off
	v_lshl_add_u64 v[208:209], s[54:55], 0, v[152:153]
	s_add_i32 m0, s56, 0x2000
	s_nop 0
	global_load_lds_dwordx4 v[208:209], off
	v_lshl_add_u64 v[208:209], v[220:221], 0, s[4:5]
	s_mov_b32 m0, s64
	s_nop 0
	global_load_lds_dwordx4 v[208:209], off
	v_lshl_add_u64 v[208:209], v[222:223], 0, s[4:5]
	s_mov_b32 m0, s65
	s_nop 0
	global_load_lds_dwordx4 v[208:209], off
	s_waitcnt vmcnt(8)
	s_waitcnt lgkmcnt(0)
	s_setprio 1
	s_barrier
	v_mfma_f32_16x16x32_bf16 v[60:63], v[128:131], v[170:173], v[60:63]
	v_mfma_f32_16x16x32_bf16 v[56:59], v[136:139], v[170:173], v[56:59]
	v_mfma_f32_16x16x32_bf16 v[44:47], v[128:131], v[180:183], v[44:47]
	v_mfma_f32_16x16x32_bf16 v[40:43], v[136:139], v[180:183], v[40:43]
	v_mfma_f32_16x16x32_bf16 v[28:31], v[128:131], v[192:195], v[28:31]
	v_mfma_f32_16x16x32_bf16 v[24:27], v[136:139], v[192:195], v[24:27]
	v_mfma_f32_16x16x32_bf16 v[12:15], v[128:131], v[200:203], v[12:15]
	v_mfma_f32_16x16x32_bf16 v[8:11], v[136:139], v[200:203], v[8:11]
	v_mfma_f32_16x16x32_bf16 v[60:63], v[132:135], v[176:179], v[60:63]
	v_mfma_f32_16x16x32_bf16 v[56:59], v[140:143], v[176:179], v[56:59]
	v_mfma_f32_16x16x32_bf16 v[44:47], v[132:135], v[184:187], v[44:47]
	v_mfma_f32_16x16x32_bf16 v[40:43], v[140:143], v[184:187], v[40:43]
	v_mfma_f32_16x16x32_bf16 v[28:31], v[132:135], v[196:199], v[28:31]
	v_mfma_f32_16x16x32_bf16 v[24:27], v[140:143], v[196:199], v[24:27]
	v_mfma_f32_16x16x32_bf16 v[12:15], v[132:135], v[204:207], v[12:15]
	v_mfma_f32_16x16x32_bf16 v[8:11], v[140:143], v[204:207], v[8:11]
	v_mfma_f32_16x16x32_bf16 v[52:55], v[144:147], v[170:173], v[52:55]
	v_mfma_f32_16x16x32_bf16 v[48:51], v[162:165], v[170:173], v[48:51]
	v_mfma_f32_16x16x32_bf16 v[36:39], v[144:147], v[180:183], v[36:39]
	v_mfma_f32_16x16x32_bf16 v[32:35], v[162:165], v[180:183], v[32:35]
	v_mfma_f32_16x16x32_bf16 v[20:23], v[144:147], v[192:195], v[20:23]
	v_mfma_f32_16x16x32_bf16 v[16:19], v[162:165], v[192:195], v[16:19]
	v_mfma_f32_16x16x32_bf16 v[4:7], v[144:147], v[200:203], v[4:7]
	v_mfma_f32_16x16x32_bf16 v[0:3], v[162:165], v[200:203], v[0:3]
	v_mfma_f32_16x16x32_bf16 v[52:55], v[148:151], v[176:179], v[52:55]
	v_mfma_f32_16x16x32_bf16 v[48:51], v[166:169], v[176:179], v[48:51]
	v_mfma_f32_16x16x32_bf16 v[36:39], v[148:151], v[184:187], v[36:39]
	v_mfma_f32_16x16x32_bf16 v[32:35], v[166:169], v[184:187], v[32:35]
	v_mfma_f32_16x16x32_bf16 v[20:23], v[148:151], v[196:199], v[20:23]
	v_mfma_f32_16x16x32_bf16 v[16:19], v[166:169], v[196:199], v[16:19]
	v_mfma_f32_16x16x32_bf16 v[4:7], v[148:151], v[204:207], v[4:7]
	v_mfma_f32_16x16x32_bf16 v[0:3], v[166:169], v[204:207], v[0:3]
	s_barrier
	s_setprio 0
	s_add_i32 s73, s73, 2
	s_add_u32 s0, s0, 0x100
	s_addc_u32 s1, s1, 0
	s_add_u32 s71, s71, 0x100
	s_addc_u32 s72, s72, 0
	s_cmp_gt_u32 s73, 61
	s_cbranch_scc0 .LBB0_1845
	s_and_b64 vcc, exec, s[38:39]
	s_cbranch_vccz .LBB0_1848
	s_barrier
